# GEMM K-loops: merged back-to-back s_setprio 0/1 pairs between MFMA blocks and the duplicate lgkmcnt(0) after each segment barrier deleted (fewer scalar issue slots inside MFMA segments)
# speedup vs baseline: 1.0024x; 1.0024x over previous
; #define PG8_GOFFS(slot_) do { _Pragma("unroll") for (int _i = 0; _i < 2; ++_i) { int R, C; stage_rc(tid * 16 + _i * 8192, R, C); _Pragma("unroll") for (int _h = 0; _h < 2; ++_h) { \
;         unsigned t_ = gtab[(slot_) * 256 + R + 128 * _h]; t_ = t_ < (unsigned)(T - 1) ? t_ : (unsigned)(T - 1); voffA[_h][_i] = (t_ * (unsigned)K + (unsigned)C) * 2u; } } } while (0)
; #define PG8_STAGE(bufoff, gbase, voff) do { _Pragma("unroll") for (int _i = 0; _i < 2; ++_i) \
;         __builtin_amdgcn_global_load_lds((const unsigned*)((const char*)(gbase) + (voff)[_i]), (LAS unsigned*)(lds + (bufoff) + ldsw + _i * 8192), 16, 0, 0); } while (0)
; #define PG8_STAGE_A1(bufoff, gbase) do { if (Epi::GATHER) PG8_STAGE(bufoff, gbase, voffA[1]); else PG8_STAGE(bufoff, (gbase) + hstep, voffA[0]); } while (0)
; #define PG8_LDA(dst, b, h) do { _Pragma("unroll") for (int m = 0; m < 4; ++m) _Pragma("unroll") for (int k = 0; k < 2; ++k) dst[m][k] = *(const LAS bf16x8*)(lds + PG8_SA(b, h) + aoff + m * 2048 + k * 1024); } while (0)
; #define PG8_LDB(dst, b, h) do { _Pragma("unroll") for (int n = 0; n < 2; ++n) _Pragma("unroll") for (int k = 0; k < 2; ++k) dst[n][k] = *(const LAS bf16x8*)(lds + PG8_SB(b, h) + boff + n * 2048 + k * 1024); } while (0)
; #define PG8_WAIT_V(n) asm volatile("s_waitcnt vmcnt(" #n ")" ::: "memory")
; #define PG8_WAIT_L(n) asm volatile("s_waitcnt lgkmcnt(" #n ")" ::: "memory")
; #define PG8_BAR __builtin_amdgcn_s_barrier()
; #define PG8_SCHED __builtin_amdgcn_sched_barrier(0)
; template <class Epi, class Sched>
; __device__ __forceinline__ void gemm_phase(const int tid, LAS unsigned char* lds, const bf16* Aop, const bf16* Bop, const int K_, const Sched& S, const Epi& E, const bf16* Aop1 = nullptr, const bf16* Bop1 = nullptr) {
;     ...
;             PG8_LDB(B0, 0, 0); PG8_LDB(B1, 0, 1); PG8_SCHED; PG8_LDA(At, 0, 0); PG8_STAGE_A1(PG8_SA(1, 1), a1);
;             PG8_WAIT_V(8); PG8_WAIT_L(0); PG8_BAR; PG8_MMA(0, 0, At, B0); PG8_MMA(0, 1, At, B1); PG8_BAR; PG8_SCHED;
;             PG8_LDA(At, 0, 1); PG8_STAGE(PG8_SB(0, 0), b2, voffB); PG8_STAGE(PG8_SB(0, 1), b2 + hstep, voffB); if (Epi::GATHER && last && has_next) PG8_GOFFS((ui + 1) & 1); PG8_STAGE(PG8_SA(0, 0), a2, voffA[0]);
;             PG8_WAIT_V(8); PG8_WAIT_L(0); PG8_BAR; PG8_MMA(1, 0, At, B0); PG8_MMA(1, 1, At, B1); PG8_BAR; PG8_SCHED;
.LBB0_129:
	v_mov_b32_e32 v143, 0
	s_andn2_b64 vcc, exec, s[18:19]
	s_cbranch_vccnz .LBB0_133
	s_add_u32 s26, s26, 0x80
	s_addc_u32 s27, s27, 0
	s_add_u32 s11, s42, 0x100
	v_mov_b64_e32 v[180:181], v[178:179]
	v_mov_b64_e32 v[178:179], v[176:177]
	v_mov_b64_e32 v[176:177], v[190:191]
	v_mov_b32_e32 v205, 0x7f800000
	v_mov_b32_e32 v203, 0x3ecc95a3
	v_mov_b32_e32 v200, 1
	v_mov_b64_e32 v[226:227], 0x100
	s_addc_u32 s42, s43, 0
	s_mov_b32 s40, 0
	s_add_i32 s43, s40, 2
	s_add_u32 s44, s26, 0x80
	s_addc_u32 s41, s27, 0
	s_add_i32 s48, 0, 0x10000
	s_cmp_eq_u32 s77, s40
	s_cselect_b32 s41, s35, s41
	s_cselect_b32 s40, s34, s44
	s_cselect_b32 s45, s37, s42
	s_cselect_b32 s44, s36, s11
	s_add_i32 s49, 0, 0x14000
	v_add_u32_e32 v80, s48, v3
	v_add_u32_e32 v160, s49, v3
	ds_read_b128 v[60:63], v80
	ds_read_b128 v[68:71], v80 offset:1024
	ds_read_b128 v[76:79], v80 offset:2048
	ds_read_b128 v[80:83], v80 offset:3072
	ds_read_b128 v[148:151], v160
	ds_read_b128 v[152:155], v160 offset:1024
	ds_read_b128 v[156:159], v160 offset:2048
	ds_read_b128 v[160:163], v160 offset:3072
	v_lshl_add_u64 v[164:165], s[26:27], 0, v[192:193]
	s_add_i32 m0, s70, 0xc000
	ds_read_b128 v[206:209], v175
	ds_read_b128 v[210:213], v175 offset:1024
	ds_read_b128 v[214:217], v175 offset:2048
	ds_read_b128 v[218:221], v175 offset:3072
	ds_read_b128 v[238:241], v175 offset:4096
	ds_read_b128 v[242:245], v175 offset:5120
	ds_read_b128 v[246:249], v175 offset:6144
	ds_read_b128 v[230:233], v175 offset:7168
	global_load_lds_dwordx4 v[164:165], off
	v_lshl_add_u64 v[164:165], s[26:27], 0, v[194:195]
	s_add_i32 m0, s70, 0xe000
	s_nop 0
	global_load_lds_dwordx4 v[164:165], off
	s_waitcnt vmcnt(8)
	s_waitcnt lgkmcnt(0)
	s_barrier
	s_setprio 1
	v_mfma_f32_16x16x32_bf16 v[140:143], v[60:63], v[206:209], 0
	v_mfma_f32_16x16x32_bf16 v[144:147], v[76:79], v[206:209], 0
	v_mfma_f32_16x16x32_bf16 v[128:131], v[60:63], v[214:217], 0
	v_mfma_f32_16x16x32_bf16 v[124:127], v[76:79], v[214:217], 0
	v_mfma_f32_16x16x32_bf16 v[112:115], v[60:63], v[238:241], 0
	v_mfma_f32_16x16x32_bf16 v[108:111], v[76:79], v[238:241], 0
	v_mfma_f32_16x16x32_bf16 v[96:99], v[60:63], v[246:249], 0
	v_mfma_f32_16x16x32_bf16 v[92:95], v[76:79], v[246:249], 0
	v_mfma_f32_16x16x32_bf16 v[140:143], v[68:71], v[210:213], v[140:143]
	v_mfma_f32_16x16x32_bf16 v[144:147], v[80:83], v[210:213], v[144:147]
	v_mfma_f32_16x16x32_bf16 v[128:131], v[68:71], v[218:221], v[128:131]
	v_mfma_f32_16x16x32_bf16 v[124:127], v[80:83], v[218:221], v[124:127]
	v_mfma_f32_16x16x32_bf16 v[112:115], v[68:71], v[242:245], v[112:115]
	v_mfma_f32_16x16x32_bf16 v[108:111], v[80:83], v[242:245], v[108:111]
	v_mfma_f32_16x16x32_bf16 v[96:99], v[68:71], v[230:233], v[96:99]
	v_mfma_f32_16x16x32_bf16 v[92:95], v[80:83], v[230:233], v[92:95]
	v_mfma_f32_16x16x32_bf16 v[136:139], v[148:151], v[206:209], 0
	v_mfma_f32_16x16x32_bf16 v[132:135], v[156:159], v[206:209], 0
	v_mfma_f32_16x16x32_bf16 v[120:123], v[148:151], v[214:217], 0
	v_mfma_f32_16x16x32_bf16 v[116:119], v[156:159], v[214:217], 0
	v_mfma_f32_16x16x32_bf16 v[104:107], v[148:151], v[238:241], 0
	v_mfma_f32_16x16x32_bf16 v[100:103], v[156:159], v[238:241], 0
	v_mfma_f32_16x16x32_bf16 v[88:91], v[148:151], v[246:249], 0
	v_mfma_f32_16x16x32_bf16 v[84:87], v[156:159], v[246:249], 0
	v_mfma_f32_16x16x32_bf16 v[136:139], v[152:155], v[210:213], v[136:139]
	v_mfma_f32_16x16x32_bf16 v[132:135], v[160:163], v[210:213], v[132:135]
	v_mfma_f32_16x16x32_bf16 v[120:123], v[152:155], v[218:221], v[120:123]
	v_mfma_f32_16x16x32_bf16 v[116:119], v[160:163], v[218:221], v[116:119]
	v_mfma_f32_16x16x32_bf16 v[104:107], v[152:155], v[242:245], v[104:107]
	v_mfma_f32_16x16x32_bf16 v[100:103], v[160:163], v[242:245], v[100:103]
	v_mfma_f32_16x16x32_bf16 v[88:91], v[152:155], v[230:233], v[88:91]
	v_mfma_f32_16x16x32_bf16 v[84:87], v[160:163], v[230:233], v[84:87]
	s_setprio 0
	s_barrier
	s_add_i32 s48, s48, s69
	v_lshl_add_u64 v[164:165], s[44:45], 0, v[166:167]
	s_mov_b32 m0, s48
	ds_read_b128 v[206:209], v175 offset:16384
	ds_read_b128 v[210:213], v175 offset:17408
	ds_read_b128 v[214:217], v175 offset:18432
	ds_read_b128 v[218:221], v175 offset:19456
	ds_read_b128 v[230:233], v175 offset:20480
	ds_read_b128 v[238:241], v175 offset:21504
	ds_read_b128 v[242:245], v175 offset:22528
	ds_read_b128 v[246:249], v175 offset:23552
	global_load_lds_dwordx4 v[164:165], off
	s_add_i32 m0, s48, 0x2000
	v_lshl_add_u64 v[222:223], s[44:45], 0, v[170:171]
	s_add_u32 s44, s44, s6
	s_addc_u32 s45, s45, s7
	s_add_i32 s48, s49, s69
	global_load_lds_dwordx4 v[222:223], off
	v_lshl_add_u64 v[250:251], s[44:45], 0, v[166:167]
	s_mov_b32 m0, s48
	v_lshl_add_u64 v[196:197], s[44:45], 0, v[170:171]
	global_load_lds_dwordx4 v[250:251], off
	s_add_i32 m0, s48, 0x2000
	v_lshl_add_u64 v[198:199], s[40:41], 0, v[0:1]
	global_load_lds_dwordx4 v[196:197], off
	s_mov_b32 m0, s70
	v_lshl_add_u64 v[224:225], s[40:41], 0, v[168:169]
	global_load_lds_dwordx4 v[198:199], off
	s_mov_b32 m0, s71
	s_nop 0
	global_load_lds_dwordx4 v[224:225], off
	s_waitcnt vmcnt(8)
	s_waitcnt lgkmcnt(0)
	s_barrier
; #define PG8_STAGE_A1(bufoff, gbase) do { if (Epi::GATHER) PG8_STAGE(bufoff, gbase, voffA[1]); else PG8_STAGE(bufoff, (gbase) + hstep, voffA[0]); } while (0)
; #define PG8_LDA(dst, b, h) do { _Pragma("unroll") for (int m = 0; m < 4; ++m) _Pragma("unroll") for (int k = 0; k < 2; ++k) dst[m][k] = *(const LAS bf16x8*)(lds + PG8_SA(b, h) + aoff + m * 2048 + k * 1024); } while (0)
; #define PG8_LDB(dst, b, h) do { _Pragma("unroll") for (int n = 0; n < 2; ++n) _Pragma("unroll") for (int k = 0; k < 2; ++k) dst[n][k] = *(const LAS bf16x8*)(lds + PG8_SB(b, h) + boff + n * 2048 + k * 1024); } while (0)
; #define PG8_MMA(ai, bj, At, Bt) do { __builtin_amdgcn_s_setprio(1); _Pragma("unroll") for (int m = 0; m < 4; ++m) _Pragma("unroll") for (int n = 0; n < 2; ++n) _Pragma("unroll") for (int k = 0; k < 2; ++k) \
;         acc[ai][bj][m][n] = __builtin_amdgcn_mfma_f32_16x16x32_bf16(Bt[n][k], At[m][k], acc[ai][bj][m][n], 0, 0, 0); __builtin_amdgcn_s_setprio(0); } while (0)
; #define PG8_WAIT_V(n) asm volatile("s_waitcnt vmcnt(" #n ")" ::: "memory")
; #define PG8_WAIT_L(n) asm volatile("s_waitcnt lgkmcnt(" #n ")" ::: "memory")
; #define PG8_BAR __builtin_amdgcn_s_barrier()
; #define PG8_SCHED __builtin_amdgcn_sched_barrier(0)
; template <class Epi, class Sched>
; __device__ __forceinline__ void gemm_phase(const int tid, LAS unsigned char* lds, const bf16* Aop, const bf16* Bop, const int K_, const Sched& S, const Epi& E, const bf16* Aop1 = nullptr, const bf16* Bop1 = nullptr) {
;     ...
;             PG8_WAIT_V(8); PG8_WAIT_L(0); PG8_BAR; PG8_MMA(1, 0, At, B0); PG8_MMA(1, 1, At, B1); PG8_BAR; PG8_SCHED;
;             PG8_LDB(B0, 1, 0); PG8_LDB(B1, 1, 1); PG8_SCHED; PG8_LDA(At, 1, 0); PG8_STAGE_A1(PG8_SA(0, 1), a2);
;             PG8_WAIT_V(8); PG8_WAIT_L(0); PG8_BAR; PG8_MMA(0, 0, At, B0); PG8_MMA(0, 1, At, B1); PG8_BAR; PG8_SCHED;
	s_setprio 1
	v_mfma_f32_16x16x32_bf16 v[72:75], v[60:63], v[206:209], 0
	v_mfma_f32_16x16x32_bf16 v[64:67], v[76:79], v[206:209], 0
	v_mfma_f32_16x16x32_bf16 v[48:51], v[60:63], v[214:217], 0
	v_mfma_f32_16x16x32_bf16 v[44:47], v[76:79], v[214:217], 0
	v_mfma_f32_16x16x32_bf16 v[32:35], v[60:63], v[230:233], 0
	v_mfma_f32_16x16x32_bf16 v[28:31], v[76:79], v[230:233], 0
	v_mfma_f32_16x16x32_bf16 v[16:19], v[60:63], v[242:245], 0
	v_mfma_f32_16x16x32_bf16 v[12:15], v[76:79], v[242:245], 0
	v_mfma_f32_16x16x32_bf16 v[72:75], v[68:71], v[210:213], v[72:75]
	v_mfma_f32_16x16x32_bf16 v[64:67], v[80:83], v[210:213], v[64:67]
	v_mfma_f32_16x16x32_bf16 v[48:51], v[68:71], v[218:221], v[48:51]
	v_mfma_f32_16x16x32_bf16 v[44:47], v[80:83], v[218:221], v[44:47]
	v_mfma_f32_16x16x32_bf16 v[32:35], v[68:71], v[238:241], v[32:35]
	v_mfma_f32_16x16x32_bf16 v[28:31], v[80:83], v[238:241], v[28:31]
	v_mfma_f32_16x16x32_bf16 v[16:19], v[68:71], v[246:249], v[16:19]
	v_mfma_f32_16x16x32_bf16 v[12:15], v[80:83], v[246:249], v[12:15]
	v_mfma_f32_16x16x32_bf16 v[56:59], v[148:151], v[206:209], 0
	v_mfma_f32_16x16x32_bf16 v[52:55], v[156:159], v[206:209], 0
	v_mfma_f32_16x16x32_bf16 v[40:43], v[148:151], v[214:217], 0
	v_mfma_f32_16x16x32_bf16 v[36:39], v[156:159], v[214:217], 0
	v_mfma_f32_16x16x32_bf16 v[24:27], v[148:151], v[230:233], 0
	v_mfma_f32_16x16x32_bf16 v[20:23], v[156:159], v[230:233], 0
	v_mfma_f32_16x16x32_bf16 v[8:11], v[148:151], v[242:245], 0
	v_mfma_f32_16x16x32_bf16 v[4:7], v[156:159], v[242:245], 0
	v_mfma_f32_16x16x32_bf16 v[56:59], v[152:155], v[210:213], v[56:59]
	v_mfma_f32_16x16x32_bf16 v[52:55], v[160:163], v[210:213], v[52:55]
	v_mfma_f32_16x16x32_bf16 v[40:43], v[152:155], v[218:221], v[40:43]
	v_mfma_f32_16x16x32_bf16 v[36:39], v[160:163], v[218:221], v[36:39]
	v_mfma_f32_16x16x32_bf16 v[24:27], v[152:155], v[238:241], v[24:27]
	v_mfma_f32_16x16x32_bf16 v[20:23], v[160:163], v[238:241], v[20:23]
	v_mfma_f32_16x16x32_bf16 v[8:11], v[152:155], v[246:249], v[8:11]
	v_mfma_f32_16x16x32_bf16 v[4:7], v[160:163], v[246:249], v[4:7]
	s_setprio 0
	s_barrier
	s_add_i32 s44, 0, 0x18000
	s_add_i32 s45, 0, 0x1c000
	v_add_u32_e32 v80, s44, v3
	v_add_u32_e32 v160, s45, v3
	ds_read_b128 v[60:63], v80
	ds_read_b128 v[68:71], v80 offset:1024
	ds_read_b128 v[76:79], v80 offset:2048
	ds_read_b128 v[80:83], v80 offset:3072
	ds_read_b128 v[148:151], v160
	ds_read_b128 v[152:155], v160 offset:1024
	ds_read_b128 v[156:159], v160 offset:2048
	ds_read_b128 v[160:163], v160 offset:3072
	s_add_u32 s40, s40, s6
	s_addc_u32 s41, s41, s7
	s_mov_b32 m0, s72
	v_lshl_add_u64 v[190:191], s[40:41], 0, v[0:1]
	ds_read_b128 v[206:209], v175 offset:32768
	ds_read_b128 v[210:213], v175 offset:33792
	ds_read_b128 v[214:217], v175 offset:34816
	ds_read_b128 v[218:221], v175 offset:35840
	ds_read_b128 v[230:233], v175 offset:36864
	ds_read_b128 v[238:241], v175 offset:37888
	ds_read_b128 v[242:245], v175 offset:38912
	ds_read_b128 v[246:249], v175 offset:39936
	global_load_lds_dwordx4 v[190:191], off
	v_lshl_add_u64 v[190:191], s[40:41], 0, v[168:169]
	s_mov_b32 m0, s73
	s_nop 0
	global_load_lds_dwordx4 v[190:191], off
	s_waitcnt vmcnt(8)
	s_waitcnt lgkmcnt(0)
	s_barrier
	s_setprio 1
	v_mfma_f32_16x16x32_bf16 v[140:143], v[60:63], v[206:209], v[140:143]
	v_mfma_f32_16x16x32_bf16 v[144:147], v[76:79], v[206:209], v[144:147]
	v_mfma_f32_16x16x32_bf16 v[128:131], v[60:63], v[214:217], v[128:131]
	v_mfma_f32_16x16x32_bf16 v[124:127], v[76:79], v[214:217], v[124:127]
	v_mfma_f32_16x16x32_bf16 v[112:115], v[60:63], v[230:233], v[112:115]
	v_mfma_f32_16x16x32_bf16 v[108:111], v[76:79], v[230:233], v[108:111]
	v_mfma_f32_16x16x32_bf16 v[96:99], v[60:63], v[242:245], v[96:99]
	v_mfma_f32_16x16x32_bf16 v[92:95], v[76:79], v[242:245], v[92:95]
	v_mfma_f32_16x16x32_bf16 v[140:143], v[68:71], v[210:213], v[140:143]
	v_mfma_f32_16x16x32_bf16 v[144:147], v[80:83], v[210:213], v[144:147]
	v_mfma_f32_16x16x32_bf16 v[128:131], v[68:71], v[218:221], v[128:131]
	v_mfma_f32_16x16x32_bf16 v[124:127], v[80:83], v[218:221], v[124:127]
	v_mfma_f32_16x16x32_bf16 v[112:115], v[68:71], v[238:241], v[112:115]
	v_mfma_f32_16x16x32_bf16 v[108:111], v[80:83], v[238:241], v[108:111]
	v_mfma_f32_16x16x32_bf16 v[96:99], v[68:71], v[246:249], v[96:99]
	v_mfma_f32_16x16x32_bf16 v[92:95], v[80:83], v[246:249], v[92:95]
	v_mfma_f32_16x16x32_bf16 v[136:139], v[148:151], v[206:209], v[136:139]
	v_mfma_f32_16x16x32_bf16 v[132:135], v[156:159], v[206:209], v[132:135]
	v_mfma_f32_16x16x32_bf16 v[120:123], v[148:151], v[214:217], v[120:123]
	v_mfma_f32_16x16x32_bf16 v[116:119], v[156:159], v[214:217], v[116:119]
	v_mfma_f32_16x16x32_bf16 v[104:107], v[148:151], v[230:233], v[104:107]
	v_mfma_f32_16x16x32_bf16 v[100:103], v[156:159], v[230:233], v[100:103]
	v_mfma_f32_16x16x32_bf16 v[88:91], v[148:151], v[242:245], v[88:91]
	v_mfma_f32_16x16x32_bf16 v[84:87], v[156:159], v[242:245], v[84:87]
	v_mfma_f32_16x16x32_bf16 v[136:139], v[152:155], v[210:213], v[136:139]
	v_mfma_f32_16x16x32_bf16 v[132:135], v[160:163], v[210:213], v[132:135]
	v_mfma_f32_16x16x32_bf16 v[120:123], v[152:155], v[218:221], v[120:123]
	v_mfma_f32_16x16x32_bf16 v[116:119], v[160:163], v[218:221], v[116:119]
	v_mfma_f32_16x16x32_bf16 v[104:107], v[152:155], v[238:241], v[104:107]
	v_mfma_f32_16x16x32_bf16 v[100:103], v[160:163], v[238:241], v[100:103]
	v_mfma_f32_16x16x32_bf16 v[88:91], v[152:155], v[246:249], v[88:91]
	v_mfma_f32_16x16x32_bf16 v[84:87], v[160:163], v[246:249], v[84:87]
	s_setprio 0
	s_barrier
; #define PG8_GOFFS(slot_) do { _Pragma("unroll") for (int _i = 0; _i < 2; ++_i) { int R, C; stage_rc(tid * 16 + _i * 8192, R, C); _Pragma("unroll") for (int _h = 0; _h < 2; ++_h) { \
;         unsigned t_ = gtab[(slot_) * 256 + R + 128 * _h]; t_ = t_ < (unsigned)(T - 1) ? t_ : (unsigned)(T - 1); voffA[_h][_i] = (t_ * (unsigned)K + (unsigned)C) * 2u; } } } while (0)
; #define PG8_STAGE(bufoff, gbase, voff) do { _Pragma("unroll") for (int _i = 0; _i < 2; ++_i) \
;         __builtin_amdgcn_global_load_lds((const unsigned*)((const char*)(gbase) + (voff)[_i]), (LAS unsigned*)(lds + (bufoff) + ldsw + _i * 8192), 16, 0, 0); } while (0)
; #define PG8_WAIT_V(n) asm volatile("s_waitcnt vmcnt(" #n ")" ::: "memory")
; template <class Epi, class Sched>
; __device__ __forceinline__ void gemm_phase(const int tid, LAS unsigned char* lds, const bf16* Aop, const bf16* Bop, const int K_, const Sched& S, const Epi& E, const bf16* Aop1 = nullptr, const bf16* Bop1 = nullptr) {
;     ...
;         for (int t = 0; t < nt; t += 2) {
;             const bool last = (t == nt - 2);
;             const char* a1 = cA + (size_t)(t + 1) * kstep;
;             const char* a2 = last ? nA : cA + (size_t)(t + 2) * kstep; const char* b2 = last ? nB : cB + (size_t)(t + 2) * kstep;
;             const char* a3 = a2 + kstep; const char* b3 = b2 + kstep;
;             PG8_LDB(B0, 0, 0); PG8_LDB(B1, 0, 1); PG8_SCHED; PG8_LDA(At, 0, 0); PG8_STAGE_A1(PG8_SA(1, 1), a1);
;             PG8_WAIT_V(8); PG8_WAIT_L(0); PG8_BAR; PG8_MMA(0, 0, At, B0); PG8_MMA(0, 1, At, B1); PG8_BAR; PG8_SCHED;
;             PG8_LDA(At, 0, 1); PG8_STAGE(PG8_SB(0, 0), b2, voffB); PG8_STAGE(PG8_SB(0, 1), b2 + hstep, voffB); if (Epi::GATHER && last && has_next) PG8_GOFFS((ui + 1) & 1); PG8_STAGE(PG8_SA(0, 0), a2, voffA[0]);
;             PG8_WAIT_V(8); PG8_WAIT_L(0); PG8_BAR; PG8_MMA(1, 0, At, B0); PG8_MMA(1, 1, At, B1); PG8_BAR; PG8_SCHED;
;             PG8_LDB(B0, 1, 0); PG8_LDB(B1, 1, 1); PG8_SCHED; PG8_LDA(At, 1, 0); PG8_STAGE_A1(PG8_SA(0, 1), a2);
;             PG8_WAIT_V(8); PG8_WAIT_L(0); PG8_BAR; PG8_MMA(0, 0, At, B0); PG8_MMA(0, 1, At, B1); PG8_BAR; PG8_SCHED;
;             PG8_LDA(At, 1, 1); PG8_STAGE(PG8_SB(1, 0), b3, voffB); PG8_STAGE(PG8_SB(1, 1), b3 + hstep, voffB); PG8_STAGE(PG8_SA(1, 0), a3, voffA[0]);
;             PG8_WAIT_V(8); PG8_WAIT_L(0); PG8_BAR; PG8_MMA(1, 0, At, B0); PG8_MMA(1, 1, At, B1); PG8_BAR; PG8_SCHED;
	s_add_i32 s40, s44, s69
	v_lshl_add_u64 v[164:165], v[164:165], 0, s[20:21]
	s_mov_b32 m0, s40
	ds_read_b128 v[206:209], v175 offset:49152
	ds_read_b128 v[210:213], v175 offset:50176
	ds_read_b128 v[214:217], v175 offset:51200
	ds_read_b128 v[218:221], v175 offset:52224
	ds_read_b128 v[230:233], v175 offset:53248
	ds_read_b128 v[238:241], v175 offset:54272
	ds_read_b128 v[242:245], v175 offset:55296
	ds_read_b128 v[246:249], v175 offset:56320
	global_load_lds_dwordx4 v[164:165], off
	v_lshl_add_u64 v[164:165], v[222:223], 0, s[20:21]
	s_add_i32 m0, s40, 0x2000
	s_add_i32 s40, s45, s69
	global_load_lds_dwordx4 v[164:165], off
	v_lshl_add_u64 v[164:165], v[250:251], 0, s[20:21]
	s_mov_b32 m0, s40
	s_nop 0
	global_load_lds_dwordx4 v[164:165], off
	v_lshl_add_u64 v[164:165], v[196:197], 0, s[20:21]
	s_add_i32 m0, s40, 0x2000
	s_nop 0
	global_load_lds_dwordx4 v[164:165], off
	v_lshl_add_u64 v[164:165], v[198:199], 0, s[20:21]
	s_mov_b32 m0, s75
	s_nop 0
	global_load_lds_dwordx4 v[164:165], off
	v_lshl_add_u64 v[164:165], v[224:225], 0, s[20:21]
	s_mov_b32 m0, s76
	s_nop 0
	global_load_lds_dwordx4 v[164:165], off
	s_waitcnt vmcnt(8)
	s_waitcnt lgkmcnt(0)
	s_barrier
	s_setprio 1
	v_mfma_f32_16x16x32_bf16 v[72:75], v[60:63], v[206:209], v[72:75]
	v_mfma_f32_16x16x32_bf16 v[64:67], v[76:79], v[206:209], v[64:67]
	v_mfma_f32_16x16x32_bf16 v[48:51], v[60:63], v[214:217], v[48:51]
	v_mfma_f32_16x16x32_bf16 v[44:47], v[76:79], v[214:217], v[44:47]
	v_mfma_f32_16x16x32_bf16 v[32:35], v[60:63], v[230:233], v[32:35]
	v_mfma_f32_16x16x32_bf16 v[28:31], v[76:79], v[230:233], v[28:31]
	v_mfma_f32_16x16x32_bf16 v[16:19], v[60:63], v[242:245], v[16:19]
	v_mfma_f32_16x16x32_bf16 v[12:15], v[76:79], v[242:245], v[12:15]
	v_mfma_f32_16x16x32_bf16 v[72:75], v[68:71], v[210:213], v[72:75]
	v_mfma_f32_16x16x32_bf16 v[64:67], v[80:83], v[210:213], v[64:67]
	v_mfma_f32_16x16x32_bf16 v[48:51], v[68:71], v[218:221], v[48:51]
	v_mfma_f32_16x16x32_bf16 v[44:47], v[80:83], v[218:221], v[44:47]
	v_mfma_f32_16x16x32_bf16 v[32:35], v[68:71], v[238:241], v[32:35]
	v_mfma_f32_16x16x32_bf16 v[28:31], v[80:83], v[238:241], v[28:31]
	v_mfma_f32_16x16x32_bf16 v[16:19], v[68:71], v[246:249], v[16:19]
	v_mfma_f32_16x16x32_bf16 v[12:15], v[80:83], v[246:249], v[12:15]
	v_mfma_f32_16x16x32_bf16 v[56:59], v[148:151], v[206:209], v[56:59]
	v_mfma_f32_16x16x32_bf16 v[52:55], v[156:159], v[206:209], v[52:55]
	v_mfma_f32_16x16x32_bf16 v[40:43], v[148:151], v[214:217], v[40:43]
	v_mfma_f32_16x16x32_bf16 v[36:39], v[156:159], v[214:217], v[36:39]
	v_mfma_f32_16x16x32_bf16 v[24:27], v[148:151], v[230:233], v[24:27]
	v_mfma_f32_16x16x32_bf16 v[20:23], v[156:159], v[230:233], v[20:23]
	v_mfma_f32_16x16x32_bf16 v[8:11], v[148:151], v[242:245], v[8:11]
	v_mfma_f32_16x16x32_bf16 v[4:7], v[156:159], v[242:245], v[4:7]
	v_mfma_f32_16x16x32_bf16 v[56:59], v[152:155], v[210:213], v[56:59]
	v_mfma_f32_16x16x32_bf16 v[52:55], v[160:163], v[210:213], v[52:55]
	v_mfma_f32_16x16x32_bf16 v[40:43], v[152:155], v[218:221], v[40:43]
	v_mfma_f32_16x16x32_bf16 v[36:39], v[160:163], v[218:221], v[36:39]
	v_mfma_f32_16x16x32_bf16 v[24:27], v[152:155], v[238:241], v[24:27]
	v_mfma_f32_16x16x32_bf16 v[20:23], v[160:163], v[238:241], v[20:23]
	v_mfma_f32_16x16x32_bf16 v[8:11], v[152:155], v[246:249], v[8:11]
	v_mfma_f32_16x16x32_bf16 v[4:7], v[160:163], v[246:249], v[4:7]
	s_setprio 0
	s_barrier
	s_add_u32 s26, s26, 0x100
	s_addc_u32 s27, s27, 0
	s_add_u32 s11, s11, 0x100
	s_addc_u32 s42, s42, 0
	s_cmp_ge_i32 s43, s74
	s_mov_b32 s40, s43
	s_cbranch_scc0 .LBB0_131
	s_branch .Lpeel_exit_131
.LBB0_131:
	s_add_i32 s43, s40, 2
	s_add_u32 s44, s26, 0x80
	s_addc_u32 s41, s27, 0
	s_add_i32 s48, 0, 0x10000
	s_cmp_eq_u32 s77, s40
	s_cselect_b32 s41, s35, s41
	s_cselect_b32 s40, s34, s44
	s_cselect_b32 s45, s37, s42
	s_cselect_b32 s44, s36, s11
	s_add_i32 s49, 0, 0x14000
	v_add_u32_e32 v80, s48, v3
	v_add_u32_e32 v160, s49, v3
	ds_read_b128 v[60:63], v80
	ds_read_b128 v[68:71], v80 offset:1024
	ds_read_b128 v[76:79], v80 offset:2048
	ds_read_b128 v[80:83], v80 offset:3072
	ds_read_b128 v[148:151], v160
	ds_read_b128 v[152:155], v160 offset:1024
	ds_read_b128 v[156:159], v160 offset:2048
	ds_read_b128 v[160:163], v160 offset:3072
	v_lshl_add_u64 v[164:165], s[26:27], 0, v[192:193]
	s_add_i32 m0, s70, 0xc000
	ds_read_b128 v[206:209], v175
	ds_read_b128 v[210:213], v175 offset:1024
	ds_read_b128 v[214:217], v175 offset:2048
	ds_read_b128 v[218:221], v175 offset:3072
	ds_read_b128 v[238:241], v175 offset:4096
	ds_read_b128 v[242:245], v175 offset:5120
	ds_read_b128 v[246:249], v175 offset:6144
	ds_read_b128 v[230:233], v175 offset:7168
	global_load_lds_dwordx4 v[164:165], off
	v_lshl_add_u64 v[164:165], s[26:27], 0, v[194:195]
	s_add_i32 m0, s70, 0xe000
	s_nop 0
	global_load_lds_dwordx4 v[164:165], off
	s_waitcnt vmcnt(8)
	s_waitcnt lgkmcnt(0)
	s_barrier
; #define PG8_GOFFS(slot_) do { _Pragma("unroll") for (int _i = 0; _i < 2; ++_i) { int R, C; stage_rc(tid * 16 + _i * 8192, R, C); _Pragma("unroll") for (int _h = 0; _h < 2; ++_h) { \
;         unsigned t_ = gtab[(slot_) * 256 + R + 128 * _h]; t_ = t_ < (unsigned)(T - 1) ? t_ : (unsigned)(T - 1); voffA[_h][_i] = (t_ * (unsigned)K + (unsigned)C) * 2u; } } } while (0)
; #define PG8_STAGE(bufoff, gbase, voff) do { _Pragma("unroll") for (int _i = 0; _i < 2; ++_i) \
;         __builtin_amdgcn_global_load_lds((const unsigned*)((const char*)(gbase) + (voff)[_i]), (LAS unsigned*)(lds + (bufoff) + ldsw + _i * 8192), 16, 0, 0); } while (0)
; #define PG8_LDA(dst, b, h) do { _Pragma("unroll") for (int m = 0; m < 4; ++m) _Pragma("unroll") for (int k = 0; k < 2; ++k) dst[m][k] = *(const LAS bf16x8*)(lds + PG8_SA(b, h) + aoff + m * 2048 + k * 1024); } while (0)
; #define PG8_MMA(ai, bj, At, Bt) do { __builtin_amdgcn_s_setprio(1); _Pragma("unroll") for (int m = 0; m < 4; ++m) _Pragma("unroll") for (int n = 0; n < 2; ++n) _Pragma("unroll") for (int k = 0; k < 2; ++k) \
;         acc[ai][bj][m][n] = __builtin_amdgcn_mfma_f32_16x16x32_bf16(Bt[n][k], At[m][k], acc[ai][bj][m][n], 0, 0, 0); __builtin_amdgcn_s_setprio(0); } while (0)
; #define PG8_WAIT_V(n) asm volatile("s_waitcnt vmcnt(" #n ")" ::: "memory")
; #define PG8_WAIT_L(n) asm volatile("s_waitcnt lgkmcnt(" #n ")" ::: "memory")
; #define PG8_BAR __builtin_amdgcn_s_barrier()
; #define PG8_SCHED __builtin_amdgcn_sched_barrier(0)
; template <class Epi, class Sched>
; __device__ __forceinline__ void gemm_phase(const int tid, LAS unsigned char* lds, const bf16* Aop, const bf16* Bop, const int K_, const Sched& S, const Epi& E, const bf16* Aop1 = nullptr, const bf16* Bop1 = nullptr) {
;     ...
;             PG8_WAIT_V(8); PG8_WAIT_L(0); PG8_BAR; PG8_MMA(0, 0, At, B0); PG8_MMA(0, 1, At, B1); PG8_BAR; PG8_SCHED;
;             PG8_LDA(At, 0, 1); PG8_STAGE(PG8_SB(0, 0), b2, voffB); PG8_STAGE(PG8_SB(0, 1), b2 + hstep, voffB); if (Epi::GATHER && last && has_next) PG8_GOFFS((ui + 1) & 1); PG8_STAGE(PG8_SA(0, 0), a2, voffA[0]);
;             PG8_WAIT_V(8); PG8_WAIT_L(0); PG8_BAR; PG8_MMA(1, 0, At, B0); PG8_MMA(1, 1, At, B1); PG8_BAR; PG8_SCHED;
	s_setprio 1
	v_mfma_f32_16x16x32_bf16 v[140:143], v[60:63], v[206:209], v[140:143]
	v_mfma_f32_16x16x32_bf16 v[144:147], v[76:79], v[206:209], v[144:147]
	v_mfma_f32_16x16x32_bf16 v[128:131], v[60:63], v[214:217], v[128:131]
	v_mfma_f32_16x16x32_bf16 v[124:127], v[76:79], v[214:217], v[124:127]
	v_mfma_f32_16x16x32_bf16 v[112:115], v[60:63], v[238:241], v[112:115]
	v_mfma_f32_16x16x32_bf16 v[108:111], v[76:79], v[238:241], v[108:111]
	v_mfma_f32_16x16x32_bf16 v[96:99], v[60:63], v[246:249], v[96:99]
	v_mfma_f32_16x16x32_bf16 v[92:95], v[76:79], v[246:249], v[92:95]
	v_mfma_f32_16x16x32_bf16 v[140:143], v[68:71], v[210:213], v[140:143]
	v_mfma_f32_16x16x32_bf16 v[144:147], v[80:83], v[210:213], v[144:147]
	v_mfma_f32_16x16x32_bf16 v[128:131], v[68:71], v[218:221], v[128:131]
	v_mfma_f32_16x16x32_bf16 v[124:127], v[80:83], v[218:221], v[124:127]
	v_mfma_f32_16x16x32_bf16 v[112:115], v[68:71], v[242:245], v[112:115]
	v_mfma_f32_16x16x32_bf16 v[108:111], v[80:83], v[242:245], v[108:111]
	v_mfma_f32_16x16x32_bf16 v[96:99], v[68:71], v[230:233], v[96:99]
	v_mfma_f32_16x16x32_bf16 v[92:95], v[80:83], v[230:233], v[92:95]
	v_mfma_f32_16x16x32_bf16 v[136:139], v[148:151], v[206:209], v[136:139]
	v_mfma_f32_16x16x32_bf16 v[132:135], v[156:159], v[206:209], v[132:135]
	v_mfma_f32_16x16x32_bf16 v[120:123], v[148:151], v[214:217], v[120:123]
	v_mfma_f32_16x16x32_bf16 v[116:119], v[156:159], v[214:217], v[116:119]
	v_mfma_f32_16x16x32_bf16 v[104:107], v[148:151], v[238:241], v[104:107]
	v_mfma_f32_16x16x32_bf16 v[100:103], v[156:159], v[238:241], v[100:103]
	v_mfma_f32_16x16x32_bf16 v[88:91], v[148:151], v[246:249], v[88:91]
	v_mfma_f32_16x16x32_bf16 v[84:87], v[156:159], v[246:249], v[84:87]
	v_mfma_f32_16x16x32_bf16 v[136:139], v[152:155], v[210:213], v[136:139]
	v_mfma_f32_16x16x32_bf16 v[132:135], v[160:163], v[210:213], v[132:135]
	v_mfma_f32_16x16x32_bf16 v[120:123], v[152:155], v[218:221], v[120:123]
	v_mfma_f32_16x16x32_bf16 v[116:119], v[160:163], v[218:221], v[116:119]
	v_mfma_f32_16x16x32_bf16 v[104:107], v[152:155], v[242:245], v[104:107]
	v_mfma_f32_16x16x32_bf16 v[100:103], v[160:163], v[242:245], v[100:103]
	v_mfma_f32_16x16x32_bf16 v[88:91], v[152:155], v[230:233], v[88:91]
	v_mfma_f32_16x16x32_bf16 v[84:87], v[160:163], v[230:233], v[84:87]
	s_setprio 0
	s_barrier
	s_add_i32 s48, s48, s69
	v_lshl_add_u64 v[164:165], s[44:45], 0, v[166:167]
	s_mov_b32 m0, s48
	ds_read_b128 v[206:209], v175 offset:16384
	ds_read_b128 v[210:213], v175 offset:17408
	ds_read_b128 v[214:217], v175 offset:18432
	ds_read_b128 v[218:221], v175 offset:19456
	ds_read_b128 v[230:233], v175 offset:20480
	ds_read_b128 v[238:241], v175 offset:21504
	ds_read_b128 v[242:245], v175 offset:22528
	ds_read_b128 v[246:249], v175 offset:23552
	global_load_lds_dwordx4 v[164:165], off
	s_add_i32 m0, s48, 0x2000
	v_lshl_add_u64 v[222:223], s[44:45], 0, v[170:171]
	s_add_u32 s44, s44, s6
	s_addc_u32 s45, s45, s7
	s_add_i32 s48, s49, s69
	global_load_lds_dwordx4 v[222:223], off
	v_lshl_add_u64 v[250:251], s[44:45], 0, v[166:167]
	s_mov_b32 m0, s48
	v_lshl_add_u64 v[196:197], s[44:45], 0, v[170:171]
	global_load_lds_dwordx4 v[250:251], off
	s_add_i32 m0, s48, 0x2000
	v_lshl_add_u64 v[198:199], s[40:41], 0, v[0:1]
	global_load_lds_dwordx4 v[196:197], off
	s_mov_b32 m0, s70
	v_lshl_add_u64 v[224:225], s[40:41], 0, v[168:169]
	global_load_lds_dwordx4 v[198:199], off
	s_mov_b32 m0, s71
	s_nop 0
	global_load_lds_dwordx4 v[224:225], off
	s_waitcnt vmcnt(8)
	s_waitcnt lgkmcnt(0)
	s_barrier
	s_setprio 1
	v_mfma_f32_16x16x32_bf16 v[72:75], v[60:63], v[206:209], v[72:75]
	v_mfma_f32_16x16x32_bf16 v[64:67], v[76:79], v[206:209], v[64:67]
	v_mfma_f32_16x16x32_bf16 v[48:51], v[60:63], v[214:217], v[48:51]
	v_mfma_f32_16x16x32_bf16 v[44:47], v[76:79], v[214:217], v[44:47]
	v_mfma_f32_16x16x32_bf16 v[32:35], v[60:63], v[230:233], v[32:35]
	v_mfma_f32_16x16x32_bf16 v[28:31], v[76:79], v[230:233], v[28:31]
	v_mfma_f32_16x16x32_bf16 v[16:19], v[60:63], v[242:245], v[16:19]
	v_mfma_f32_16x16x32_bf16 v[12:15], v[76:79], v[242:245], v[12:15]
	v_mfma_f32_16x16x32_bf16 v[72:75], v[68:71], v[210:213], v[72:75]
	v_mfma_f32_16x16x32_bf16 v[64:67], v[80:83], v[210:213], v[64:67]
	v_mfma_f32_16x16x32_bf16 v[48:51], v[68:71], v[218:221], v[48:51]
	v_mfma_f32_16x16x32_bf16 v[44:47], v[80:83], v[218:221], v[44:47]
	v_mfma_f32_16x16x32_bf16 v[32:35], v[68:71], v[238:241], v[32:35]
	v_mfma_f32_16x16x32_bf16 v[28:31], v[80:83], v[238:241], v[28:31]
	v_mfma_f32_16x16x32_bf16 v[16:19], v[68:71], v[246:249], v[16:19]
	v_mfma_f32_16x16x32_bf16 v[12:15], v[80:83], v[246:249], v[12:15]
	v_mfma_f32_16x16x32_bf16 v[56:59], v[148:151], v[206:209], v[56:59]
	v_mfma_f32_16x16x32_bf16 v[52:55], v[156:159], v[206:209], v[52:55]
	v_mfma_f32_16x16x32_bf16 v[40:43], v[148:151], v[214:217], v[40:43]
	v_mfma_f32_16x16x32_bf16 v[36:39], v[156:159], v[214:217], v[36:39]
	v_mfma_f32_16x16x32_bf16 v[24:27], v[148:151], v[230:233], v[24:27]
	v_mfma_f32_16x16x32_bf16 v[20:23], v[156:159], v[230:233], v[20:23]
	v_mfma_f32_16x16x32_bf16 v[8:11], v[148:151], v[242:245], v[8:11]
	v_mfma_f32_16x16x32_bf16 v[4:7], v[156:159], v[242:245], v[4:7]
	v_mfma_f32_16x16x32_bf16 v[56:59], v[152:155], v[210:213], v[56:59]
	v_mfma_f32_16x16x32_bf16 v[52:55], v[160:163], v[210:213], v[52:55]
	v_mfma_f32_16x16x32_bf16 v[40:43], v[152:155], v[218:221], v[40:43]
	v_mfma_f32_16x16x32_bf16 v[36:39], v[160:163], v[218:221], v[36:39]
	v_mfma_f32_16x16x32_bf16 v[24:27], v[152:155], v[238:241], v[24:27]
	v_mfma_f32_16x16x32_bf16 v[20:23], v[160:163], v[238:241], v[20:23]
	v_mfma_f32_16x16x32_bf16 v[8:11], v[152:155], v[246:249], v[8:11]
	v_mfma_f32_16x16x32_bf16 v[4:7], v[160:163], v[246:249], v[4:7]
	s_setprio 0
	s_barrier
; #define PG8_STAGE(bufoff, gbase, voff) do { _Pragma("unroll") for (int _i = 0; _i < 2; ++_i) \
;         __builtin_amdgcn_global_load_lds((const unsigned*)((const char*)(gbase) + (voff)[_i]), (LAS unsigned*)(lds + (bufoff) + ldsw + _i * 8192), 16, 0, 0); } while (0)
; #define PG8_STAGE_A1(bufoff, gbase) do { if (Epi::GATHER) PG8_STAGE(bufoff, gbase, voffA[1]); else PG8_STAGE(bufoff, (gbase) + hstep, voffA[0]); } while (0)
; #define PG8_LDA(dst, b, h) do { _Pragma("unroll") for (int m = 0; m < 4; ++m) _Pragma("unroll") for (int k = 0; k < 2; ++k) dst[m][k] = *(const LAS bf16x8*)(lds + PG8_SA(b, h) + aoff + m * 2048 + k * 1024); } while (0)
; #define PG8_LDB(dst, b, h) do { _Pragma("unroll") for (int n = 0; n < 2; ++n) _Pragma("unroll") for (int k = 0; k < 2; ++k) dst[n][k] = *(const LAS bf16x8*)(lds + PG8_SB(b, h) + boff + n * 2048 + k * 1024); } while (0)
; #define PG8_MMA(ai, bj, At, Bt) do { __builtin_amdgcn_s_setprio(1); _Pragma("unroll") for (int m = 0; m < 4; ++m) _Pragma("unroll") for (int n = 0; n < 2; ++n) _Pragma("unroll") for (int k = 0; k < 2; ++k) \
;         acc[ai][bj][m][n] = __builtin_amdgcn_mfma_f32_16x16x32_bf16(Bt[n][k], At[m][k], acc[ai][bj][m][n], 0, 0, 0); __builtin_amdgcn_s_setprio(0); } while (0)
; #define PG8_WAIT_V(n) asm volatile("s_waitcnt vmcnt(" #n ")" ::: "memory")
; #define PG8_WAIT_L(n) asm volatile("s_waitcnt lgkmcnt(" #n ")" ::: "memory")
; #define PG8_BAR __builtin_amdgcn_s_barrier()
; #define PG8_SCHED __builtin_amdgcn_sched_barrier(0)
; template <class Epi, class Sched>
; __device__ __forceinline__ void gemm_phase(const int tid, LAS unsigned char* lds, const bf16* Aop, const bf16* Bop, const int K_, const Sched& S, const Epi& E, const bf16* Aop1 = nullptr, const bf16* Bop1 = nullptr) {
;     ...
;             PG8_LDB(B0, 1, 0); PG8_LDB(B1, 1, 1); PG8_SCHED; PG8_LDA(At, 1, 0); PG8_STAGE_A1(PG8_SA(0, 1), a2);
;             PG8_WAIT_V(8); PG8_WAIT_L(0); PG8_BAR; PG8_MMA(0, 0, At, B0); PG8_MMA(0, 1, At, B1); PG8_BAR; PG8_SCHED;
;             PG8_LDA(At, 1, 1); PG8_STAGE(PG8_SB(1, 0), b3, voffB); PG8_STAGE(PG8_SB(1, 1), b3 + hstep, voffB); PG8_STAGE(PG8_SA(1, 0), a3, voffA[0]);
;             PG8_WAIT_V(8); PG8_WAIT_L(0); PG8_BAR; PG8_MMA(1, 0, At, B0); PG8_MMA(1, 1, At, B1); PG8_BAR; PG8_SCHED;
;         }
	s_add_i32 s44, 0, 0x18000
	s_add_i32 s45, 0, 0x1c000
	v_add_u32_e32 v80, s44, v3
	v_add_u32_e32 v160, s45, v3
	ds_read_b128 v[60:63], v80
	ds_read_b128 v[68:71], v80 offset:1024
	ds_read_b128 v[76:79], v80 offset:2048
	ds_read_b128 v[80:83], v80 offset:3072
	ds_read_b128 v[148:151], v160
	ds_read_b128 v[152:155], v160 offset:1024
	ds_read_b128 v[156:159], v160 offset:2048
	ds_read_b128 v[160:163], v160 offset:3072
	s_add_u32 s40, s40, s6
	s_addc_u32 s41, s41, s7
	s_mov_b32 m0, s72
	v_lshl_add_u64 v[190:191], s[40:41], 0, v[0:1]
	ds_read_b128 v[206:209], v175 offset:32768
	ds_read_b128 v[210:213], v175 offset:33792
	ds_read_b128 v[214:217], v175 offset:34816
	ds_read_b128 v[218:221], v175 offset:35840
	ds_read_b128 v[230:233], v175 offset:36864
	ds_read_b128 v[238:241], v175 offset:37888
	ds_read_b128 v[242:245], v175 offset:38912
	ds_read_b128 v[246:249], v175 offset:39936
	global_load_lds_dwordx4 v[190:191], off
	v_lshl_add_u64 v[190:191], s[40:41], 0, v[168:169]
	s_mov_b32 m0, s73
	s_nop 0
	global_load_lds_dwordx4 v[190:191], off
	s_waitcnt vmcnt(8)
	s_waitcnt lgkmcnt(0)
	s_barrier
	s_setprio 1
	v_mfma_f32_16x16x32_bf16 v[140:143], v[60:63], v[206:209], v[140:143]
	v_mfma_f32_16x16x32_bf16 v[144:147], v[76:79], v[206:209], v[144:147]
	v_mfma_f32_16x16x32_bf16 v[128:131], v[60:63], v[214:217], v[128:131]
	v_mfma_f32_16x16x32_bf16 v[124:127], v[76:79], v[214:217], v[124:127]
	v_mfma_f32_16x16x32_bf16 v[112:115], v[60:63], v[230:233], v[112:115]
	v_mfma_f32_16x16x32_bf16 v[108:111], v[76:79], v[230:233], v[108:111]
	v_mfma_f32_16x16x32_bf16 v[96:99], v[60:63], v[242:245], v[96:99]
	v_mfma_f32_16x16x32_bf16 v[92:95], v[76:79], v[242:245], v[92:95]
	v_mfma_f32_16x16x32_bf16 v[140:143], v[68:71], v[210:213], v[140:143]
	v_mfma_f32_16x16x32_bf16 v[144:147], v[80:83], v[210:213], v[144:147]
	v_mfma_f32_16x16x32_bf16 v[128:131], v[68:71], v[218:221], v[128:131]
	v_mfma_f32_16x16x32_bf16 v[124:127], v[80:83], v[218:221], v[124:127]
	v_mfma_f32_16x16x32_bf16 v[112:115], v[68:71], v[238:241], v[112:115]
	v_mfma_f32_16x16x32_bf16 v[108:111], v[80:83], v[238:241], v[108:111]
	v_mfma_f32_16x16x32_bf16 v[96:99], v[68:71], v[246:249], v[96:99]
	v_mfma_f32_16x16x32_bf16 v[92:95], v[80:83], v[246:249], v[92:95]
	v_mfma_f32_16x16x32_bf16 v[136:139], v[148:151], v[206:209], v[136:139]
	v_mfma_f32_16x16x32_bf16 v[132:135], v[156:159], v[206:209], v[132:135]
	v_mfma_f32_16x16x32_bf16 v[120:123], v[148:151], v[214:217], v[120:123]
	v_mfma_f32_16x16x32_bf16 v[116:119], v[156:159], v[214:217], v[116:119]
	v_mfma_f32_16x16x32_bf16 v[104:107], v[148:151], v[230:233], v[104:107]
	v_mfma_f32_16x16x32_bf16 v[100:103], v[156:159], v[230:233], v[100:103]
	v_mfma_f32_16x16x32_bf16 v[88:91], v[148:151], v[242:245], v[88:91]
	v_mfma_f32_16x16x32_bf16 v[84:87], v[156:159], v[242:245], v[84:87]
	v_mfma_f32_16x16x32_bf16 v[136:139], v[152:155], v[210:213], v[136:139]
	v_mfma_f32_16x16x32_bf16 v[132:135], v[160:163], v[210:213], v[132:135]
	v_mfma_f32_16x16x32_bf16 v[120:123], v[152:155], v[218:221], v[120:123]
	v_mfma_f32_16x16x32_bf16 v[116:119], v[160:163], v[218:221], v[116:119]
	v_mfma_f32_16x16x32_bf16 v[104:107], v[152:155], v[238:241], v[104:107]
	v_mfma_f32_16x16x32_bf16 v[100:103], v[160:163], v[238:241], v[100:103]
	v_mfma_f32_16x16x32_bf16 v[88:91], v[152:155], v[246:249], v[88:91]
	v_mfma_f32_16x16x32_bf16 v[84:87], v[160:163], v[246:249], v[84:87]
	s_setprio 0
	s_barrier
	s_add_i32 s40, s44, s69
	v_lshl_add_u64 v[164:165], v[164:165], 0, s[20:21]
	s_mov_b32 m0, s40
	ds_read_b128 v[206:209], v175 offset:49152
	ds_read_b128 v[210:213], v175 offset:50176
	ds_read_b128 v[214:217], v175 offset:51200
	ds_read_b128 v[218:221], v175 offset:52224
	ds_read_b128 v[230:233], v175 offset:53248
	ds_read_b128 v[238:241], v175 offset:54272
	ds_read_b128 v[242:245], v175 offset:55296
	ds_read_b128 v[246:249], v175 offset:56320
	global_load_lds_dwordx4 v[164:165], off
	v_lshl_add_u64 v[164:165], v[222:223], 0, s[20:21]
	s_add_i32 m0, s40, 0x2000
	s_add_i32 s40, s45, s69
	global_load_lds_dwordx4 v[164:165], off
	v_lshl_add_u64 v[164:165], v[250:251], 0, s[20:21]
	s_mov_b32 m0, s40
	s_nop 0
	global_load_lds_dwordx4 v[164:165], off
	v_lshl_add_u64 v[164:165], v[196:197], 0, s[20:21]
	s_add_i32 m0, s40, 0x2000
	s_nop 0
	global_load_lds_dwordx4 v[164:165], off
	v_lshl_add_u64 v[164:165], v[198:199], 0, s[20:21]
	s_mov_b32 m0, s75
	s_nop 0
	global_load_lds_dwordx4 v[164:165], off
	v_lshl_add_u64 v[164:165], v[224:225], 0, s[20:21]
	s_mov_b32 m0, s76
	s_nop 0
	global_load_lds_dwordx4 v[164:165], off
	s_waitcnt vmcnt(8)
	s_waitcnt lgkmcnt(0)
	s_barrier
	s_setprio 1
	v_mfma_f32_16x16x32_bf16 v[72:75], v[60:63], v[206:209], v[72:75]
	v_mfma_f32_16x16x32_bf16 v[64:67], v[76:79], v[206:209], v[64:67]
	v_mfma_f32_16x16x32_bf16 v[48:51], v[60:63], v[214:217], v[48:51]
	v_mfma_f32_16x16x32_bf16 v[44:47], v[76:79], v[214:217], v[44:47]
	v_mfma_f32_16x16x32_bf16 v[32:35], v[60:63], v[230:233], v[32:35]
	v_mfma_f32_16x16x32_bf16 v[28:31], v[76:79], v[230:233], v[28:31]
	v_mfma_f32_16x16x32_bf16 v[16:19], v[60:63], v[242:245], v[16:19]
	v_mfma_f32_16x16x32_bf16 v[12:15], v[76:79], v[242:245], v[12:15]
	v_mfma_f32_16x16x32_bf16 v[72:75], v[68:71], v[210:213], v[72:75]
	v_mfma_f32_16x16x32_bf16 v[64:67], v[80:83], v[210:213], v[64:67]
	v_mfma_f32_16x16x32_bf16 v[48:51], v[68:71], v[218:221], v[48:51]
	v_mfma_f32_16x16x32_bf16 v[44:47], v[80:83], v[218:221], v[44:47]
	v_mfma_f32_16x16x32_bf16 v[32:35], v[68:71], v[238:241], v[32:35]
	v_mfma_f32_16x16x32_bf16 v[28:31], v[80:83], v[238:241], v[28:31]
	v_mfma_f32_16x16x32_bf16 v[16:19], v[68:71], v[246:249], v[16:19]
	v_mfma_f32_16x16x32_bf16 v[12:15], v[80:83], v[246:249], v[12:15]
	v_mfma_f32_16x16x32_bf16 v[56:59], v[148:151], v[206:209], v[56:59]
	v_mfma_f32_16x16x32_bf16 v[52:55], v[156:159], v[206:209], v[52:55]
	v_mfma_f32_16x16x32_bf16 v[40:43], v[148:151], v[214:217], v[40:43]
	v_mfma_f32_16x16x32_bf16 v[36:39], v[156:159], v[214:217], v[36:39]
	v_mfma_f32_16x16x32_bf16 v[24:27], v[148:151], v[230:233], v[24:27]
	v_mfma_f32_16x16x32_bf16 v[20:23], v[156:159], v[230:233], v[20:23]
	v_mfma_f32_16x16x32_bf16 v[8:11], v[148:151], v[242:245], v[8:11]
	v_mfma_f32_16x16x32_bf16 v[4:7], v[156:159], v[242:245], v[4:7]
	v_mfma_f32_16x16x32_bf16 v[56:59], v[152:155], v[210:213], v[56:59]
	v_mfma_f32_16x16x32_bf16 v[52:55], v[160:163], v[210:213], v[52:55]
	v_mfma_f32_16x16x32_bf16 v[40:43], v[152:155], v[218:221], v[40:43]
	v_mfma_f32_16x16x32_bf16 v[36:39], v[160:163], v[218:221], v[36:39]
	v_mfma_f32_16x16x32_bf16 v[24:27], v[152:155], v[238:241], v[24:27]
	v_mfma_f32_16x16x32_bf16 v[20:23], v[160:163], v[238:241], v[20:23]
	v_mfma_f32_16x16x32_bf16 v[8:11], v[152:155], v[246:249], v[8:11]
	v_mfma_f32_16x16x32_bf16 v[4:7], v[160:163], v[246:249], v[4:7]
	s_setprio 0
	s_barrier
	s_add_u32 s26, s26, 0x100
	s_addc_u32 s27, s27, 0
	s_add_u32 s11, s11, 0x100
	s_addc_u32 s42, s42, 0
	s_cmp_ge_i32 s43, s74
	s_mov_b32 s40, s43
	s_cbranch_scc0 .LBB0_131

; #define PG8_GOFFS(slot_) do { _Pragma("unroll") for (int _i = 0; _i < 2; ++_i) { int R, C; stage_rc(tid * 16 + _i * 8192, R, C); _Pragma("unroll") for (int _h = 0; _h < 2; ++_h) { \
;         unsigned t_ = gtab[(slot_) * 256 + R + 128 * _h]; t_ = t_ < (unsigned)(T - 1) ? t_ : (unsigned)(T - 1); voffA[_h][_i] = (t_ * (unsigned)K + (unsigned)C) * 2u; } } } while (0)
; #define PG8_STAGE(bufoff, gbase, voff) do { _Pragma("unroll") for (int _i = 0; _i < 2; ++_i) \
;         __builtin_amdgcn_global_load_lds((const unsigned*)((const char*)(gbase) + (voff)[_i]), (LAS unsigned*)(lds + (bufoff) + ldsw + _i * 8192), 16, 0, 0); } while (0)
; #define PG8_STAGE_A1(bufoff, gbase) do { if (Epi::GATHER) PG8_STAGE(bufoff, gbase, voffA[1]); else PG8_STAGE(bufoff, (gbase) + hstep, voffA[0]); } while (0)
; #define PG8_WAIT_V(n) asm volatile("s_waitcnt vmcnt(" #n ")" ::: "memory")
; template <class Epi, class Sched>
; __device__ __forceinline__ void gemm_phase(const int tid, LAS unsigned char* lds, const bf16* Aop, const bf16* Bop, const int K_, const Sched& S, const Epi& E, const bf16* Aop1 = nullptr, const bf16* Bop1 = nullptr) {
;     ...
;     f32x4 acc[2][2][4][2];
; #pragma unroll
;     for (int a = 0; a < 2; ++a)
; #pragma unroll
;         for (int b = 0; b < 2; ++b)
; #pragma unroll
;             for (int m = 0; m < 4; ++m)
; #pragma unroll
;                 for (int n = 0; n < 2; ++n) acc[a][b][m][n] = (f32x4){0.f, 0.f, 0.f, 0.f};
;     ...
;         for (int t = 0; t < nt; t += 2) {
;             const bool last = (t == nt - 2);
;             const char* a1 = cA + (size_t)(t + 1) * kstep;
;             const char* a2 = last ? nA : cA + (size_t)(t + 2) * kstep; const char* b2 = last ? nB : cB + (size_t)(t + 2) * kstep;
;             const char* a3 = a2 + kstep; const char* b3 = b2 + kstep;
;             PG8_LDB(B0, 0, 0); PG8_LDB(B1, 0, 1); PG8_SCHED; PG8_LDA(At, 0, 0); PG8_STAGE_A1(PG8_SA(1, 1), a1);
;             PG8_WAIT_V(8); PG8_WAIT_L(0); PG8_BAR; PG8_MMA(0, 0, At, B0); PG8_MMA(0, 1, At, B1); PG8_BAR; PG8_SCHED;
;             PG8_LDA(At, 0, 1); PG8_STAGE(PG8_SB(0, 0), b2, voffB); PG8_STAGE(PG8_SB(0, 1), b2 + hstep, voffB); if (Epi::GATHER && last && has_next) PG8_GOFFS((ui + 1) & 1); PG8_STAGE(PG8_SA(0, 0), a2, voffA[0]);
;             PG8_WAIT_V(8); PG8_WAIT_L(0); PG8_BAR; PG8_MMA(1, 0, At, B0); PG8_MMA(1, 1, At, B1); PG8_BAR; PG8_SCHED;
.LBB0_998:
	v_mov_b32_e32 v131, 0
	s_andn2_b64 vcc, exec, s[44:45]
	s_cbranch_vccnz .LBB0_1001
	s_add_u32 s12, s12, 0x80
	s_addc_u32 s13, s13, 0
	s_add_u32 s11, s26, 0x100
	s_addc_u32 s71, s27, 0
	s_mov_b32 s26, 0
	s_add_i32 s72, s26, 2
	s_add_u32 s73, s12, 0x80
	s_addc_u32 s27, s13, 0
	s_add_i32 s76, 0, 0x10000
	s_cmp_eq_u32 s64, s26
	s_cselect_b32 s27, s7, s27
	s_cselect_b32 s26, s6, s73
	s_cselect_b32 s75, s41, s71
	s_cselect_b32 s74, s40, s11
	s_add_i32 s73, 0, 0x14000
	v_add_u32_e32 v156, s76, v171
	v_add_u32_e32 v178, s73, v171
	ds_read_b128 v[132:135], v156
	ds_read_b128 v[148:151], v156 offset:1024
	ds_read_b128 v[152:155], v156 offset:2048
	ds_read_b128 v[156:159], v156 offset:3072
	ds_read_b128 v[160:163], v178
	ds_read_b128 v[164:167], v178 offset:1024
	ds_read_b128 v[174:177], v178 offset:2048
	ds_read_b128 v[178:181], v178 offset:3072
	v_lshl_add_u64 v[194:195], s[12:13], 0, v[144:145]
	s_add_i32 m0, s56, 0xc000
	ds_read_b128 v[182:185], v173
	ds_read_b128 v[186:189], v173 offset:1024
	ds_read_b128 v[190:193], v173 offset:2048
	ds_read_b128 v[202:205], v173 offset:3072
	ds_read_b128 v[206:209], v173 offset:4096
	ds_read_b128 v[210:213], v173 offset:5120
	ds_read_b128 v[214:217], v173 offset:6144
	ds_read_b128 v[218:221], v173 offset:7168
	global_load_lds_dwordx4 v[194:195], off
	v_lshl_add_u64 v[194:195], s[12:13], 0, v[146:147]
	s_add_i32 m0, s56, 0xe000
	s_nop 0
	global_load_lds_dwordx4 v[194:195], off
	s_waitcnt vmcnt(8)
	s_waitcnt lgkmcnt(0)
	s_barrier
	s_setprio 1
	v_mfma_f32_16x16x32_bf16 v[128:131], v[132:135], v[182:185], 0
	v_mfma_f32_16x16x32_bf16 v[124:127], v[152:155], v[182:185], 0
	v_mfma_f32_16x16x32_bf16 v[112:115], v[132:135], v[190:193], 0
	v_mfma_f32_16x16x32_bf16 v[108:111], v[152:155], v[190:193], 0
	v_mfma_f32_16x16x32_bf16 v[96:99], v[132:135], v[206:209], 0
	v_mfma_f32_16x16x32_bf16 v[92:95], v[152:155], v[206:209], 0
	v_mfma_f32_16x16x32_bf16 v[80:83], v[132:135], v[214:217], 0
	v_mfma_f32_16x16x32_bf16 v[76:79], v[152:155], v[214:217], 0
	v_mfma_f32_16x16x32_bf16 v[128:131], v[148:151], v[186:189], v[128:131]
	v_mfma_f32_16x16x32_bf16 v[124:127], v[156:159], v[186:189], v[124:127]
	v_mfma_f32_16x16x32_bf16 v[112:115], v[148:151], v[202:205], v[112:115]
	v_mfma_f32_16x16x32_bf16 v[108:111], v[156:159], v[202:205], v[108:111]
	v_mfma_f32_16x16x32_bf16 v[96:99], v[148:151], v[210:213], v[96:99]
	v_mfma_f32_16x16x32_bf16 v[92:95], v[156:159], v[210:213], v[92:95]
	v_mfma_f32_16x16x32_bf16 v[80:83], v[148:151], v[218:221], v[80:83]
	v_mfma_f32_16x16x32_bf16 v[76:79], v[156:159], v[218:221], v[76:79]
	v_mfma_f32_16x16x32_bf16 v[120:123], v[160:163], v[182:185], 0
	v_mfma_f32_16x16x32_bf16 v[116:119], v[174:177], v[182:185], 0
	v_mfma_f32_16x16x32_bf16 v[104:107], v[160:163], v[190:193], 0
	v_mfma_f32_16x16x32_bf16 v[100:103], v[174:177], v[190:193], 0
	v_mfma_f32_16x16x32_bf16 v[88:91], v[160:163], v[206:209], 0
	v_mfma_f32_16x16x32_bf16 v[84:87], v[174:177], v[206:209], 0
	v_mfma_f32_16x16x32_bf16 v[72:75], v[160:163], v[214:217], 0
	v_mfma_f32_16x16x32_bf16 v[68:71], v[174:177], v[214:217], 0
	v_mfma_f32_16x16x32_bf16 v[120:123], v[164:167], v[186:189], v[120:123]
	v_mfma_f32_16x16x32_bf16 v[116:119], v[178:181], v[186:189], v[116:119]
	v_mfma_f32_16x16x32_bf16 v[104:107], v[164:167], v[202:205], v[104:107]
	v_mfma_f32_16x16x32_bf16 v[100:103], v[178:181], v[202:205], v[100:103]
	v_mfma_f32_16x16x32_bf16 v[88:91], v[164:167], v[210:213], v[88:91]
	v_mfma_f32_16x16x32_bf16 v[84:87], v[178:181], v[210:213], v[84:87]
	v_mfma_f32_16x16x32_bf16 v[72:75], v[164:167], v[218:221], v[72:75]
	v_mfma_f32_16x16x32_bf16 v[68:71], v[178:181], v[218:221], v[68:71]
	s_setprio 0
	s_barrier
	s_add_i32 s76, s76, s55
	v_lshl_add_u64 v[194:195], s[74:75], 0, v[136:137]
	s_mov_b32 m0, s76
	ds_read_b128 v[182:185], v173 offset:16384
	ds_read_b128 v[186:189], v173 offset:17408
	ds_read_b128 v[190:193], v173 offset:18432
	ds_read_b128 v[202:205], v173 offset:19456
	ds_read_b128 v[206:209], v173 offset:20480
	ds_read_b128 v[210:213], v173 offset:21504
	ds_read_b128 v[214:217], v173 offset:22528
	ds_read_b128 v[218:221], v173 offset:23552
	global_load_lds_dwordx4 v[194:195], off
	s_add_i32 m0, s76, 0x2000
	v_lshl_add_u64 v[196:197], s[74:75], 0, v[140:141]
	s_add_u32 s74, s74, s18
	s_addc_u32 s75, s75, s19
	s_add_i32 s73, s73, s55
	global_load_lds_dwordx4 v[196:197], off
	v_lshl_add_u64 v[198:199], s[74:75], 0, v[136:137]
	s_mov_b32 m0, s73
	v_lshl_add_u64 v[222:223], s[74:75], 0, v[140:141]
	global_load_lds_dwordx4 v[198:199], off
	s_add_i32 m0, s73, 0x2000
	v_lshl_add_u64 v[224:225], s[26:27], 0, v[0:1]
	global_load_lds_dwordx4 v[222:223], off
	s_mov_b32 m0, s56
	v_lshl_add_u64 v[230:231], s[26:27], 0, v[138:139]
	global_load_lds_dwordx4 v[224:225], off
	s_mov_b32 m0, s57
	s_nop 0
	global_load_lds_dwordx4 v[230:231], off
	s_waitcnt vmcnt(8)
	s_waitcnt lgkmcnt(0)
	s_barrier
; #define PG8_STAGE_A1(bufoff, gbase) do { if (Epi::GATHER) PG8_STAGE(bufoff, gbase, voffA[1]); else PG8_STAGE(bufoff, (gbase) + hstep, voffA[0]); } while (0)
; #define PG8_LDA(dst, b, h) do { _Pragma("unroll") for (int m = 0; m < 4; ++m) _Pragma("unroll") for (int k = 0; k < 2; ++k) dst[m][k] = *(const LAS bf16x8*)(lds + PG8_SA(b, h) + aoff + m * 2048 + k * 1024); } while (0)
; #define PG8_LDB(dst, b, h) do { _Pragma("unroll") for (int n = 0; n < 2; ++n) _Pragma("unroll") for (int k = 0; k < 2; ++k) dst[n][k] = *(const LAS bf16x8*)(lds + PG8_SB(b, h) + boff + n * 2048 + k * 1024); } while (0)
; #define PG8_MMA(ai, bj, At, Bt) do { __builtin_amdgcn_s_setprio(1); _Pragma("unroll") for (int m = 0; m < 4; ++m) _Pragma("unroll") for (int n = 0; n < 2; ++n) _Pragma("unroll") for (int k = 0; k < 2; ++k) \
;         acc[ai][bj][m][n] = __builtin_amdgcn_mfma_f32_16x16x32_bf16(Bt[n][k], At[m][k], acc[ai][bj][m][n], 0, 0, 0); __builtin_amdgcn_s_setprio(0); } while (0)
; #define PG8_WAIT_V(n) asm volatile("s_waitcnt vmcnt(" #n ")" ::: "memory")
; #define PG8_WAIT_L(n) asm volatile("s_waitcnt lgkmcnt(" #n ")" ::: "memory")
; #define PG8_BAR __builtin_amdgcn_s_barrier()
; #define PG8_SCHED __builtin_amdgcn_sched_barrier(0)
; template <class Epi, class Sched>
; __device__ __forceinline__ void gemm_phase(const int tid, LAS unsigned char* lds, const bf16* Aop, const bf16* Bop, const int K_, const Sched& S, const Epi& E, const bf16* Aop1 = nullptr, const bf16* Bop1 = nullptr) {
;     ...
;             PG8_WAIT_V(8); PG8_WAIT_L(0); PG8_BAR; PG8_MMA(1, 0, At, B0); PG8_MMA(1, 1, At, B1); PG8_BAR; PG8_SCHED;
;             PG8_LDB(B0, 1, 0); PG8_LDB(B1, 1, 1); PG8_SCHED; PG8_LDA(At, 1, 0); PG8_STAGE_A1(PG8_SA(0, 1), a2);
;             PG8_WAIT_V(8); PG8_WAIT_L(0); PG8_BAR; PG8_MMA(0, 0, At, B0); PG8_MMA(0, 1, At, B1); PG8_BAR; PG8_SCHED;
	s_setprio 1
	v_mfma_f32_16x16x32_bf16 v[64:67], v[132:135], v[182:185], 0
	v_mfma_f32_16x16x32_bf16 v[60:63], v[152:155], v[182:185], 0
	v_mfma_f32_16x16x32_bf16 v[48:51], v[132:135], v[190:193], 0
	v_mfma_f32_16x16x32_bf16 v[44:47], v[152:155], v[190:193], 0
	v_mfma_f32_16x16x32_bf16 v[32:35], v[132:135], v[206:209], 0
	v_mfma_f32_16x16x32_bf16 v[28:31], v[152:155], v[206:209], 0
	v_mfma_f32_16x16x32_bf16 v[16:19], v[132:135], v[214:217], 0
	v_mfma_f32_16x16x32_bf16 v[12:15], v[152:155], v[214:217], 0
	v_mfma_f32_16x16x32_bf16 v[64:67], v[148:151], v[186:189], v[64:67]
	v_mfma_f32_16x16x32_bf16 v[60:63], v[156:159], v[186:189], v[60:63]
	v_mfma_f32_16x16x32_bf16 v[48:51], v[148:151], v[202:205], v[48:51]
	v_mfma_f32_16x16x32_bf16 v[44:47], v[156:159], v[202:205], v[44:47]
	v_mfma_f32_16x16x32_bf16 v[32:35], v[148:151], v[210:213], v[32:35]
	v_mfma_f32_16x16x32_bf16 v[28:31], v[156:159], v[210:213], v[28:31]
	v_mfma_f32_16x16x32_bf16 v[16:19], v[148:151], v[218:221], v[16:19]
	v_mfma_f32_16x16x32_bf16 v[12:15], v[156:159], v[218:221], v[12:15]
	v_mfma_f32_16x16x32_bf16 v[56:59], v[160:163], v[182:185], 0
	v_mfma_f32_16x16x32_bf16 v[52:55], v[174:177], v[182:185], 0
	v_mfma_f32_16x16x32_bf16 v[40:43], v[160:163], v[190:193], 0
	v_mfma_f32_16x16x32_bf16 v[36:39], v[174:177], v[190:193], 0
	v_mfma_f32_16x16x32_bf16 v[24:27], v[160:163], v[206:209], 0
	v_mfma_f32_16x16x32_bf16 v[20:23], v[174:177], v[206:209], 0
	v_mfma_f32_16x16x32_bf16 v[8:11], v[160:163], v[214:217], 0
	v_mfma_f32_16x16x32_bf16 v[4:7], v[174:177], v[214:217], 0
	v_mfma_f32_16x16x32_bf16 v[56:59], v[164:167], v[186:189], v[56:59]
	v_mfma_f32_16x16x32_bf16 v[52:55], v[178:181], v[186:189], v[52:55]
	v_mfma_f32_16x16x32_bf16 v[40:43], v[164:167], v[202:205], v[40:43]
	v_mfma_f32_16x16x32_bf16 v[36:39], v[178:181], v[202:205], v[36:39]
	v_mfma_f32_16x16x32_bf16 v[24:27], v[164:167], v[210:213], v[24:27]
	v_mfma_f32_16x16x32_bf16 v[20:23], v[178:181], v[210:213], v[20:23]
	v_mfma_f32_16x16x32_bf16 v[8:11], v[164:167], v[218:221], v[8:11]
	v_mfma_f32_16x16x32_bf16 v[4:7], v[178:181], v[218:221], v[4:7]
	s_setprio 0
	s_barrier
	s_add_i32 s73, 0, 0x18000
	s_add_i32 s74, 0, 0x1c000
	v_add_u32_e32 v156, s73, v171
	v_add_u32_e32 v178, s74, v171
	ds_read_b128 v[132:135], v156
	ds_read_b128 v[148:151], v156 offset:1024
	ds_read_b128 v[152:155], v156 offset:2048
	ds_read_b128 v[156:159], v156 offset:3072
	ds_read_b128 v[160:163], v178
	ds_read_b128 v[164:167], v178 offset:1024
	ds_read_b128 v[174:177], v178 offset:2048
	ds_read_b128 v[178:181], v178 offset:3072
	s_add_u32 s26, s26, s18
	s_addc_u32 s27, s27, s19
	s_mov_b32 m0, s58
	v_lshl_add_u64 v[232:233], s[26:27], 0, v[0:1]
	ds_read_b128 v[182:185], v173 offset:32768
	ds_read_b128 v[186:189], v173 offset:33792
	ds_read_b128 v[190:193], v173 offset:34816
	ds_read_b128 v[202:205], v173 offset:35840
	ds_read_b128 v[206:209], v173 offset:36864
	ds_read_b128 v[210:213], v173 offset:37888
	ds_read_b128 v[214:217], v173 offset:38912
	ds_read_b128 v[218:221], v173 offset:39936
	global_load_lds_dwordx4 v[232:233], off
	v_lshl_add_u64 v[232:233], s[26:27], 0, v[138:139]
	s_mov_b32 m0, s59
	s_nop 0
	global_load_lds_dwordx4 v[232:233], off
	s_waitcnt vmcnt(8)
	s_waitcnt lgkmcnt(0)
	s_barrier
	s_setprio 1
	v_mfma_f32_16x16x32_bf16 v[128:131], v[132:135], v[182:185], v[128:131]
	v_mfma_f32_16x16x32_bf16 v[124:127], v[152:155], v[182:185], v[124:127]
	v_mfma_f32_16x16x32_bf16 v[112:115], v[132:135], v[190:193], v[112:115]
	v_mfma_f32_16x16x32_bf16 v[108:111], v[152:155], v[190:193], v[108:111]
	v_mfma_f32_16x16x32_bf16 v[96:99], v[132:135], v[206:209], v[96:99]
	v_mfma_f32_16x16x32_bf16 v[92:95], v[152:155], v[206:209], v[92:95]
	v_mfma_f32_16x16x32_bf16 v[80:83], v[132:135], v[214:217], v[80:83]
	v_mfma_f32_16x16x32_bf16 v[76:79], v[152:155], v[214:217], v[76:79]
	v_mfma_f32_16x16x32_bf16 v[128:131], v[148:151], v[186:189], v[128:131]
	v_mfma_f32_16x16x32_bf16 v[124:127], v[156:159], v[186:189], v[124:127]
	v_mfma_f32_16x16x32_bf16 v[112:115], v[148:151], v[202:205], v[112:115]
	v_mfma_f32_16x16x32_bf16 v[108:111], v[156:159], v[202:205], v[108:111]
	v_mfma_f32_16x16x32_bf16 v[96:99], v[148:151], v[210:213], v[96:99]
	v_mfma_f32_16x16x32_bf16 v[92:95], v[156:159], v[210:213], v[92:95]
	v_mfma_f32_16x16x32_bf16 v[80:83], v[148:151], v[218:221], v[80:83]
	v_mfma_f32_16x16x32_bf16 v[76:79], v[156:159], v[218:221], v[76:79]
	v_mfma_f32_16x16x32_bf16 v[120:123], v[160:163], v[182:185], v[120:123]
	v_mfma_f32_16x16x32_bf16 v[116:119], v[174:177], v[182:185], v[116:119]
	v_mfma_f32_16x16x32_bf16 v[104:107], v[160:163], v[190:193], v[104:107]
	v_mfma_f32_16x16x32_bf16 v[100:103], v[174:177], v[190:193], v[100:103]
	v_mfma_f32_16x16x32_bf16 v[88:91], v[160:163], v[206:209], v[88:91]
	v_mfma_f32_16x16x32_bf16 v[84:87], v[174:177], v[206:209], v[84:87]
	v_mfma_f32_16x16x32_bf16 v[72:75], v[160:163], v[214:217], v[72:75]
	v_mfma_f32_16x16x32_bf16 v[68:71], v[174:177], v[214:217], v[68:71]
	v_mfma_f32_16x16x32_bf16 v[120:123], v[164:167], v[186:189], v[120:123]
	v_mfma_f32_16x16x32_bf16 v[116:119], v[178:181], v[186:189], v[116:119]
	v_mfma_f32_16x16x32_bf16 v[104:107], v[164:167], v[202:205], v[104:107]
	v_mfma_f32_16x16x32_bf16 v[100:103], v[178:181], v[202:205], v[100:103]
	v_mfma_f32_16x16x32_bf16 v[88:91], v[164:167], v[210:213], v[88:91]
	v_mfma_f32_16x16x32_bf16 v[84:87], v[178:181], v[210:213], v[84:87]
	v_mfma_f32_16x16x32_bf16 v[72:75], v[164:167], v[218:221], v[72:75]
	v_mfma_f32_16x16x32_bf16 v[68:71], v[178:181], v[218:221], v[68:71]
	s_setprio 0
	s_barrier
; #define PG8_GOFFS(slot_) do { _Pragma("unroll") for (int _i = 0; _i < 2; ++_i) { int R, C; stage_rc(tid * 16 + _i * 8192, R, C); _Pragma("unroll") for (int _h = 0; _h < 2; ++_h) { \
;         unsigned t_ = gtab[(slot_) * 256 + R + 128 * _h]; t_ = t_ < (unsigned)(T - 1) ? t_ : (unsigned)(T - 1); voffA[_h][_i] = (t_ * (unsigned)K + (unsigned)C) * 2u; } } } while (0)
; #define PG8_STAGE(bufoff, gbase, voff) do { _Pragma("unroll") for (int _i = 0; _i < 2; ++_i) \
;         __builtin_amdgcn_global_load_lds((const unsigned*)((const char*)(gbase) + (voff)[_i]), (LAS unsigned*)(lds + (bufoff) + ldsw + _i * 8192), 16, 0, 0); } while (0)
; #define PG8_WAIT_V(n) asm volatile("s_waitcnt vmcnt(" #n ")" ::: "memory")
; template <class Epi, class Sched>
; __device__ __forceinline__ void gemm_phase(const int tid, LAS unsigned char* lds, const bf16* Aop, const bf16* Bop, const int K_, const Sched& S, const Epi& E, const bf16* Aop1 = nullptr, const bf16* Bop1 = nullptr) {
;     ...
;         for (int t = 0; t < nt; t += 2) {
;             const bool last = (t == nt - 2);
;             const char* a1 = cA + (size_t)(t + 1) * kstep;
;             const char* a2 = last ? nA : cA + (size_t)(t + 2) * kstep; const char* b2 = last ? nB : cB + (size_t)(t + 2) * kstep;
;             const char* a3 = a2 + kstep; const char* b3 = b2 + kstep;
;             PG8_LDB(B0, 0, 0); PG8_LDB(B1, 0, 1); PG8_SCHED; PG8_LDA(At, 0, 0); PG8_STAGE_A1(PG8_SA(1, 1), a1);
;             PG8_WAIT_V(8); PG8_WAIT_L(0); PG8_BAR; PG8_MMA(0, 0, At, B0); PG8_MMA(0, 1, At, B1); PG8_BAR; PG8_SCHED;
;             PG8_LDA(At, 0, 1); PG8_STAGE(PG8_SB(0, 0), b2, voffB); PG8_STAGE(PG8_SB(0, 1), b2 + hstep, voffB); if (Epi::GATHER && last && has_next) PG8_GOFFS((ui + 1) & 1); PG8_STAGE(PG8_SA(0, 0), a2, voffA[0]);
;             PG8_WAIT_V(8); PG8_WAIT_L(0); PG8_BAR; PG8_MMA(1, 0, At, B0); PG8_MMA(1, 1, At, B1); PG8_BAR; PG8_SCHED;
;             PG8_LDB(B0, 1, 0); PG8_LDB(B1, 1, 1); PG8_SCHED; PG8_LDA(At, 1, 0); PG8_STAGE_A1(PG8_SA(0, 1), a2);
;             PG8_WAIT_V(8); PG8_WAIT_L(0); PG8_BAR; PG8_MMA(0, 0, At, B0); PG8_MMA(0, 1, At, B1); PG8_BAR; PG8_SCHED;
;             PG8_LDA(At, 1, 1); PG8_STAGE(PG8_SB(1, 0), b3, voffB); PG8_STAGE(PG8_SB(1, 1), b3 + hstep, voffB); PG8_STAGE(PG8_SA(1, 0), a3, voffA[0]);
;             PG8_WAIT_V(8); PG8_WAIT_L(0); PG8_BAR; PG8_MMA(1, 0, At, B0); PG8_MMA(1, 1, At, B1); PG8_BAR; PG8_SCHED;
	s_add_i32 s26, s73, s55
	v_lshl_add_u64 v[194:195], v[194:195], 0, s[20:21]
	s_mov_b32 m0, s26
	ds_read_b128 v[182:185], v173 offset:49152
	ds_read_b128 v[186:189], v173 offset:50176
	ds_read_b128 v[190:193], v173 offset:51200
	ds_read_b128 v[202:205], v173 offset:52224
	ds_read_b128 v[206:209], v173 offset:53248
	ds_read_b128 v[210:213], v173 offset:54272
	ds_read_b128 v[214:217], v173 offset:55296
	ds_read_b128 v[218:221], v173 offset:56320
	global_load_lds_dwordx4 v[194:195], off
	v_lshl_add_u64 v[194:195], v[196:197], 0, s[20:21]
	s_add_i32 m0, s26, 0x2000
	s_add_i32 s26, s74, s55
	global_load_lds_dwordx4 v[194:195], off
	v_lshl_add_u64 v[194:195], v[198:199], 0, s[20:21]
	s_mov_b32 m0, s26
	s_nop 0
	global_load_lds_dwordx4 v[194:195], off
	v_lshl_add_u64 v[194:195], v[222:223], 0, s[20:21]
	s_add_i32 m0, s26, 0x2000
	s_nop 0
	global_load_lds_dwordx4 v[194:195], off
	v_lshl_add_u64 v[194:195], v[224:225], 0, s[20:21]
	s_mov_b32 m0, s60
	s_nop 0
	global_load_lds_dwordx4 v[194:195], off
	v_lshl_add_u64 v[194:195], v[230:231], 0, s[20:21]
	s_mov_b32 m0, s61
	s_nop 0
	global_load_lds_dwordx4 v[194:195], off
	s_waitcnt vmcnt(8)
	s_waitcnt lgkmcnt(0)
	s_barrier
	s_setprio 1
	v_mfma_f32_16x16x32_bf16 v[64:67], v[132:135], v[182:185], v[64:67]
	v_mfma_f32_16x16x32_bf16 v[60:63], v[152:155], v[182:185], v[60:63]
	v_mfma_f32_16x16x32_bf16 v[48:51], v[132:135], v[190:193], v[48:51]
	v_mfma_f32_16x16x32_bf16 v[44:47], v[152:155], v[190:193], v[44:47]
	v_mfma_f32_16x16x32_bf16 v[32:35], v[132:135], v[206:209], v[32:35]
	v_mfma_f32_16x16x32_bf16 v[28:31], v[152:155], v[206:209], v[28:31]
	v_mfma_f32_16x16x32_bf16 v[16:19], v[132:135], v[214:217], v[16:19]
	v_mfma_f32_16x16x32_bf16 v[12:15], v[152:155], v[214:217], v[12:15]
	v_mfma_f32_16x16x32_bf16 v[64:67], v[148:151], v[186:189], v[64:67]
	v_mfma_f32_16x16x32_bf16 v[60:63], v[156:159], v[186:189], v[60:63]
	v_mfma_f32_16x16x32_bf16 v[48:51], v[148:151], v[202:205], v[48:51]
	v_mfma_f32_16x16x32_bf16 v[44:47], v[156:159], v[202:205], v[44:47]
	v_mfma_f32_16x16x32_bf16 v[32:35], v[148:151], v[210:213], v[32:35]
	v_mfma_f32_16x16x32_bf16 v[28:31], v[156:159], v[210:213], v[28:31]
	v_mfma_f32_16x16x32_bf16 v[16:19], v[148:151], v[218:221], v[16:19]
	v_mfma_f32_16x16x32_bf16 v[12:15], v[156:159], v[218:221], v[12:15]
	v_mfma_f32_16x16x32_bf16 v[56:59], v[160:163], v[182:185], v[56:59]
	v_mfma_f32_16x16x32_bf16 v[52:55], v[174:177], v[182:185], v[52:55]
	v_mfma_f32_16x16x32_bf16 v[40:43], v[160:163], v[190:193], v[40:43]
	v_mfma_f32_16x16x32_bf16 v[36:39], v[174:177], v[190:193], v[36:39]
	v_mfma_f32_16x16x32_bf16 v[24:27], v[160:163], v[206:209], v[24:27]
	v_mfma_f32_16x16x32_bf16 v[20:23], v[174:177], v[206:209], v[20:23]
	v_mfma_f32_16x16x32_bf16 v[8:11], v[160:163], v[214:217], v[8:11]
	v_mfma_f32_16x16x32_bf16 v[4:7], v[174:177], v[214:217], v[4:7]
	v_mfma_f32_16x16x32_bf16 v[56:59], v[164:167], v[186:189], v[56:59]
	v_mfma_f32_16x16x32_bf16 v[52:55], v[178:181], v[186:189], v[52:55]
	v_mfma_f32_16x16x32_bf16 v[40:43], v[164:167], v[202:205], v[40:43]
	v_mfma_f32_16x16x32_bf16 v[36:39], v[178:181], v[202:205], v[36:39]
	v_mfma_f32_16x16x32_bf16 v[24:27], v[164:167], v[210:213], v[24:27]
	v_mfma_f32_16x16x32_bf16 v[20:23], v[178:181], v[210:213], v[20:23]
	v_mfma_f32_16x16x32_bf16 v[8:11], v[164:167], v[218:221], v[8:11]
	v_mfma_f32_16x16x32_bf16 v[4:7], v[178:181], v[218:221], v[4:7]
	s_setprio 0
	s_barrier
	s_add_u32 s12, s12, 0x100
	s_addc_u32 s13, s13, 0
	s_add_u32 s11, s11, 0x100
	s_addc_u32 s71, s71, 0
	s_cmp_ge_i32 s72, s8
	s_mov_b32 s26, s72
	s_cbranch_scc0 .LBB0_1000
	s_branch .LBB0_1001
.LBB0_1000:
	s_add_i32 s72, s26, 2
	s_add_u32 s73, s12, 0x80
	s_addc_u32 s27, s13, 0
	s_add_i32 s76, 0, 0x10000
	s_cmp_eq_u32 s64, s26
	s_cselect_b32 s27, s7, s27
	s_cselect_b32 s26, s6, s73
	s_cselect_b32 s75, s41, s71
	s_cselect_b32 s74, s40, s11
	s_add_i32 s73, 0, 0x14000
	v_add_u32_e32 v156, s76, v171
	v_add_u32_e32 v178, s73, v171
	ds_read_b128 v[132:135], v156
	ds_read_b128 v[148:151], v156 offset:1024
	ds_read_b128 v[152:155], v156 offset:2048
	ds_read_b128 v[156:159], v156 offset:3072
	ds_read_b128 v[160:163], v178
	ds_read_b128 v[164:167], v178 offset:1024
	ds_read_b128 v[174:177], v178 offset:2048
	ds_read_b128 v[178:181], v178 offset:3072
	v_lshl_add_u64 v[194:195], s[12:13], 0, v[144:145]
	s_add_i32 m0, s56, 0xc000
	ds_read_b128 v[182:185], v173
	ds_read_b128 v[186:189], v173 offset:1024
	ds_read_b128 v[190:193], v173 offset:2048
	ds_read_b128 v[202:205], v173 offset:3072
	ds_read_b128 v[206:209], v173 offset:4096
	ds_read_b128 v[210:213], v173 offset:5120
	ds_read_b128 v[214:217], v173 offset:6144
	ds_read_b128 v[218:221], v173 offset:7168
	global_load_lds_dwordx4 v[194:195], off
	v_lshl_add_u64 v[194:195], s[12:13], 0, v[146:147]
	s_add_i32 m0, s56, 0xe000
	s_nop 0
	global_load_lds_dwordx4 v[194:195], off
	s_waitcnt vmcnt(8)
	s_waitcnt lgkmcnt(0)
	s_barrier
; #define PG8_GOFFS(slot_) do { _Pragma("unroll") for (int _i = 0; _i < 2; ++_i) { int R, C; stage_rc(tid * 16 + _i * 8192, R, C); _Pragma("unroll") for (int _h = 0; _h < 2; ++_h) { \
;         unsigned t_ = gtab[(slot_) * 256 + R + 128 * _h]; t_ = t_ < (unsigned)(T - 1) ? t_ : (unsigned)(T - 1); voffA[_h][_i] = (t_ * (unsigned)K + (unsigned)C) * 2u; } } } while (0)
; #define PG8_STAGE(bufoff, gbase, voff) do { _Pragma("unroll") for (int _i = 0; _i < 2; ++_i) \
;         __builtin_amdgcn_global_load_lds((const unsigned*)((const char*)(gbase) + (voff)[_i]), (LAS unsigned*)(lds + (bufoff) + ldsw + _i * 8192), 16, 0, 0); } while (0)
; #define PG8_LDA(dst, b, h) do { _Pragma("unroll") for (int m = 0; m < 4; ++m) _Pragma("unroll") for (int k = 0; k < 2; ++k) dst[m][k] = *(const LAS bf16x8*)(lds + PG8_SA(b, h) + aoff + m * 2048 + k * 1024); } while (0)
; #define PG8_MMA(ai, bj, At, Bt) do { __builtin_amdgcn_s_setprio(1); _Pragma("unroll") for (int m = 0; m < 4; ++m) _Pragma("unroll") for (int n = 0; n < 2; ++n) _Pragma("unroll") for (int k = 0; k < 2; ++k) \
;         acc[ai][bj][m][n] = __builtin_amdgcn_mfma_f32_16x16x32_bf16(Bt[n][k], At[m][k], acc[ai][bj][m][n], 0, 0, 0); __builtin_amdgcn_s_setprio(0); } while (0)
; #define PG8_WAIT_V(n) asm volatile("s_waitcnt vmcnt(" #n ")" ::: "memory")
; #define PG8_WAIT_L(n) asm volatile("s_waitcnt lgkmcnt(" #n ")" ::: "memory")
; #define PG8_BAR __builtin_amdgcn_s_barrier()
; #define PG8_SCHED __builtin_amdgcn_sched_barrier(0)
; template <class Epi, class Sched>
; __device__ __forceinline__ void gemm_phase(const int tid, LAS unsigned char* lds, const bf16* Aop, const bf16* Bop, const int K_, const Sched& S, const Epi& E, const bf16* Aop1 = nullptr, const bf16* Bop1 = nullptr) {
;     ...
;             PG8_WAIT_V(8); PG8_WAIT_L(0); PG8_BAR; PG8_MMA(0, 0, At, B0); PG8_MMA(0, 1, At, B1); PG8_BAR; PG8_SCHED;
;             PG8_LDA(At, 0, 1); PG8_STAGE(PG8_SB(0, 0), b2, voffB); PG8_STAGE(PG8_SB(0, 1), b2 + hstep, voffB); if (Epi::GATHER && last && has_next) PG8_GOFFS((ui + 1) & 1); PG8_STAGE(PG8_SA(0, 0), a2, voffA[0]);
;             PG8_WAIT_V(8); PG8_WAIT_L(0); PG8_BAR; PG8_MMA(1, 0, At, B0); PG8_MMA(1, 1, At, B1); PG8_BAR; PG8_SCHED;
	s_setprio 1
	v_mfma_f32_16x16x32_bf16 v[128:131], v[132:135], v[182:185], v[128:131]
	v_mfma_f32_16x16x32_bf16 v[124:127], v[152:155], v[182:185], v[124:127]
	v_mfma_f32_16x16x32_bf16 v[112:115], v[132:135], v[190:193], v[112:115]
	v_mfma_f32_16x16x32_bf16 v[108:111], v[152:155], v[190:193], v[108:111]
	v_mfma_f32_16x16x32_bf16 v[96:99], v[132:135], v[206:209], v[96:99]
	v_mfma_f32_16x16x32_bf16 v[92:95], v[152:155], v[206:209], v[92:95]
	v_mfma_f32_16x16x32_bf16 v[80:83], v[132:135], v[214:217], v[80:83]
	v_mfma_f32_16x16x32_bf16 v[76:79], v[152:155], v[214:217], v[76:79]
	v_mfma_f32_16x16x32_bf16 v[128:131], v[148:151], v[186:189], v[128:131]
	v_mfma_f32_16x16x32_bf16 v[124:127], v[156:159], v[186:189], v[124:127]
	v_mfma_f32_16x16x32_bf16 v[112:115], v[148:151], v[202:205], v[112:115]
	v_mfma_f32_16x16x32_bf16 v[108:111], v[156:159], v[202:205], v[108:111]
	v_mfma_f32_16x16x32_bf16 v[96:99], v[148:151], v[210:213], v[96:99]
	v_mfma_f32_16x16x32_bf16 v[92:95], v[156:159], v[210:213], v[92:95]
	v_mfma_f32_16x16x32_bf16 v[80:83], v[148:151], v[218:221], v[80:83]
	v_mfma_f32_16x16x32_bf16 v[76:79], v[156:159], v[218:221], v[76:79]
	v_mfma_f32_16x16x32_bf16 v[120:123], v[160:163], v[182:185], v[120:123]
	v_mfma_f32_16x16x32_bf16 v[116:119], v[174:177], v[182:185], v[116:119]
	v_mfma_f32_16x16x32_bf16 v[104:107], v[160:163], v[190:193], v[104:107]
	v_mfma_f32_16x16x32_bf16 v[100:103], v[174:177], v[190:193], v[100:103]
	v_mfma_f32_16x16x32_bf16 v[88:91], v[160:163], v[206:209], v[88:91]
	v_mfma_f32_16x16x32_bf16 v[84:87], v[174:177], v[206:209], v[84:87]
	v_mfma_f32_16x16x32_bf16 v[72:75], v[160:163], v[214:217], v[72:75]
	v_mfma_f32_16x16x32_bf16 v[68:71], v[174:177], v[214:217], v[68:71]
	v_mfma_f32_16x16x32_bf16 v[120:123], v[164:167], v[186:189], v[120:123]
	v_mfma_f32_16x16x32_bf16 v[116:119], v[178:181], v[186:189], v[116:119]
	v_mfma_f32_16x16x32_bf16 v[104:107], v[164:167], v[202:205], v[104:107]
	v_mfma_f32_16x16x32_bf16 v[100:103], v[178:181], v[202:205], v[100:103]
	v_mfma_f32_16x16x32_bf16 v[88:91], v[164:167], v[210:213], v[88:91]
	v_mfma_f32_16x16x32_bf16 v[84:87], v[178:181], v[210:213], v[84:87]
	v_mfma_f32_16x16x32_bf16 v[72:75], v[164:167], v[218:221], v[72:75]
	v_mfma_f32_16x16x32_bf16 v[68:71], v[178:181], v[218:221], v[68:71]
	s_setprio 0
	s_barrier
	s_add_i32 s76, s76, s55
	v_lshl_add_u64 v[194:195], s[74:75], 0, v[136:137]
	s_mov_b32 m0, s76
	ds_read_b128 v[182:185], v173 offset:16384
	ds_read_b128 v[186:189], v173 offset:17408
	ds_read_b128 v[190:193], v173 offset:18432
	ds_read_b128 v[202:205], v173 offset:19456
	ds_read_b128 v[206:209], v173 offset:20480
	ds_read_b128 v[210:213], v173 offset:21504
	ds_read_b128 v[214:217], v173 offset:22528
	ds_read_b128 v[218:221], v173 offset:23552
	global_load_lds_dwordx4 v[194:195], off
	s_add_i32 m0, s76, 0x2000
	v_lshl_add_u64 v[196:197], s[74:75], 0, v[140:141]
	s_add_u32 s74, s74, s18
	s_addc_u32 s75, s75, s19
	s_add_i32 s73, s73, s55
	global_load_lds_dwordx4 v[196:197], off
	v_lshl_add_u64 v[198:199], s[74:75], 0, v[136:137]
	s_mov_b32 m0, s73
	v_lshl_add_u64 v[222:223], s[74:75], 0, v[140:141]
	global_load_lds_dwordx4 v[198:199], off
	s_add_i32 m0, s73, 0x2000
	v_lshl_add_u64 v[224:225], s[26:27], 0, v[0:1]
	global_load_lds_dwordx4 v[222:223], off
	s_mov_b32 m0, s56
	v_lshl_add_u64 v[230:231], s[26:27], 0, v[138:139]
	global_load_lds_dwordx4 v[224:225], off
	s_mov_b32 m0, s57
	s_nop 0
	global_load_lds_dwordx4 v[230:231], off
	s_waitcnt vmcnt(8)
	s_waitcnt lgkmcnt(0)
	s_barrier
	s_setprio 1
	v_mfma_f32_16x16x32_bf16 v[64:67], v[132:135], v[182:185], v[64:67]
	v_mfma_f32_16x16x32_bf16 v[60:63], v[152:155], v[182:185], v[60:63]
	v_mfma_f32_16x16x32_bf16 v[48:51], v[132:135], v[190:193], v[48:51]
	v_mfma_f32_16x16x32_bf16 v[44:47], v[152:155], v[190:193], v[44:47]
	v_mfma_f32_16x16x32_bf16 v[32:35], v[132:135], v[206:209], v[32:35]
	v_mfma_f32_16x16x32_bf16 v[28:31], v[152:155], v[206:209], v[28:31]
	v_mfma_f32_16x16x32_bf16 v[16:19], v[132:135], v[214:217], v[16:19]
	v_mfma_f32_16x16x32_bf16 v[12:15], v[152:155], v[214:217], v[12:15]
	v_mfma_f32_16x16x32_bf16 v[64:67], v[148:151], v[186:189], v[64:67]
	v_mfma_f32_16x16x32_bf16 v[60:63], v[156:159], v[186:189], v[60:63]
	v_mfma_f32_16x16x32_bf16 v[48:51], v[148:151], v[202:205], v[48:51]
	v_mfma_f32_16x16x32_bf16 v[44:47], v[156:159], v[202:205], v[44:47]
	v_mfma_f32_16x16x32_bf16 v[32:35], v[148:151], v[210:213], v[32:35]
	v_mfma_f32_16x16x32_bf16 v[28:31], v[156:159], v[210:213], v[28:31]
	v_mfma_f32_16x16x32_bf16 v[16:19], v[148:151], v[218:221], v[16:19]
	v_mfma_f32_16x16x32_bf16 v[12:15], v[156:159], v[218:221], v[12:15]
	v_mfma_f32_16x16x32_bf16 v[56:59], v[160:163], v[182:185], v[56:59]
	v_mfma_f32_16x16x32_bf16 v[52:55], v[174:177], v[182:185], v[52:55]
	v_mfma_f32_16x16x32_bf16 v[40:43], v[160:163], v[190:193], v[40:43]
	v_mfma_f32_16x16x32_bf16 v[36:39], v[174:177], v[190:193], v[36:39]
	v_mfma_f32_16x16x32_bf16 v[24:27], v[160:163], v[206:209], v[24:27]
	v_mfma_f32_16x16x32_bf16 v[20:23], v[174:177], v[206:209], v[20:23]
	v_mfma_f32_16x16x32_bf16 v[8:11], v[160:163], v[214:217], v[8:11]
	v_mfma_f32_16x16x32_bf16 v[4:7], v[174:177], v[214:217], v[4:7]
	v_mfma_f32_16x16x32_bf16 v[56:59], v[164:167], v[186:189], v[56:59]
	v_mfma_f32_16x16x32_bf16 v[52:55], v[178:181], v[186:189], v[52:55]
	v_mfma_f32_16x16x32_bf16 v[40:43], v[164:167], v[202:205], v[40:43]
	v_mfma_f32_16x16x32_bf16 v[36:39], v[178:181], v[202:205], v[36:39]
	v_mfma_f32_16x16x32_bf16 v[24:27], v[164:167], v[210:213], v[24:27]
	v_mfma_f32_16x16x32_bf16 v[20:23], v[178:181], v[210:213], v[20:23]
	v_mfma_f32_16x16x32_bf16 v[8:11], v[164:167], v[218:221], v[8:11]
	v_mfma_f32_16x16x32_bf16 v[4:7], v[178:181], v[218:221], v[4:7]
	s_setprio 0
	s_barrier
; #define PG8_STAGE(bufoff, gbase, voff) do { _Pragma("unroll") for (int _i = 0; _i < 2; ++_i) \
;         __builtin_amdgcn_global_load_lds((const unsigned*)((const char*)(gbase) + (voff)[_i]), (LAS unsigned*)(lds + (bufoff) + ldsw + _i * 8192), 16, 0, 0); } while (0)
; #define PG8_STAGE_A1(bufoff, gbase) do { if (Epi::GATHER) PG8_STAGE(bufoff, gbase, voffA[1]); else PG8_STAGE(bufoff, (gbase) + hstep, voffA[0]); } while (0)
; #define PG8_LDA(dst, b, h) do { _Pragma("unroll") for (int m = 0; m < 4; ++m) _Pragma("unroll") for (int k = 0; k < 2; ++k) dst[m][k] = *(const LAS bf16x8*)(lds + PG8_SA(b, h) + aoff + m * 2048 + k * 1024); } while (0)
; #define PG8_LDB(dst, b, h) do { _Pragma("unroll") for (int n = 0; n < 2; ++n) _Pragma("unroll") for (int k = 0; k < 2; ++k) dst[n][k] = *(const LAS bf16x8*)(lds + PG8_SB(b, h) + boff + n * 2048 + k * 1024); } while (0)
; #define PG8_MMA(ai, bj, At, Bt) do { __builtin_amdgcn_s_setprio(1); _Pragma("unroll") for (int m = 0; m < 4; ++m) _Pragma("unroll") for (int n = 0; n < 2; ++n) _Pragma("unroll") for (int k = 0; k < 2; ++k) \
;         acc[ai][bj][m][n] = __builtin_amdgcn_mfma_f32_16x16x32_bf16(Bt[n][k], At[m][k], acc[ai][bj][m][n], 0, 0, 0); __builtin_amdgcn_s_setprio(0); } while (0)
; #define PG8_WAIT_V(n) asm volatile("s_waitcnt vmcnt(" #n ")" ::: "memory")
; #define PG8_WAIT_L(n) asm volatile("s_waitcnt lgkmcnt(" #n ")" ::: "memory")
; #define PG8_BAR __builtin_amdgcn_s_barrier()
; #define PG8_SCHED __builtin_amdgcn_sched_barrier(0)
; template <class Epi, class Sched>
; __device__ __forceinline__ void gemm_phase(const int tid, LAS unsigned char* lds, const bf16* Aop, const bf16* Bop, const int K_, const Sched& S, const Epi& E, const bf16* Aop1 = nullptr, const bf16* Bop1 = nullptr) {
;     ...
;             PG8_LDB(B0, 1, 0); PG8_LDB(B1, 1, 1); PG8_SCHED; PG8_LDA(At, 1, 0); PG8_STAGE_A1(PG8_SA(0, 1), a2);
;             PG8_WAIT_V(8); PG8_WAIT_L(0); PG8_BAR; PG8_MMA(0, 0, At, B0); PG8_MMA(0, 1, At, B1); PG8_BAR; PG8_SCHED;
;             PG8_LDA(At, 1, 1); PG8_STAGE(PG8_SB(1, 0), b3, voffB); PG8_STAGE(PG8_SB(1, 1), b3 + hstep, voffB); PG8_STAGE(PG8_SA(1, 0), a3, voffA[0]);
;             PG8_WAIT_V(8); PG8_WAIT_L(0); PG8_BAR; PG8_MMA(1, 0, At, B0); PG8_MMA(1, 1, At, B1); PG8_BAR; PG8_SCHED;
;         }
	s_add_i32 s73, 0, 0x18000
	s_add_i32 s74, 0, 0x1c000
	v_add_u32_e32 v156, s73, v171
	v_add_u32_e32 v178, s74, v171
	ds_read_b128 v[132:135], v156
	ds_read_b128 v[148:151], v156 offset:1024
	ds_read_b128 v[152:155], v156 offset:2048
	ds_read_b128 v[156:159], v156 offset:3072
	ds_read_b128 v[160:163], v178
	ds_read_b128 v[164:167], v178 offset:1024
	ds_read_b128 v[174:177], v178 offset:2048
	ds_read_b128 v[178:181], v178 offset:3072
	s_add_u32 s26, s26, s18
	s_addc_u32 s27, s27, s19
	s_mov_b32 m0, s58
	v_lshl_add_u64 v[232:233], s[26:27], 0, v[0:1]
	ds_read_b128 v[182:185], v173 offset:32768
	ds_read_b128 v[186:189], v173 offset:33792
	ds_read_b128 v[190:193], v173 offset:34816
	ds_read_b128 v[202:205], v173 offset:35840
	ds_read_b128 v[206:209], v173 offset:36864
	ds_read_b128 v[210:213], v173 offset:37888
	ds_read_b128 v[214:217], v173 offset:38912
	ds_read_b128 v[218:221], v173 offset:39936
	global_load_lds_dwordx4 v[232:233], off
	v_lshl_add_u64 v[232:233], s[26:27], 0, v[138:139]
	s_mov_b32 m0, s59
	s_nop 0
	global_load_lds_dwordx4 v[232:233], off
	s_waitcnt vmcnt(8)
	s_waitcnt lgkmcnt(0)
	s_barrier
	s_setprio 1
	v_mfma_f32_16x16x32_bf16 v[128:131], v[132:135], v[182:185], v[128:131]
	v_mfma_f32_16x16x32_bf16 v[124:127], v[152:155], v[182:185], v[124:127]
	v_mfma_f32_16x16x32_bf16 v[112:115], v[132:135], v[190:193], v[112:115]
	v_mfma_f32_16x16x32_bf16 v[108:111], v[152:155], v[190:193], v[108:111]
	v_mfma_f32_16x16x32_bf16 v[96:99], v[132:135], v[206:209], v[96:99]
	v_mfma_f32_16x16x32_bf16 v[92:95], v[152:155], v[206:209], v[92:95]
	v_mfma_f32_16x16x32_bf16 v[80:83], v[132:135], v[214:217], v[80:83]
	v_mfma_f32_16x16x32_bf16 v[76:79], v[152:155], v[214:217], v[76:79]
	v_mfma_f32_16x16x32_bf16 v[128:131], v[148:151], v[186:189], v[128:131]
	v_mfma_f32_16x16x32_bf16 v[124:127], v[156:159], v[186:189], v[124:127]
	v_mfma_f32_16x16x32_bf16 v[112:115], v[148:151], v[202:205], v[112:115]
	v_mfma_f32_16x16x32_bf16 v[108:111], v[156:159], v[202:205], v[108:111]
	v_mfma_f32_16x16x32_bf16 v[96:99], v[148:151], v[210:213], v[96:99]
	v_mfma_f32_16x16x32_bf16 v[92:95], v[156:159], v[210:213], v[92:95]
	v_mfma_f32_16x16x32_bf16 v[80:83], v[148:151], v[218:221], v[80:83]
	v_mfma_f32_16x16x32_bf16 v[76:79], v[156:159], v[218:221], v[76:79]
	v_mfma_f32_16x16x32_bf16 v[120:123], v[160:163], v[182:185], v[120:123]
	v_mfma_f32_16x16x32_bf16 v[116:119], v[174:177], v[182:185], v[116:119]
	v_mfma_f32_16x16x32_bf16 v[104:107], v[160:163], v[190:193], v[104:107]
	v_mfma_f32_16x16x32_bf16 v[100:103], v[174:177], v[190:193], v[100:103]
	v_mfma_f32_16x16x32_bf16 v[88:91], v[160:163], v[206:209], v[88:91]
	v_mfma_f32_16x16x32_bf16 v[84:87], v[174:177], v[206:209], v[84:87]
	v_mfma_f32_16x16x32_bf16 v[72:75], v[160:163], v[214:217], v[72:75]
	v_mfma_f32_16x16x32_bf16 v[68:71], v[174:177], v[214:217], v[68:71]
	v_mfma_f32_16x16x32_bf16 v[120:123], v[164:167], v[186:189], v[120:123]
	v_mfma_f32_16x16x32_bf16 v[116:119], v[178:181], v[186:189], v[116:119]
	v_mfma_f32_16x16x32_bf16 v[104:107], v[164:167], v[202:205], v[104:107]
	v_mfma_f32_16x16x32_bf16 v[100:103], v[178:181], v[202:205], v[100:103]
	v_mfma_f32_16x16x32_bf16 v[88:91], v[164:167], v[210:213], v[88:91]
	v_mfma_f32_16x16x32_bf16 v[84:87], v[178:181], v[210:213], v[84:87]
	v_mfma_f32_16x16x32_bf16 v[72:75], v[164:167], v[218:221], v[72:75]
	v_mfma_f32_16x16x32_bf16 v[68:71], v[178:181], v[218:221], v[68:71]
	s_setprio 0
	s_barrier
	s_add_i32 s26, s73, s55
	v_lshl_add_u64 v[194:195], v[194:195], 0, s[20:21]
	s_mov_b32 m0, s26
	ds_read_b128 v[182:185], v173 offset:49152
	ds_read_b128 v[186:189], v173 offset:50176
	ds_read_b128 v[190:193], v173 offset:51200
	ds_read_b128 v[202:205], v173 offset:52224
	ds_read_b128 v[206:209], v173 offset:53248
	ds_read_b128 v[210:213], v173 offset:54272
	ds_read_b128 v[214:217], v173 offset:55296
	ds_read_b128 v[218:221], v173 offset:56320
	global_load_lds_dwordx4 v[194:195], off
	v_lshl_add_u64 v[194:195], v[196:197], 0, s[20:21]
	s_add_i32 m0, s26, 0x2000
	s_add_i32 s26, s74, s55
	global_load_lds_dwordx4 v[194:195], off
	v_lshl_add_u64 v[194:195], v[198:199], 0, s[20:21]
	s_mov_b32 m0, s26
	s_nop 0
	global_load_lds_dwordx4 v[194:195], off
	v_lshl_add_u64 v[194:195], v[222:223], 0, s[20:21]
	s_add_i32 m0, s26, 0x2000
	s_nop 0
	global_load_lds_dwordx4 v[194:195], off
	v_lshl_add_u64 v[194:195], v[224:225], 0, s[20:21]
	s_mov_b32 m0, s60
	s_nop 0
	global_load_lds_dwordx4 v[194:195], off
	v_lshl_add_u64 v[194:195], v[230:231], 0, s[20:21]
	s_mov_b32 m0, s61
	s_nop 0
	global_load_lds_dwordx4 v[194:195], off
	s_waitcnt vmcnt(8)
	s_waitcnt lgkmcnt(0)
	s_barrier
	s_setprio 1
	v_mfma_f32_16x16x32_bf16 v[64:67], v[132:135], v[182:185], v[64:67]
	v_mfma_f32_16x16x32_bf16 v[60:63], v[152:155], v[182:185], v[60:63]
	v_mfma_f32_16x16x32_bf16 v[48:51], v[132:135], v[190:193], v[48:51]
	v_mfma_f32_16x16x32_bf16 v[44:47], v[152:155], v[190:193], v[44:47]
	v_mfma_f32_16x16x32_bf16 v[32:35], v[132:135], v[206:209], v[32:35]
	v_mfma_f32_16x16x32_bf16 v[28:31], v[152:155], v[206:209], v[28:31]
	v_mfma_f32_16x16x32_bf16 v[16:19], v[132:135], v[214:217], v[16:19]
	v_mfma_f32_16x16x32_bf16 v[12:15], v[152:155], v[214:217], v[12:15]
	v_mfma_f32_16x16x32_bf16 v[64:67], v[148:151], v[186:189], v[64:67]
	v_mfma_f32_16x16x32_bf16 v[60:63], v[156:159], v[186:189], v[60:63]
	v_mfma_f32_16x16x32_bf16 v[48:51], v[148:151], v[202:205], v[48:51]
	v_mfma_f32_16x16x32_bf16 v[44:47], v[156:159], v[202:205], v[44:47]
	v_mfma_f32_16x16x32_bf16 v[32:35], v[148:151], v[210:213], v[32:35]
	v_mfma_f32_16x16x32_bf16 v[28:31], v[156:159], v[210:213], v[28:31]
	v_mfma_f32_16x16x32_bf16 v[16:19], v[148:151], v[218:221], v[16:19]
	v_mfma_f32_16x16x32_bf16 v[12:15], v[156:159], v[218:221], v[12:15]
	v_mfma_f32_16x16x32_bf16 v[56:59], v[160:163], v[182:185], v[56:59]
	v_mfma_f32_16x16x32_bf16 v[52:55], v[174:177], v[182:185], v[52:55]
	v_mfma_f32_16x16x32_bf16 v[40:43], v[160:163], v[190:193], v[40:43]
	v_mfma_f32_16x16x32_bf16 v[36:39], v[174:177], v[190:193], v[36:39]
	v_mfma_f32_16x16x32_bf16 v[24:27], v[160:163], v[206:209], v[24:27]
	v_mfma_f32_16x16x32_bf16 v[20:23], v[174:177], v[206:209], v[20:23]
	v_mfma_f32_16x16x32_bf16 v[8:11], v[160:163], v[214:217], v[8:11]
	v_mfma_f32_16x16x32_bf16 v[4:7], v[174:177], v[214:217], v[4:7]
	v_mfma_f32_16x16x32_bf16 v[56:59], v[164:167], v[186:189], v[56:59]
	v_mfma_f32_16x16x32_bf16 v[52:55], v[178:181], v[186:189], v[52:55]
	v_mfma_f32_16x16x32_bf16 v[40:43], v[164:167], v[202:205], v[40:43]
	v_mfma_f32_16x16x32_bf16 v[36:39], v[178:181], v[202:205], v[36:39]
	v_mfma_f32_16x16x32_bf16 v[24:27], v[164:167], v[210:213], v[24:27]
	v_mfma_f32_16x16x32_bf16 v[20:23], v[178:181], v[210:213], v[20:23]
	v_mfma_f32_16x16x32_bf16 v[8:11], v[164:167], v[218:221], v[8:11]
	v_mfma_f32_16x16x32_bf16 v[4:7], v[178:181], v[218:221], v[4:7]
	s_setprio 0
	s_barrier
	s_add_u32 s12, s12, 0x100
	s_addc_u32 s13, s13, 0
	s_add_u32 s11, s11, 0x100
	s_addc_u32 s71, s71, 0
	s_cmp_ge_i32 s72, s8
	s_mov_b32 s26, s72
	s_cbranch_scc0 .LBB0_1000

; #define PG8_GOFFS(slot_) do { _Pragma("unroll") for (int _i = 0; _i < 2; ++_i) { int R, C; stage_rc(tid * 16 + _i * 8192, R, C); _Pragma("unroll") for (int _h = 0; _h < 2; ++_h) { \
;         unsigned t_ = gtab[(slot_) * 256 + R + 128 * _h]; t_ = t_ < (unsigned)(T - 1) ? t_ : (unsigned)(T - 1); voffA[_h][_i] = (t_ * (unsigned)K + (unsigned)C) * 2u; } } } while (0)
; #define PG8_STAGE(bufoff, gbase, voff) do { _Pragma("unroll") for (int _i = 0; _i < 2; ++_i) \
;         __builtin_amdgcn_global_load_lds((const unsigned*)((const char*)(gbase) + (voff)[_i]), (LAS unsigned*)(lds + (bufoff) + ldsw + _i * 8192), 16, 0, 0); } while (0)
; #define PG8_STAGE_A1(bufoff, gbase) do { if (Epi::GATHER) PG8_STAGE(bufoff, gbase, voffA[1]); else PG8_STAGE(bufoff, (gbase) + hstep, voffA[0]); } while (0)
; #define PG8_LDA(dst, b, h) do { _Pragma("unroll") for (int m = 0; m < 4; ++m) _Pragma("unroll") for (int k = 0; k < 2; ++k) dst[m][k] = *(const LAS bf16x8*)(lds + PG8_SA(b, h) + aoff + m * 2048 + k * 1024); } while (0)
; template <class Epi, class Sched>
; __device__ __forceinline__ void gemm_phase(const int tid, LAS unsigned char* lds, const bf16* Aop, const bf16* Bop, const int K_, const Sched& S, const Epi& E, const bf16* Aop1 = nullptr, const bf16* Bop1 = nullptr) {
;     ...
;     f32x4 acc[2][2][4][2];
; #pragma unroll
;     for (int a = 0; a < 2; ++a)
; #pragma unroll
;         for (int b = 0; b < 2; ++b)
; #pragma unroll
;             for (int m = 0; m < 4; ++m)
; #pragma unroll
;                 for (int n = 0; n < 2; ++n) acc[a][b][m][n] = (f32x4){0.f, 0.f, 0.f, 0.f};
;     ...
;         for (int t = 0; t < nt; t += 2) {
;             const bool last = (t == nt - 2);
;             const char* a1 = cA + (size_t)(t + 1) * kstep;
;             const char* a2 = last ? nA : cA + (size_t)(t + 2) * kstep; const char* b2 = last ? nB : cB + (size_t)(t + 2) * kstep;
;             const char* a3 = a2 + kstep; const char* b3 = b2 + kstep;
;             PG8_LDB(B0, 0, 0); PG8_LDB(B1, 0, 1); PG8_SCHED; PG8_LDA(At, 0, 0); PG8_STAGE_A1(PG8_SA(1, 1), a1);
;             PG8_WAIT_V(8); PG8_WAIT_L(0); PG8_BAR; PG8_MMA(0, 0, At, B0); PG8_MMA(0, 1, At, B1); PG8_BAR; PG8_SCHED;
;             PG8_LDA(At, 0, 1); PG8_STAGE(PG8_SB(0, 0), b2, voffB); PG8_STAGE(PG8_SB(0, 1), b2 + hstep, voffB); if (Epi::GATHER && last && has_next) PG8_GOFFS((ui + 1) & 1); PG8_STAGE(PG8_SA(0, 0), a2, voffA[0]);
.LBB0_1092:
	v_mov_b32_e32 v127, 0
	s_andn2_b64 vcc, exec, s[14:15]
	s_cbranch_vccnz .LBB0_1095
	s_add_u32 s34, s34, 0x80
	s_addc_u32 s35, s35, 0
	s_add_u32 s40, s36, 0x100
	s_addc_u32 s41, s37, 0
	s_mov_b32 s36, 0
	s_add_i32 s60, s36, 2
	s_add_u32 s61, s34, 0x80
	s_addc_u32 s37, s35, 0
	s_add_i32 s66, 0, 0x10000
	s_cmp_eq_u32 s56, s36
	s_cselect_b32 s37, s19, s37
	s_cselect_b32 s36, s18, s61
	v_add_u32_e32 v144, s66, v149
	s_cselect_b32 s65, s27, s41
	s_cselect_b32 s64, s26, s40
	s_add_i32 s61, 0, 0x14000
	ds_read_b128 v[152:155], v144
	ds_read_b128 v[156:159], v144 offset:1024
	ds_read_b128 v[160:163], v144 offset:2048
	ds_read_b128 v[164:167], v144 offset:3072
	v_add_u32_e32 v144, s61, v149
	ds_read_b128 v[168:171], v144
	ds_read_b128 v[172:175], v144 offset:1024
	ds_read_b128 v[176:179], v144 offset:2048
	ds_read_b128 v[180:183], v144 offset:3072
	v_lshl_add_u64 v[144:145], s[34:35], 0, v[140:141]
	s_add_i32 m0, s50, 0xc000
	ds_read_b128 v[184:187], v151
	ds_read_b128 v[188:191], v151 offset:1024
	ds_read_b128 v[192:195], v151 offset:2048
	ds_read_b128 v[202:205], v151 offset:3072
	ds_read_b128 v[206:209], v151 offset:4096
	ds_read_b128 v[210:213], v151 offset:5120
	ds_read_b128 v[214:217], v151 offset:6144
	ds_read_b128 v[218:221], v151 offset:7168
	global_load_lds_dwordx4 v[144:145], off
	v_lshl_add_u64 v[144:145], s[34:35], 0, v[142:143]
	s_add_i32 m0, s50, 0xe000
	s_nop 0
	global_load_lds_dwordx4 v[144:145], off
	s_waitcnt vmcnt(8)
	s_waitcnt lgkmcnt(0)
	s_barrier
	s_setprio 1
	v_mfma_f32_16x16x32_bf16 v[124:127], v[152:155], v[184:187], 0
	v_mfma_f32_16x16x32_bf16 v[128:131], v[160:163], v[184:187], 0
	v_mfma_f32_16x16x32_bf16 v[112:115], v[152:155], v[192:195], 0
	v_mfma_f32_16x16x32_bf16 v[108:111], v[160:163], v[192:195], 0
	v_mfma_f32_16x16x32_bf16 v[96:99], v[152:155], v[206:209], 0
	v_mfma_f32_16x16x32_bf16 v[92:95], v[160:163], v[206:209], 0
	v_mfma_f32_16x16x32_bf16 v[80:83], v[152:155], v[214:217], 0
	v_mfma_f32_16x16x32_bf16 v[76:79], v[160:163], v[214:217], 0
	v_mfma_f32_16x16x32_bf16 v[124:127], v[156:159], v[188:191], v[124:127]
	v_mfma_f32_16x16x32_bf16 v[128:131], v[164:167], v[188:191], v[128:131]
	v_mfma_f32_16x16x32_bf16 v[112:115], v[156:159], v[202:205], v[112:115]
	v_mfma_f32_16x16x32_bf16 v[108:111], v[164:167], v[202:205], v[108:111]
	v_mfma_f32_16x16x32_bf16 v[96:99], v[156:159], v[210:213], v[96:99]
	v_mfma_f32_16x16x32_bf16 v[92:95], v[164:167], v[210:213], v[92:95]
	v_mfma_f32_16x16x32_bf16 v[80:83], v[156:159], v[218:221], v[80:83]
	v_mfma_f32_16x16x32_bf16 v[76:79], v[164:167], v[218:221], v[76:79]
	v_mfma_f32_16x16x32_bf16 v[120:123], v[168:171], v[184:187], 0
	v_mfma_f32_16x16x32_bf16 v[116:119], v[176:179], v[184:187], 0
	v_mfma_f32_16x16x32_bf16 v[104:107], v[168:171], v[192:195], 0
	v_mfma_f32_16x16x32_bf16 v[100:103], v[176:179], v[192:195], 0
	v_mfma_f32_16x16x32_bf16 v[88:91], v[168:171], v[206:209], 0
	v_mfma_f32_16x16x32_bf16 v[84:87], v[176:179], v[206:209], 0
	v_mfma_f32_16x16x32_bf16 v[72:75], v[168:171], v[214:217], 0
	v_mfma_f32_16x16x32_bf16 v[68:71], v[176:179], v[214:217], 0
	v_mfma_f32_16x16x32_bf16 v[120:123], v[172:175], v[188:191], v[120:123]
	v_mfma_f32_16x16x32_bf16 v[116:119], v[180:183], v[188:191], v[116:119]
	v_mfma_f32_16x16x32_bf16 v[104:107], v[172:175], v[202:205], v[104:107]
	v_mfma_f32_16x16x32_bf16 v[100:103], v[180:183], v[202:205], v[100:103]
	v_mfma_f32_16x16x32_bf16 v[88:91], v[172:175], v[210:213], v[88:91]
	v_mfma_f32_16x16x32_bf16 v[84:87], v[180:183], v[210:213], v[84:87]
	v_mfma_f32_16x16x32_bf16 v[72:75], v[172:175], v[218:221], v[72:75]
	v_mfma_f32_16x16x32_bf16 v[68:71], v[180:183], v[218:221], v[68:71]
	s_setprio 0
	s_barrier
	s_add_i32 s66, s66, s49
	v_lshl_add_u64 v[144:145], s[64:65], 0, v[132:133]
	s_mov_b32 m0, s66
	ds_read_b128 v[184:187], v151 offset:16384
	ds_read_b128 v[188:191], v151 offset:17408
	ds_read_b128 v[192:195], v151 offset:18432
	ds_read_b128 v[202:205], v151 offset:19456
	ds_read_b128 v[206:209], v151 offset:20480
	ds_read_b128 v[210:213], v151 offset:21504
	ds_read_b128 v[214:217], v151 offset:22528
	ds_read_b128 v[218:221], v151 offset:23552
	global_load_lds_dwordx4 v[144:145], off
	s_add_i32 m0, s66, 0x2000
	v_lshl_add_u64 v[196:197], s[64:65], 0, v[136:137]
	s_add_u32 s64, s64, s6
	s_addc_u32 s65, s65, s7
	s_add_i32 s61, s61, s49
	global_load_lds_dwordx4 v[196:197], off
	v_lshl_add_u64 v[198:199], s[64:65], 0, v[132:133]
	s_mov_b32 m0, s61
	v_lshl_add_u64 v[222:223], s[64:65], 0, v[136:137]
	global_load_lds_dwordx4 v[198:199], off
	s_add_i32 m0, s61, 0x2000
	v_lshl_add_u64 v[224:225], s[36:37], 0, v[0:1]
	global_load_lds_dwordx4 v[222:223], off
	s_mov_b32 m0, s50
	v_lshl_add_u64 v[230:231], s[36:37], 0, v[134:135]
	global_load_lds_dwordx4 v[224:225], off
	s_mov_b32 m0, s51
	s_nop 0
	global_load_lds_dwordx4 v[230:231], off
	s_waitcnt vmcnt(8)
	s_waitcnt lgkmcnt(0)
	s_barrier
; #define PG8_STAGE_A1(bufoff, gbase) do { if (Epi::GATHER) PG8_STAGE(bufoff, gbase, voffA[1]); else PG8_STAGE(bufoff, (gbase) + hstep, voffA[0]); } while (0)
; #define PG8_LDA(dst, b, h) do { _Pragma("unroll") for (int m = 0; m < 4; ++m) _Pragma("unroll") for (int k = 0; k < 2; ++k) dst[m][k] = *(const LAS bf16x8*)(lds + PG8_SA(b, h) + aoff + m * 2048 + k * 1024); } while (0)
; #define PG8_LDB(dst, b, h) do { _Pragma("unroll") for (int n = 0; n < 2; ++n) _Pragma("unroll") for (int k = 0; k < 2; ++k) dst[n][k] = *(const LAS bf16x8*)(lds + PG8_SB(b, h) + boff + n * 2048 + k * 1024); } while (0)
; #define PG8_MMA(ai, bj, At, Bt) do { __builtin_amdgcn_s_setprio(1); _Pragma("unroll") for (int m = 0; m < 4; ++m) _Pragma("unroll") for (int n = 0; n < 2; ++n) _Pragma("unroll") for (int k = 0; k < 2; ++k) \
;         acc[ai][bj][m][n] = __builtin_amdgcn_mfma_f32_16x16x32_bf16(Bt[n][k], At[m][k], acc[ai][bj][m][n], 0, 0, 0); __builtin_amdgcn_s_setprio(0); } while (0)
; #define PG8_WAIT_V(n) asm volatile("s_waitcnt vmcnt(" #n ")" ::: "memory")
; #define PG8_WAIT_L(n) asm volatile("s_waitcnt lgkmcnt(" #n ")" ::: "memory")
; #define PG8_BAR __builtin_amdgcn_s_barrier()
; #define PG8_SCHED __builtin_amdgcn_sched_barrier(0)
; template <class Epi, class Sched>
; __device__ __forceinline__ void gemm_phase(const int tid, LAS unsigned char* lds, const bf16* Aop, const bf16* Bop, const int K_, const Sched& S, const Epi& E, const bf16* Aop1 = nullptr, const bf16* Bop1 = nullptr) {
;     ...
;             PG8_WAIT_V(8); PG8_WAIT_L(0); PG8_BAR; PG8_MMA(1, 0, At, B0); PG8_MMA(1, 1, At, B1); PG8_BAR; PG8_SCHED;
;             PG8_LDB(B0, 1, 0); PG8_LDB(B1, 1, 1); PG8_SCHED; PG8_LDA(At, 1, 0); PG8_STAGE_A1(PG8_SA(0, 1), a2);
;             PG8_WAIT_V(8); PG8_WAIT_L(0); PG8_BAR; PG8_MMA(0, 0, At, B0); PG8_MMA(0, 1, At, B1); PG8_BAR; PG8_SCHED;
	s_setprio 1
	v_mfma_f32_16x16x32_bf16 v[64:67], v[152:155], v[184:187], 0
	v_mfma_f32_16x16x32_bf16 v[60:63], v[160:163], v[184:187], 0
	v_mfma_f32_16x16x32_bf16 v[48:51], v[152:155], v[192:195], 0
	v_mfma_f32_16x16x32_bf16 v[44:47], v[160:163], v[192:195], 0
	v_mfma_f32_16x16x32_bf16 v[32:35], v[152:155], v[206:209], 0
	v_mfma_f32_16x16x32_bf16 v[28:31], v[160:163], v[206:209], 0
	v_mfma_f32_16x16x32_bf16 v[16:19], v[152:155], v[214:217], 0
	v_mfma_f32_16x16x32_bf16 v[12:15], v[160:163], v[214:217], 0
	v_mfma_f32_16x16x32_bf16 v[64:67], v[156:159], v[188:191], v[64:67]
	v_mfma_f32_16x16x32_bf16 v[60:63], v[164:167], v[188:191], v[60:63]
	v_mfma_f32_16x16x32_bf16 v[48:51], v[156:159], v[202:205], v[48:51]
	v_mfma_f32_16x16x32_bf16 v[44:47], v[164:167], v[202:205], v[44:47]
	v_mfma_f32_16x16x32_bf16 v[32:35], v[156:159], v[210:213], v[32:35]
	v_mfma_f32_16x16x32_bf16 v[28:31], v[164:167], v[210:213], v[28:31]
	v_mfma_f32_16x16x32_bf16 v[16:19], v[156:159], v[218:221], v[16:19]
	v_mfma_f32_16x16x32_bf16 v[12:15], v[164:167], v[218:221], v[12:15]
	v_mfma_f32_16x16x32_bf16 v[56:59], v[168:171], v[184:187], 0
	v_mfma_f32_16x16x32_bf16 v[52:55], v[176:179], v[184:187], 0
	v_mfma_f32_16x16x32_bf16 v[40:43], v[168:171], v[192:195], 0
	v_mfma_f32_16x16x32_bf16 v[36:39], v[176:179], v[192:195], 0
	v_mfma_f32_16x16x32_bf16 v[24:27], v[168:171], v[206:209], 0
	v_mfma_f32_16x16x32_bf16 v[20:23], v[176:179], v[206:209], 0
	v_mfma_f32_16x16x32_bf16 v[8:11], v[168:171], v[214:217], 0
	v_mfma_f32_16x16x32_bf16 v[4:7], v[176:179], v[214:217], 0
	v_mfma_f32_16x16x32_bf16 v[56:59], v[172:175], v[188:191], v[56:59]
	v_mfma_f32_16x16x32_bf16 v[52:55], v[180:183], v[188:191], v[52:55]
	v_mfma_f32_16x16x32_bf16 v[40:43], v[172:175], v[202:205], v[40:43]
	v_mfma_f32_16x16x32_bf16 v[36:39], v[180:183], v[202:205], v[36:39]
	v_mfma_f32_16x16x32_bf16 v[24:27], v[172:175], v[210:213], v[24:27]
	v_mfma_f32_16x16x32_bf16 v[20:23], v[180:183], v[210:213], v[20:23]
	v_mfma_f32_16x16x32_bf16 v[8:11], v[172:175], v[218:221], v[8:11]
	v_mfma_f32_16x16x32_bf16 v[4:7], v[180:183], v[218:221], v[4:7]
	s_setprio 0
	s_barrier
	s_add_i32 s61, 0, 0x18000
	s_add_i32 s64, 0, 0x1c000
	v_add_u32_e32 v164, s61, v149
	v_add_u32_e32 v180, s64, v149
	ds_read_b128 v[152:155], v164
	ds_read_b128 v[156:159], v164 offset:1024
	ds_read_b128 v[160:163], v164 offset:2048
	ds_read_b128 v[164:167], v164 offset:3072
	ds_read_b128 v[168:171], v180
	ds_read_b128 v[172:175], v180 offset:1024
	ds_read_b128 v[176:179], v180 offset:2048
	ds_read_b128 v[180:183], v180 offset:3072
	s_add_u32 s36, s36, s6
	s_addc_u32 s37, s37, s7
	s_mov_b32 m0, s52
	v_lshl_add_u64 v[232:233], s[36:37], 0, v[0:1]
	ds_read_b128 v[184:187], v151 offset:32768
	ds_read_b128 v[188:191], v151 offset:33792
	ds_read_b128 v[192:195], v151 offset:34816
	ds_read_b128 v[202:205], v151 offset:35840
	ds_read_b128 v[206:209], v151 offset:36864
	ds_read_b128 v[210:213], v151 offset:37888
	ds_read_b128 v[214:217], v151 offset:38912
	ds_read_b128 v[218:221], v151 offset:39936
	global_load_lds_dwordx4 v[232:233], off
	v_lshl_add_u64 v[232:233], s[36:37], 0, v[134:135]
	s_mov_b32 m0, s53
	s_nop 0
	global_load_lds_dwordx4 v[232:233], off
	s_waitcnt vmcnt(8)
	s_waitcnt lgkmcnt(0)
	s_barrier
	s_setprio 1
	v_mfma_f32_16x16x32_bf16 v[124:127], v[152:155], v[184:187], v[124:127]
	v_mfma_f32_16x16x32_bf16 v[128:131], v[160:163], v[184:187], v[128:131]
	v_mfma_f32_16x16x32_bf16 v[112:115], v[152:155], v[192:195], v[112:115]
	v_mfma_f32_16x16x32_bf16 v[108:111], v[160:163], v[192:195], v[108:111]
	v_mfma_f32_16x16x32_bf16 v[96:99], v[152:155], v[206:209], v[96:99]
	v_mfma_f32_16x16x32_bf16 v[92:95], v[160:163], v[206:209], v[92:95]
	v_mfma_f32_16x16x32_bf16 v[80:83], v[152:155], v[214:217], v[80:83]
	v_mfma_f32_16x16x32_bf16 v[76:79], v[160:163], v[214:217], v[76:79]
	v_mfma_f32_16x16x32_bf16 v[124:127], v[156:159], v[188:191], v[124:127]
	v_mfma_f32_16x16x32_bf16 v[128:131], v[164:167], v[188:191], v[128:131]
	v_mfma_f32_16x16x32_bf16 v[112:115], v[156:159], v[202:205], v[112:115]
	v_mfma_f32_16x16x32_bf16 v[108:111], v[164:167], v[202:205], v[108:111]
	v_mfma_f32_16x16x32_bf16 v[96:99], v[156:159], v[210:213], v[96:99]
	v_mfma_f32_16x16x32_bf16 v[92:95], v[164:167], v[210:213], v[92:95]
	v_mfma_f32_16x16x32_bf16 v[80:83], v[156:159], v[218:221], v[80:83]
	v_mfma_f32_16x16x32_bf16 v[76:79], v[164:167], v[218:221], v[76:79]
	v_mfma_f32_16x16x32_bf16 v[120:123], v[168:171], v[184:187], v[120:123]
	v_mfma_f32_16x16x32_bf16 v[116:119], v[176:179], v[184:187], v[116:119]
	v_mfma_f32_16x16x32_bf16 v[104:107], v[168:171], v[192:195], v[104:107]
	v_mfma_f32_16x16x32_bf16 v[100:103], v[176:179], v[192:195], v[100:103]
	v_mfma_f32_16x16x32_bf16 v[88:91], v[168:171], v[206:209], v[88:91]
	v_mfma_f32_16x16x32_bf16 v[84:87], v[176:179], v[206:209], v[84:87]
	v_mfma_f32_16x16x32_bf16 v[72:75], v[168:171], v[214:217], v[72:75]
	v_mfma_f32_16x16x32_bf16 v[68:71], v[176:179], v[214:217], v[68:71]
	v_mfma_f32_16x16x32_bf16 v[120:123], v[172:175], v[188:191], v[120:123]
	v_mfma_f32_16x16x32_bf16 v[116:119], v[180:183], v[188:191], v[116:119]
	v_mfma_f32_16x16x32_bf16 v[104:107], v[172:175], v[202:205], v[104:107]
	v_mfma_f32_16x16x32_bf16 v[100:103], v[180:183], v[202:205], v[100:103]
	v_mfma_f32_16x16x32_bf16 v[88:91], v[172:175], v[210:213], v[88:91]
	v_mfma_f32_16x16x32_bf16 v[84:87], v[180:183], v[210:213], v[84:87]
	v_mfma_f32_16x16x32_bf16 v[72:75], v[172:175], v[218:221], v[72:75]
	v_mfma_f32_16x16x32_bf16 v[68:71], v[180:183], v[218:221], v[68:71]
	s_setprio 0
	s_barrier
; #define PG8_GOFFS(slot_) do { _Pragma("unroll") for (int _i = 0; _i < 2; ++_i) { int R, C; stage_rc(tid * 16 + _i * 8192, R, C); _Pragma("unroll") for (int _h = 0; _h < 2; ++_h) { \
;         unsigned t_ = gtab[(slot_) * 256 + R + 128 * _h]; t_ = t_ < (unsigned)(T - 1) ? t_ : (unsigned)(T - 1); voffA[_h][_i] = (t_ * (unsigned)K + (unsigned)C) * 2u; } } } while (0)
; #define PG8_STAGE(bufoff, gbase, voff) do { _Pragma("unroll") for (int _i = 0; _i < 2; ++_i) \
;         __builtin_amdgcn_global_load_lds((const unsigned*)((const char*)(gbase) + (voff)[_i]), (LAS unsigned*)(lds + (bufoff) + ldsw + _i * 8192), 16, 0, 0); } while (0)
; #define PG8_BAR __builtin_amdgcn_s_barrier()
; template <class Epi, class Sched>
; __device__ __forceinline__ void gemm_phase(const int tid, LAS unsigned char* lds, const bf16* Aop, const bf16* Bop, const int K_, const Sched& S, const Epi& E, const bf16* Aop1 = nullptr, const bf16* Bop1 = nullptr) {
;     ...
;         for (int t = 0; t < nt; t += 2) {
;             const bool last = (t == nt - 2);
;             const char* a1 = cA + (size_t)(t + 1) * kstep;
;             const char* a2 = last ? nA : cA + (size_t)(t + 2) * kstep; const char* b2 = last ? nB : cB + (size_t)(t + 2) * kstep;
;             const char* a3 = a2 + kstep; const char* b3 = b2 + kstep;
;             PG8_LDB(B0, 0, 0); PG8_LDB(B1, 0, 1); PG8_SCHED; PG8_LDA(At, 0, 0); PG8_STAGE_A1(PG8_SA(1, 1), a1);
;             PG8_WAIT_V(8); PG8_WAIT_L(0); PG8_BAR; PG8_MMA(0, 0, At, B0); PG8_MMA(0, 1, At, B1); PG8_BAR; PG8_SCHED;
;             PG8_LDA(At, 0, 1); PG8_STAGE(PG8_SB(0, 0), b2, voffB); PG8_STAGE(PG8_SB(0, 1), b2 + hstep, voffB); if (Epi::GATHER && last && has_next) PG8_GOFFS((ui + 1) & 1); PG8_STAGE(PG8_SA(0, 0), a2, voffA[0]);
;             PG8_WAIT_V(8); PG8_WAIT_L(0); PG8_BAR; PG8_MMA(1, 0, At, B0); PG8_MMA(1, 1, At, B1); PG8_BAR; PG8_SCHED;
;             PG8_LDB(B0, 1, 0); PG8_LDB(B1, 1, 1); PG8_SCHED; PG8_LDA(At, 1, 0); PG8_STAGE_A1(PG8_SA(0, 1), a2);
;             PG8_WAIT_V(8); PG8_WAIT_L(0); PG8_BAR; PG8_MMA(0, 0, At, B0); PG8_MMA(0, 1, At, B1); PG8_BAR; PG8_SCHED;
;             PG8_LDA(At, 1, 1); PG8_STAGE(PG8_SB(1, 0), b3, voffB); PG8_STAGE(PG8_SB(1, 1), b3 + hstep, voffB); PG8_STAGE(PG8_SA(1, 0), a3, voffA[0]);
;             PG8_WAIT_V(8); PG8_WAIT_L(0); PG8_BAR; PG8_MMA(1, 0, At, B0); PG8_MMA(1, 1, At, B1); PG8_BAR; PG8_SCHED;
;         }
	s_add_i32 s36, s61, s49
	v_lshl_add_u64 v[144:145], v[144:145], 0, s[20:21]
	s_mov_b32 m0, s36
	ds_read_b128 v[184:187], v151 offset:49152
	ds_read_b128 v[188:191], v151 offset:50176
	ds_read_b128 v[192:195], v151 offset:51200
	ds_read_b128 v[202:205], v151 offset:52224
	ds_read_b128 v[206:209], v151 offset:53248
	ds_read_b128 v[210:213], v151 offset:54272
	ds_read_b128 v[214:217], v151 offset:55296
	ds_read_b128 v[218:221], v151 offset:56320
	global_load_lds_dwordx4 v[144:145], off
	v_lshl_add_u64 v[144:145], v[196:197], 0, s[20:21]
	s_add_i32 m0, s36, 0x2000
	s_add_i32 s36, s64, s49
	global_load_lds_dwordx4 v[144:145], off
	v_lshl_add_u64 v[144:145], v[198:199], 0, s[20:21]
	s_mov_b32 m0, s36
	s_nop 0
	global_load_lds_dwordx4 v[144:145], off
	v_lshl_add_u64 v[144:145], v[222:223], 0, s[20:21]
	s_add_i32 m0, s36, 0x2000
	s_nop 0
	global_load_lds_dwordx4 v[144:145], off
	v_lshl_add_u64 v[144:145], v[224:225], 0, s[20:21]
	s_mov_b32 m0, s54
	s_nop 0
	global_load_lds_dwordx4 v[144:145], off
	v_lshl_add_u64 v[144:145], v[230:231], 0, s[20:21]
	s_mov_b32 m0, s55
	s_nop 0
	global_load_lds_dwordx4 v[144:145], off
	s_waitcnt vmcnt(8)
	s_waitcnt lgkmcnt(0)
	s_barrier
	s_setprio 1
	v_mfma_f32_16x16x32_bf16 v[64:67], v[152:155], v[184:187], v[64:67]
	v_mfma_f32_16x16x32_bf16 v[60:63], v[160:163], v[184:187], v[60:63]
	v_mfma_f32_16x16x32_bf16 v[48:51], v[152:155], v[192:195], v[48:51]
	v_mfma_f32_16x16x32_bf16 v[44:47], v[160:163], v[192:195], v[44:47]
	v_mfma_f32_16x16x32_bf16 v[32:35], v[152:155], v[206:209], v[32:35]
	v_mfma_f32_16x16x32_bf16 v[28:31], v[160:163], v[206:209], v[28:31]
	v_mfma_f32_16x16x32_bf16 v[16:19], v[152:155], v[214:217], v[16:19]
	v_mfma_f32_16x16x32_bf16 v[12:15], v[160:163], v[214:217], v[12:15]
	v_mfma_f32_16x16x32_bf16 v[64:67], v[156:159], v[188:191], v[64:67]
	v_mfma_f32_16x16x32_bf16 v[60:63], v[164:167], v[188:191], v[60:63]
	v_mfma_f32_16x16x32_bf16 v[48:51], v[156:159], v[202:205], v[48:51]
	v_mfma_f32_16x16x32_bf16 v[44:47], v[164:167], v[202:205], v[44:47]
	v_mfma_f32_16x16x32_bf16 v[32:35], v[156:159], v[210:213], v[32:35]
	v_mfma_f32_16x16x32_bf16 v[28:31], v[164:167], v[210:213], v[28:31]
	v_mfma_f32_16x16x32_bf16 v[16:19], v[156:159], v[218:221], v[16:19]
	v_mfma_f32_16x16x32_bf16 v[12:15], v[164:167], v[218:221], v[12:15]
	v_mfma_f32_16x16x32_bf16 v[56:59], v[168:171], v[184:187], v[56:59]
	v_mfma_f32_16x16x32_bf16 v[52:55], v[176:179], v[184:187], v[52:55]
	v_mfma_f32_16x16x32_bf16 v[40:43], v[168:171], v[192:195], v[40:43]
	v_mfma_f32_16x16x32_bf16 v[36:39], v[176:179], v[192:195], v[36:39]
	v_mfma_f32_16x16x32_bf16 v[24:27], v[168:171], v[206:209], v[24:27]
	v_mfma_f32_16x16x32_bf16 v[20:23], v[176:179], v[206:209], v[20:23]
	v_mfma_f32_16x16x32_bf16 v[8:11], v[168:171], v[214:217], v[8:11]
	v_mfma_f32_16x16x32_bf16 v[4:7], v[176:179], v[214:217], v[4:7]
	v_mfma_f32_16x16x32_bf16 v[56:59], v[172:175], v[188:191], v[56:59]
	v_mfma_f32_16x16x32_bf16 v[52:55], v[180:183], v[188:191], v[52:55]
	v_mfma_f32_16x16x32_bf16 v[40:43], v[172:175], v[202:205], v[40:43]
	v_mfma_f32_16x16x32_bf16 v[36:39], v[180:183], v[202:205], v[36:39]
	v_mfma_f32_16x16x32_bf16 v[24:27], v[172:175], v[210:213], v[24:27]
	v_mfma_f32_16x16x32_bf16 v[20:23], v[180:183], v[210:213], v[20:23]
	v_mfma_f32_16x16x32_bf16 v[8:11], v[172:175], v[218:221], v[8:11]
	v_mfma_f32_16x16x32_bf16 v[4:7], v[180:183], v[218:221], v[4:7]
	s_setprio 0
	s_barrier
	s_add_u32 s34, s34, 0x100
	s_addc_u32 s35, s35, 0
	s_add_u32 s40, s40, 0x100
	s_addc_u32 s41, s41, 0
	s_cmp_ge_i32 s60, s8
	s_mov_b32 s36, s60
	s_cbranch_scc0 .LBB0_1094
	s_branch .LBB0_1095
.LBB0_1094:
	s_add_i32 s60, s36, 2
	s_add_u32 s61, s34, 0x80
	s_addc_u32 s37, s35, 0
	s_add_i32 s66, 0, 0x10000
	s_cmp_eq_u32 s56, s36
	s_cselect_b32 s37, s19, s37
	s_cselect_b32 s36, s18, s61
	v_add_u32_e32 v144, s66, v149
	s_cselect_b32 s65, s27, s41
	s_cselect_b32 s64, s26, s40
	s_add_i32 s61, 0, 0x14000
	ds_read_b128 v[152:155], v144
	ds_read_b128 v[156:159], v144 offset:1024
	ds_read_b128 v[160:163], v144 offset:2048
	ds_read_b128 v[164:167], v144 offset:3072
	v_add_u32_e32 v144, s61, v149
	ds_read_b128 v[168:171], v144
	ds_read_b128 v[172:175], v144 offset:1024
	ds_read_b128 v[176:179], v144 offset:2048
	ds_read_b128 v[180:183], v144 offset:3072
	v_lshl_add_u64 v[144:145], s[34:35], 0, v[140:141]
	s_add_i32 m0, s50, 0xc000
	ds_read_b128 v[184:187], v151
	ds_read_b128 v[188:191], v151 offset:1024
	ds_read_b128 v[192:195], v151 offset:2048
	ds_read_b128 v[202:205], v151 offset:3072
	ds_read_b128 v[206:209], v151 offset:4096
	ds_read_b128 v[210:213], v151 offset:5120
	ds_read_b128 v[214:217], v151 offset:6144
	ds_read_b128 v[218:221], v151 offset:7168
	global_load_lds_dwordx4 v[144:145], off
	v_lshl_add_u64 v[144:145], s[34:35], 0, v[142:143]
	s_add_i32 m0, s50, 0xe000
	s_nop 0
	global_load_lds_dwordx4 v[144:145], off
	s_waitcnt vmcnt(8)
	s_waitcnt lgkmcnt(0)
	s_barrier
; #define PG8_GOFFS(slot_) do { _Pragma("unroll") for (int _i = 0; _i < 2; ++_i) { int R, C; stage_rc(tid * 16 + _i * 8192, R, C); _Pragma("unroll") for (int _h = 0; _h < 2; ++_h) { \
;         unsigned t_ = gtab[(slot_) * 256 + R + 128 * _h]; t_ = t_ < (unsigned)(T - 1) ? t_ : (unsigned)(T - 1); voffA[_h][_i] = (t_ * (unsigned)K + (unsigned)C) * 2u; } } } while (0)
; #define PG8_STAGE(bufoff, gbase, voff) do { _Pragma("unroll") for (int _i = 0; _i < 2; ++_i) \
;         __builtin_amdgcn_global_load_lds((const unsigned*)((const char*)(gbase) + (voff)[_i]), (LAS unsigned*)(lds + (bufoff) + ldsw + _i * 8192), 16, 0, 0); } while (0)
; #define PG8_LDA(dst, b, h) do { _Pragma("unroll") for (int m = 0; m < 4; ++m) _Pragma("unroll") for (int k = 0; k < 2; ++k) dst[m][k] = *(const LAS bf16x8*)(lds + PG8_SA(b, h) + aoff + m * 2048 + k * 1024); } while (0)
; #define PG8_MMA(ai, bj, At, Bt) do { __builtin_amdgcn_s_setprio(1); _Pragma("unroll") for (int m = 0; m < 4; ++m) _Pragma("unroll") for (int n = 0; n < 2; ++n) _Pragma("unroll") for (int k = 0; k < 2; ++k) \
;         acc[ai][bj][m][n] = __builtin_amdgcn_mfma_f32_16x16x32_bf16(Bt[n][k], At[m][k], acc[ai][bj][m][n], 0, 0, 0); __builtin_amdgcn_s_setprio(0); } while (0)
; #define PG8_WAIT_V(n) asm volatile("s_waitcnt vmcnt(" #n ")" ::: "memory")
; #define PG8_WAIT_L(n) asm volatile("s_waitcnt lgkmcnt(" #n ")" ::: "memory")
; #define PG8_BAR __builtin_amdgcn_s_barrier()
; #define PG8_SCHED __builtin_amdgcn_sched_barrier(0)
; template <class Epi, class Sched>
; __device__ __forceinline__ void gemm_phase(const int tid, LAS unsigned char* lds, const bf16* Aop, const bf16* Bop, const int K_, const Sched& S, const Epi& E, const bf16* Aop1 = nullptr, const bf16* Bop1 = nullptr) {
;     ...
;             PG8_WAIT_V(8); PG8_WAIT_L(0); PG8_BAR; PG8_MMA(0, 0, At, B0); PG8_MMA(0, 1, At, B1); PG8_BAR; PG8_SCHED;
;             PG8_LDA(At, 0, 1); PG8_STAGE(PG8_SB(0, 0), b2, voffB); PG8_STAGE(PG8_SB(0, 1), b2 + hstep, voffB); if (Epi::GATHER && last && has_next) PG8_GOFFS((ui + 1) & 1); PG8_STAGE(PG8_SA(0, 0), a2, voffA[0]);
;             PG8_WAIT_V(8); PG8_WAIT_L(0); PG8_BAR; PG8_MMA(1, 0, At, B0); PG8_MMA(1, 1, At, B1); PG8_BAR; PG8_SCHED;
	s_setprio 1
	v_mfma_f32_16x16x32_bf16 v[124:127], v[152:155], v[184:187], v[124:127]
	v_mfma_f32_16x16x32_bf16 v[128:131], v[160:163], v[184:187], v[128:131]
	v_mfma_f32_16x16x32_bf16 v[112:115], v[152:155], v[192:195], v[112:115]
	v_mfma_f32_16x16x32_bf16 v[108:111], v[160:163], v[192:195], v[108:111]
	v_mfma_f32_16x16x32_bf16 v[96:99], v[152:155], v[206:209], v[96:99]
	v_mfma_f32_16x16x32_bf16 v[92:95], v[160:163], v[206:209], v[92:95]
	v_mfma_f32_16x16x32_bf16 v[80:83], v[152:155], v[214:217], v[80:83]
	v_mfma_f32_16x16x32_bf16 v[76:79], v[160:163], v[214:217], v[76:79]
	v_mfma_f32_16x16x32_bf16 v[124:127], v[156:159], v[188:191], v[124:127]
	v_mfma_f32_16x16x32_bf16 v[128:131], v[164:167], v[188:191], v[128:131]
	v_mfma_f32_16x16x32_bf16 v[112:115], v[156:159], v[202:205], v[112:115]
	v_mfma_f32_16x16x32_bf16 v[108:111], v[164:167], v[202:205], v[108:111]
	v_mfma_f32_16x16x32_bf16 v[96:99], v[156:159], v[210:213], v[96:99]
	v_mfma_f32_16x16x32_bf16 v[92:95], v[164:167], v[210:213], v[92:95]
	v_mfma_f32_16x16x32_bf16 v[80:83], v[156:159], v[218:221], v[80:83]
	v_mfma_f32_16x16x32_bf16 v[76:79], v[164:167], v[218:221], v[76:79]
	v_mfma_f32_16x16x32_bf16 v[120:123], v[168:171], v[184:187], v[120:123]
	v_mfma_f32_16x16x32_bf16 v[116:119], v[176:179], v[184:187], v[116:119]
	v_mfma_f32_16x16x32_bf16 v[104:107], v[168:171], v[192:195], v[104:107]
	v_mfma_f32_16x16x32_bf16 v[100:103], v[176:179], v[192:195], v[100:103]
	v_mfma_f32_16x16x32_bf16 v[88:91], v[168:171], v[206:209], v[88:91]
	v_mfma_f32_16x16x32_bf16 v[84:87], v[176:179], v[206:209], v[84:87]
	v_mfma_f32_16x16x32_bf16 v[72:75], v[168:171], v[214:217], v[72:75]
	v_mfma_f32_16x16x32_bf16 v[68:71], v[176:179], v[214:217], v[68:71]
	v_mfma_f32_16x16x32_bf16 v[120:123], v[172:175], v[188:191], v[120:123]
	v_mfma_f32_16x16x32_bf16 v[116:119], v[180:183], v[188:191], v[116:119]
	v_mfma_f32_16x16x32_bf16 v[104:107], v[172:175], v[202:205], v[104:107]
	v_mfma_f32_16x16x32_bf16 v[100:103], v[180:183], v[202:205], v[100:103]
	v_mfma_f32_16x16x32_bf16 v[88:91], v[172:175], v[210:213], v[88:91]
	v_mfma_f32_16x16x32_bf16 v[84:87], v[180:183], v[210:213], v[84:87]
	v_mfma_f32_16x16x32_bf16 v[72:75], v[172:175], v[218:221], v[72:75]
	v_mfma_f32_16x16x32_bf16 v[68:71], v[180:183], v[218:221], v[68:71]
	s_setprio 0
	s_barrier
	s_add_i32 s66, s66, s49
	v_lshl_add_u64 v[144:145], s[64:65], 0, v[132:133]
	s_mov_b32 m0, s66
	ds_read_b128 v[184:187], v151 offset:16384
	ds_read_b128 v[188:191], v151 offset:17408
	ds_read_b128 v[192:195], v151 offset:18432
	ds_read_b128 v[202:205], v151 offset:19456
	ds_read_b128 v[206:209], v151 offset:20480
	ds_read_b128 v[210:213], v151 offset:21504
	ds_read_b128 v[214:217], v151 offset:22528
	ds_read_b128 v[218:221], v151 offset:23552
	global_load_lds_dwordx4 v[144:145], off
	s_add_i32 m0, s66, 0x2000
	v_lshl_add_u64 v[196:197], s[64:65], 0, v[136:137]
	s_add_u32 s64, s64, s6
	s_addc_u32 s65, s65, s7
	s_add_i32 s61, s61, s49
	global_load_lds_dwordx4 v[196:197], off
	v_lshl_add_u64 v[198:199], s[64:65], 0, v[132:133]
	s_mov_b32 m0, s61
	v_lshl_add_u64 v[222:223], s[64:65], 0, v[136:137]
	global_load_lds_dwordx4 v[198:199], off
	s_add_i32 m0, s61, 0x2000
	v_lshl_add_u64 v[224:225], s[36:37], 0, v[0:1]
	global_load_lds_dwordx4 v[222:223], off
	s_mov_b32 m0, s50
	v_lshl_add_u64 v[230:231], s[36:37], 0, v[134:135]
	global_load_lds_dwordx4 v[224:225], off
	s_mov_b32 m0, s51
	s_nop 0
	global_load_lds_dwordx4 v[230:231], off
	s_waitcnt vmcnt(8)
	s_waitcnt lgkmcnt(0)
	s_barrier
	s_setprio 1
	v_mfma_f32_16x16x32_bf16 v[64:67], v[152:155], v[184:187], v[64:67]
	v_mfma_f32_16x16x32_bf16 v[60:63], v[160:163], v[184:187], v[60:63]
	v_mfma_f32_16x16x32_bf16 v[48:51], v[152:155], v[192:195], v[48:51]
	v_mfma_f32_16x16x32_bf16 v[44:47], v[160:163], v[192:195], v[44:47]
	v_mfma_f32_16x16x32_bf16 v[32:35], v[152:155], v[206:209], v[32:35]
	v_mfma_f32_16x16x32_bf16 v[28:31], v[160:163], v[206:209], v[28:31]
	v_mfma_f32_16x16x32_bf16 v[16:19], v[152:155], v[214:217], v[16:19]
	v_mfma_f32_16x16x32_bf16 v[12:15], v[160:163], v[214:217], v[12:15]
	v_mfma_f32_16x16x32_bf16 v[64:67], v[156:159], v[188:191], v[64:67]
	v_mfma_f32_16x16x32_bf16 v[60:63], v[164:167], v[188:191], v[60:63]
	v_mfma_f32_16x16x32_bf16 v[48:51], v[156:159], v[202:205], v[48:51]
	v_mfma_f32_16x16x32_bf16 v[44:47], v[164:167], v[202:205], v[44:47]
	v_mfma_f32_16x16x32_bf16 v[32:35], v[156:159], v[210:213], v[32:35]
	v_mfma_f32_16x16x32_bf16 v[28:31], v[164:167], v[210:213], v[28:31]
	v_mfma_f32_16x16x32_bf16 v[16:19], v[156:159], v[218:221], v[16:19]
	v_mfma_f32_16x16x32_bf16 v[12:15], v[164:167], v[218:221], v[12:15]
	v_mfma_f32_16x16x32_bf16 v[56:59], v[168:171], v[184:187], v[56:59]
	v_mfma_f32_16x16x32_bf16 v[52:55], v[176:179], v[184:187], v[52:55]
	v_mfma_f32_16x16x32_bf16 v[40:43], v[168:171], v[192:195], v[40:43]
	v_mfma_f32_16x16x32_bf16 v[36:39], v[176:179], v[192:195], v[36:39]
	v_mfma_f32_16x16x32_bf16 v[24:27], v[168:171], v[206:209], v[24:27]
	v_mfma_f32_16x16x32_bf16 v[20:23], v[176:179], v[206:209], v[20:23]
	v_mfma_f32_16x16x32_bf16 v[8:11], v[168:171], v[214:217], v[8:11]
	v_mfma_f32_16x16x32_bf16 v[4:7], v[176:179], v[214:217], v[4:7]
	v_mfma_f32_16x16x32_bf16 v[56:59], v[172:175], v[188:191], v[56:59]
	v_mfma_f32_16x16x32_bf16 v[52:55], v[180:183], v[188:191], v[52:55]
	v_mfma_f32_16x16x32_bf16 v[40:43], v[172:175], v[202:205], v[40:43]
	v_mfma_f32_16x16x32_bf16 v[36:39], v[180:183], v[202:205], v[36:39]
	v_mfma_f32_16x16x32_bf16 v[24:27], v[172:175], v[210:213], v[24:27]
	v_mfma_f32_16x16x32_bf16 v[20:23], v[180:183], v[210:213], v[20:23]
	v_mfma_f32_16x16x32_bf16 v[8:11], v[172:175], v[218:221], v[8:11]
	v_mfma_f32_16x16x32_bf16 v[4:7], v[180:183], v[218:221], v[4:7]
	s_setprio 0
	s_barrier
; #define PG8_STAGE(bufoff, gbase, voff) do { _Pragma("unroll") for (int _i = 0; _i < 2; ++_i) \
;         __builtin_amdgcn_global_load_lds((const unsigned*)((const char*)(gbase) + (voff)[_i]), (LAS unsigned*)(lds + (bufoff) + ldsw + _i * 8192), 16, 0, 0); } while (0)
; #define PG8_STAGE_A1(bufoff, gbase) do { if (Epi::GATHER) PG8_STAGE(bufoff, gbase, voffA[1]); else PG8_STAGE(bufoff, (gbase) + hstep, voffA[0]); } while (0)
; #define PG8_LDA(dst, b, h) do { _Pragma("unroll") for (int m = 0; m < 4; ++m) _Pragma("unroll") for (int k = 0; k < 2; ++k) dst[m][k] = *(const LAS bf16x8*)(lds + PG8_SA(b, h) + aoff + m * 2048 + k * 1024); } while (0)
; #define PG8_LDB(dst, b, h) do { _Pragma("unroll") for (int n = 0; n < 2; ++n) _Pragma("unroll") for (int k = 0; k < 2; ++k) dst[n][k] = *(const LAS bf16x8*)(lds + PG8_SB(b, h) + boff + n * 2048 + k * 1024); } while (0)
; #define PG8_MMA(ai, bj, At, Bt) do { __builtin_amdgcn_s_setprio(1); _Pragma("unroll") for (int m = 0; m < 4; ++m) _Pragma("unroll") for (int n = 0; n < 2; ++n) _Pragma("unroll") for (int k = 0; k < 2; ++k) \
;         acc[ai][bj][m][n] = __builtin_amdgcn_mfma_f32_16x16x32_bf16(Bt[n][k], At[m][k], acc[ai][bj][m][n], 0, 0, 0); __builtin_amdgcn_s_setprio(0); } while (0)
; #define PG8_WAIT_V(n) asm volatile("s_waitcnt vmcnt(" #n ")" ::: "memory")
; #define PG8_WAIT_L(n) asm volatile("s_waitcnt lgkmcnt(" #n ")" ::: "memory")
; #define PG8_BAR __builtin_amdgcn_s_barrier()
; #define PG8_SCHED __builtin_amdgcn_sched_barrier(0)
; template <class Epi, class Sched>
; __device__ __forceinline__ void gemm_phase(const int tid, LAS unsigned char* lds, const bf16* Aop, const bf16* Bop, const int K_, const Sched& S, const Epi& E, const bf16* Aop1 = nullptr, const bf16* Bop1 = nullptr) {
;     ...
;             PG8_LDB(B0, 1, 0); PG8_LDB(B1, 1, 1); PG8_SCHED; PG8_LDA(At, 1, 0); PG8_STAGE_A1(PG8_SA(0, 1), a2);
;             PG8_WAIT_V(8); PG8_WAIT_L(0); PG8_BAR; PG8_MMA(0, 0, At, B0); PG8_MMA(0, 1, At, B1); PG8_BAR; PG8_SCHED;
;             PG8_LDA(At, 1, 1); PG8_STAGE(PG8_SB(1, 0), b3, voffB); PG8_STAGE(PG8_SB(1, 1), b3 + hstep, voffB); PG8_STAGE(PG8_SA(1, 0), a3, voffA[0]);
;             PG8_WAIT_V(8); PG8_WAIT_L(0); PG8_BAR; PG8_MMA(1, 0, At, B0); PG8_MMA(1, 1, At, B1); PG8_BAR; PG8_SCHED;
;         }
	s_add_i32 s61, 0, 0x18000
	s_add_i32 s64, 0, 0x1c000
	v_add_u32_e32 v164, s61, v149
	v_add_u32_e32 v180, s64, v149
	ds_read_b128 v[152:155], v164
	ds_read_b128 v[156:159], v164 offset:1024
	ds_read_b128 v[160:163], v164 offset:2048
	ds_read_b128 v[164:167], v164 offset:3072
	ds_read_b128 v[168:171], v180
	ds_read_b128 v[172:175], v180 offset:1024
	ds_read_b128 v[176:179], v180 offset:2048
	ds_read_b128 v[180:183], v180 offset:3072
	s_add_u32 s36, s36, s6
	s_addc_u32 s37, s37, s7
	s_mov_b32 m0, s52
	v_lshl_add_u64 v[232:233], s[36:37], 0, v[0:1]
	ds_read_b128 v[184:187], v151 offset:32768
	ds_read_b128 v[188:191], v151 offset:33792
	ds_read_b128 v[192:195], v151 offset:34816
	ds_read_b128 v[202:205], v151 offset:35840
	ds_read_b128 v[206:209], v151 offset:36864
	ds_read_b128 v[210:213], v151 offset:37888
	ds_read_b128 v[214:217], v151 offset:38912
	ds_read_b128 v[218:221], v151 offset:39936
	global_load_lds_dwordx4 v[232:233], off
	v_lshl_add_u64 v[232:233], s[36:37], 0, v[134:135]
	s_mov_b32 m0, s53
	s_nop 0
	global_load_lds_dwordx4 v[232:233], off
	s_waitcnt vmcnt(8)
	s_waitcnt lgkmcnt(0)
	s_barrier
	s_setprio 1
	v_mfma_f32_16x16x32_bf16 v[124:127], v[152:155], v[184:187], v[124:127]
	v_mfma_f32_16x16x32_bf16 v[128:131], v[160:163], v[184:187], v[128:131]
	v_mfma_f32_16x16x32_bf16 v[112:115], v[152:155], v[192:195], v[112:115]
	v_mfma_f32_16x16x32_bf16 v[108:111], v[160:163], v[192:195], v[108:111]
	v_mfma_f32_16x16x32_bf16 v[96:99], v[152:155], v[206:209], v[96:99]
	v_mfma_f32_16x16x32_bf16 v[92:95], v[160:163], v[206:209], v[92:95]
	v_mfma_f32_16x16x32_bf16 v[80:83], v[152:155], v[214:217], v[80:83]
	v_mfma_f32_16x16x32_bf16 v[76:79], v[160:163], v[214:217], v[76:79]
	v_mfma_f32_16x16x32_bf16 v[124:127], v[156:159], v[188:191], v[124:127]
	v_mfma_f32_16x16x32_bf16 v[128:131], v[164:167], v[188:191], v[128:131]
	v_mfma_f32_16x16x32_bf16 v[112:115], v[156:159], v[202:205], v[112:115]
	v_mfma_f32_16x16x32_bf16 v[108:111], v[164:167], v[202:205], v[108:111]
	v_mfma_f32_16x16x32_bf16 v[96:99], v[156:159], v[210:213], v[96:99]
	v_mfma_f32_16x16x32_bf16 v[92:95], v[164:167], v[210:213], v[92:95]
	v_mfma_f32_16x16x32_bf16 v[80:83], v[156:159], v[218:221], v[80:83]
	v_mfma_f32_16x16x32_bf16 v[76:79], v[164:167], v[218:221], v[76:79]
	v_mfma_f32_16x16x32_bf16 v[120:123], v[168:171], v[184:187], v[120:123]
	v_mfma_f32_16x16x32_bf16 v[116:119], v[176:179], v[184:187], v[116:119]
	v_mfma_f32_16x16x32_bf16 v[104:107], v[168:171], v[192:195], v[104:107]
	v_mfma_f32_16x16x32_bf16 v[100:103], v[176:179], v[192:195], v[100:103]
	v_mfma_f32_16x16x32_bf16 v[88:91], v[168:171], v[206:209], v[88:91]
	v_mfma_f32_16x16x32_bf16 v[84:87], v[176:179], v[206:209], v[84:87]
	v_mfma_f32_16x16x32_bf16 v[72:75], v[168:171], v[214:217], v[72:75]
	v_mfma_f32_16x16x32_bf16 v[68:71], v[176:179], v[214:217], v[68:71]
	v_mfma_f32_16x16x32_bf16 v[120:123], v[172:175], v[188:191], v[120:123]
	v_mfma_f32_16x16x32_bf16 v[116:119], v[180:183], v[188:191], v[116:119]
	v_mfma_f32_16x16x32_bf16 v[104:107], v[172:175], v[202:205], v[104:107]
	v_mfma_f32_16x16x32_bf16 v[100:103], v[180:183], v[202:205], v[100:103]
	v_mfma_f32_16x16x32_bf16 v[88:91], v[172:175], v[210:213], v[88:91]
	v_mfma_f32_16x16x32_bf16 v[84:87], v[180:183], v[210:213], v[84:87]
	v_mfma_f32_16x16x32_bf16 v[72:75], v[172:175], v[218:221], v[72:75]
	v_mfma_f32_16x16x32_bf16 v[68:71], v[180:183], v[218:221], v[68:71]
	s_setprio 0
	s_barrier
	s_add_i32 s36, s61, s49
	v_lshl_add_u64 v[144:145], v[144:145], 0, s[20:21]
	s_mov_b32 m0, s36
	ds_read_b128 v[184:187], v151 offset:49152
	ds_read_b128 v[188:191], v151 offset:50176
	ds_read_b128 v[192:195], v151 offset:51200
	ds_read_b128 v[202:205], v151 offset:52224
	ds_read_b128 v[206:209], v151 offset:53248
	ds_read_b128 v[210:213], v151 offset:54272
	ds_read_b128 v[214:217], v151 offset:55296
	ds_read_b128 v[218:221], v151 offset:56320
	global_load_lds_dwordx4 v[144:145], off
	v_lshl_add_u64 v[144:145], v[196:197], 0, s[20:21]
	s_add_i32 m0, s36, 0x2000
	s_add_i32 s36, s64, s49
	global_load_lds_dwordx4 v[144:145], off
	v_lshl_add_u64 v[144:145], v[198:199], 0, s[20:21]
	s_mov_b32 m0, s36
	s_nop 0
	global_load_lds_dwordx4 v[144:145], off
	v_lshl_add_u64 v[144:145], v[222:223], 0, s[20:21]
	s_add_i32 m0, s36, 0x2000
	s_nop 0
	global_load_lds_dwordx4 v[144:145], off
	v_lshl_add_u64 v[144:145], v[224:225], 0, s[20:21]
	s_mov_b32 m0, s54
	s_nop 0
	global_load_lds_dwordx4 v[144:145], off
	v_lshl_add_u64 v[144:145], v[230:231], 0, s[20:21]
	s_mov_b32 m0, s55
	s_nop 0
	global_load_lds_dwordx4 v[144:145], off
	s_waitcnt vmcnt(8)
	s_waitcnt lgkmcnt(0)
	s_barrier
	s_setprio 1
	v_mfma_f32_16x16x32_bf16 v[64:67], v[152:155], v[184:187], v[64:67]
	v_mfma_f32_16x16x32_bf16 v[60:63], v[160:163], v[184:187], v[60:63]
	v_mfma_f32_16x16x32_bf16 v[48:51], v[152:155], v[192:195], v[48:51]
	v_mfma_f32_16x16x32_bf16 v[44:47], v[160:163], v[192:195], v[44:47]
	v_mfma_f32_16x16x32_bf16 v[32:35], v[152:155], v[206:209], v[32:35]
	v_mfma_f32_16x16x32_bf16 v[28:31], v[160:163], v[206:209], v[28:31]
	v_mfma_f32_16x16x32_bf16 v[16:19], v[152:155], v[214:217], v[16:19]
	v_mfma_f32_16x16x32_bf16 v[12:15], v[160:163], v[214:217], v[12:15]
	v_mfma_f32_16x16x32_bf16 v[64:67], v[156:159], v[188:191], v[64:67]
	v_mfma_f32_16x16x32_bf16 v[60:63], v[164:167], v[188:191], v[60:63]
	v_mfma_f32_16x16x32_bf16 v[48:51], v[156:159], v[202:205], v[48:51]
	v_mfma_f32_16x16x32_bf16 v[44:47], v[164:167], v[202:205], v[44:47]
	v_mfma_f32_16x16x32_bf16 v[32:35], v[156:159], v[210:213], v[32:35]
	v_mfma_f32_16x16x32_bf16 v[28:31], v[164:167], v[210:213], v[28:31]
	v_mfma_f32_16x16x32_bf16 v[16:19], v[156:159], v[218:221], v[16:19]
	v_mfma_f32_16x16x32_bf16 v[12:15], v[164:167], v[218:221], v[12:15]
	v_mfma_f32_16x16x32_bf16 v[56:59], v[168:171], v[184:187], v[56:59]
	v_mfma_f32_16x16x32_bf16 v[52:55], v[176:179], v[184:187], v[52:55]
	v_mfma_f32_16x16x32_bf16 v[40:43], v[168:171], v[192:195], v[40:43]
	v_mfma_f32_16x16x32_bf16 v[36:39], v[176:179], v[192:195], v[36:39]
	v_mfma_f32_16x16x32_bf16 v[24:27], v[168:171], v[206:209], v[24:27]
	v_mfma_f32_16x16x32_bf16 v[20:23], v[176:179], v[206:209], v[20:23]
	v_mfma_f32_16x16x32_bf16 v[8:11], v[168:171], v[214:217], v[8:11]
	v_mfma_f32_16x16x32_bf16 v[4:7], v[176:179], v[214:217], v[4:7]
	v_mfma_f32_16x16x32_bf16 v[56:59], v[172:175], v[188:191], v[56:59]
	v_mfma_f32_16x16x32_bf16 v[52:55], v[180:183], v[188:191], v[52:55]
	v_mfma_f32_16x16x32_bf16 v[40:43], v[172:175], v[202:205], v[40:43]
	v_mfma_f32_16x16x32_bf16 v[36:39], v[180:183], v[202:205], v[36:39]
	v_mfma_f32_16x16x32_bf16 v[24:27], v[172:175], v[210:213], v[24:27]
	v_mfma_f32_16x16x32_bf16 v[20:23], v[180:183], v[210:213], v[20:23]
	v_mfma_f32_16x16x32_bf16 v[8:11], v[172:175], v[218:221], v[8:11]
	v_mfma_f32_16x16x32_bf16 v[4:7], v[180:183], v[218:221], v[4:7]
	s_setprio 0
	s_barrier
	s_add_u32 s34, s34, 0x100
	s_addc_u32 s35, s35, 0
	s_add_u32 s40, s40, 0x100
	s_addc_u32 s41, s41, 0
	s_cmp_ge_i32 s60, s8
	s_mov_b32 s36, s60
	s_cbranch_scc0 .LBB0_1094

; #define PG8_GOFFS(slot_) do { _Pragma("unroll") for (int _i = 0; _i < 2; ++_i) { int R, C; stage_rc(tid * 16 + _i * 8192, R, C); _Pragma("unroll") for (int _h = 0; _h < 2; ++_h) { \
;         unsigned t_ = gtab[(slot_) * 256 + R + 128 * _h]; t_ = t_ < (unsigned)(T - 1) ? t_ : (unsigned)(T - 1); voffA[_h][_i] = (t_ * (unsigned)K + (unsigned)C) * 2u; } } } while (0)
; #define PG8_STAGE(bufoff, gbase, voff) do { _Pragma("unroll") for (int _i = 0; _i < 2; ++_i) \
;         __builtin_amdgcn_global_load_lds((const unsigned*)((const char*)(gbase) + (voff)[_i]), (LAS unsigned*)(lds + (bufoff) + ldsw + _i * 8192), 16, 0, 0); } while (0)
; #define PG8_STAGE_A1(bufoff, gbase) do { if (Epi::GATHER) PG8_STAGE(bufoff, gbase, voffA[1]); else PG8_STAGE(bufoff, (gbase) + hstep, voffA[0]); } while (0)
; #define PG8_LDA(dst, b, h) do { _Pragma("unroll") for (int m = 0; m < 4; ++m) _Pragma("unroll") for (int k = 0; k < 2; ++k) dst[m][k] = *(const LAS bf16x8*)(lds + PG8_SA(b, h) + aoff + m * 2048 + k * 1024); } while (0)
; #define PG8_LDB(dst, b, h) do { _Pragma("unroll") for (int n = 0; n < 2; ++n) _Pragma("unroll") for (int k = 0; k < 2; ++k) dst[n][k] = *(const LAS bf16x8*)(lds + PG8_SB(b, h) + boff + n * 2048 + k * 1024); } while (0)
; #define PG8_WAIT_V(n) asm volatile("s_waitcnt vmcnt(" #n ")" ::: "memory")
; #define PG8_WAIT_L(n) asm volatile("s_waitcnt lgkmcnt(" #n ")" ::: "memory")
; #define PG8_BAR __builtin_amdgcn_s_barrier()
; #define PG8_SCHED __builtin_amdgcn_sched_barrier(0)
; template <class Epi, class Sched>
; __device__ __forceinline__ void gemm_phase(const int tid, LAS unsigned char* lds, const bf16* Aop, const bf16* Bop, const int K_, const Sched& S, const Epi& E, const bf16* Aop1 = nullptr, const bf16* Bop1 = nullptr) {
;     ...
;             PG8_LDA(At, 0, 1); PG8_STAGE(PG8_SB(0, 0), b2, voffB); PG8_STAGE(PG8_SB(0, 1), b2 + hstep, voffB); if (Epi::GATHER && last && has_next) PG8_GOFFS((ui + 1) & 1); PG8_STAGE(PG8_SA(0, 0), a2, voffA[0]);
;             PG8_WAIT_V(8); PG8_WAIT_L(0); PG8_BAR; PG8_MMA(1, 0, At, B0); PG8_MMA(1, 1, At, B1); PG8_BAR; PG8_SCHED;
;             PG8_LDB(B0, 1, 0); PG8_LDB(B1, 1, 1); PG8_SCHED; PG8_LDA(At, 1, 0); PG8_STAGE_A1(PG8_SA(0, 1), a2);
;             PG8_WAIT_V(8); PG8_WAIT_L(0); PG8_BAR; PG8_MMA(0, 0, At, B0); PG8_MMA(0, 1, At, B1); PG8_BAR; PG8_SCHED;
.LBB0_1314:
	s_add_i32 s69, s69, 2
	s_add_u32 s40, s40, 0x100
	s_addc_u32 s41, s41, 0
	s_and_b64 s[42:43], s[42:43], exec
	s_cselect_b32 s42, 0, s40
	s_cselect_b32 s43, 0, s41
	s_add_u32 s42, s4, s42
	s_mov_b32 m0, s52
	s_addc_u32 s43, s5, s43
	global_load_lds_dwordx4 v204, s[42:43]
	s_mov_b32 m0, s53
	v_mov_b32_e32 v205, v2
	global_load_lds_dwordx4 v208, s[42:43]
	s_waitcnt vmcnt(8)
	s_waitcnt lgkmcnt(0)
	v_mov_b32_e32 v209, v2
	v_mov_b32_e32 v207, v2
	v_mov_b32_e32 v211, v2
	v_lshl_add_u64 v[196:197], s[42:43], 0, v[204:205]
	v_lshl_add_u64 v[198:199], s[42:43], 0, v[208:209]
	s_barrier
	s_setprio 1
	s_waitcnt lgkmcnt(0)
	v_mfma_f32_16x16x32_bf16 v[64:67], v[148:151], v[188:191], v[64:67]
	v_mfma_f32_16x16x32_bf16 v[56:59], v[156:159], v[188:191], v[56:59]
	v_mfma_f32_16x16x32_bf16 v[48:51], v[148:151], v[180:183], v[48:51]
	v_mfma_f32_16x16x32_bf16 v[40:43], v[156:159], v[180:183], v[40:43]
	v_mfma_f32_16x16x32_bf16 v[32:35], v[148:151], v[172:175], v[32:35]
	v_mfma_f32_16x16x32_bf16 v[24:27], v[156:159], v[172:175], v[24:27]
	v_mfma_f32_16x16x32_bf16 v[16:19], v[148:151], v[164:167], v[16:19]
	v_mfma_f32_16x16x32_bf16 v[8:11], v[156:159], v[164:167], v[8:11]
	v_mfma_f32_16x16x32_bf16 v[64:67], v[152:155], v[192:195], v[64:67]
	v_mfma_f32_16x16x32_bf16 v[56:59], v[160:163], v[192:195], v[56:59]
	v_mfma_f32_16x16x32_bf16 v[48:51], v[152:155], v[184:187], v[48:51]
	v_mfma_f32_16x16x32_bf16 v[40:43], v[160:163], v[184:187], v[40:43]
	v_mfma_f32_16x16x32_bf16 v[32:35], v[152:155], v[176:179], v[32:35]
	v_mfma_f32_16x16x32_bf16 v[24:27], v[160:163], v[176:179], v[24:27]
	v_mfma_f32_16x16x32_bf16 v[16:19], v[152:155], v[168:171], v[16:19]
	v_mfma_f32_16x16x32_bf16 v[8:11], v[160:163], v[168:171], v[8:11]
	v_mfma_f32_16x16x32_bf16 v[60:63], v[132:135], v[188:191], v[60:63]
	v_mfma_f32_16x16x32_bf16 v[52:55], v[140:143], v[188:191], v[52:55]
	v_mfma_f32_16x16x32_bf16 v[44:47], v[132:135], v[180:183], v[44:47]
	v_mfma_f32_16x16x32_bf16 v[36:39], v[140:143], v[180:183], v[36:39]
	v_mfma_f32_16x16x32_bf16 v[28:31], v[132:135], v[172:175], v[28:31]
	v_mfma_f32_16x16x32_bf16 v[20:23], v[140:143], v[172:175], v[20:23]
	v_mfma_f32_16x16x32_bf16 v[12:15], v[132:135], v[164:167], v[12:15]
	v_mfma_f32_16x16x32_bf16 v[4:7], v[140:143], v[164:167], v[4:7]
	v_mfma_f32_16x16x32_bf16 v[60:63], v[136:139], v[192:195], v[60:63]
	v_mfma_f32_16x16x32_bf16 v[52:55], v[144:147], v[192:195], v[52:55]
	v_mfma_f32_16x16x32_bf16 v[44:47], v[136:139], v[184:187], v[44:47]
	v_mfma_f32_16x16x32_bf16 v[36:39], v[144:147], v[184:187], v[36:39]
	v_mfma_f32_16x16x32_bf16 v[28:31], v[136:139], v[176:179], v[28:31]
	v_mfma_f32_16x16x32_bf16 v[20:23], v[144:147], v[176:179], v[20:23]
	v_mfma_f32_16x16x32_bf16 v[12:15], v[136:139], v[168:171], v[12:15]
	v_mfma_f32_16x16x32_bf16 v[4:7], v[144:147], v[168:171], v[4:7]
	s_setprio 0
	s_barrier
	s_add_i32 s70, 0, 0x18000
	s_add_i32 s71, 0, 0x1c000
	v_add_u32_e32 v144, s70, v242
	v_add_u32_e32 v160, s71, v242
	ds_read_b128 v[132:135], v144
	ds_read_b128 v[136:139], v144 offset:1024
	ds_read_b128 v[140:143], v144 offset:2048
	ds_read_b128 v[144:147], v144 offset:3072
	ds_read_b128 v[148:151], v160
	ds_read_b128 v[152:155], v160 offset:1024
	ds_read_b128 v[156:159], v160 offset:2048
	ds_read_b128 v[160:163], v160 offset:3072
	s_mov_b32 m0, s54
	v_lshl_add_u64 v[224:225], s[42:43], 0, v[206:207]
	ds_read_b128 v[164:167], v244 offset:32768
	ds_read_b128 v[168:171], v244 offset:33792
	ds_read_b128 v[172:175], v244 offset:34816
	ds_read_b128 v[176:179], v244 offset:35840
	ds_read_b128 v[180:183], v244 offset:36864
	ds_read_b128 v[184:187], v244 offset:37888
	ds_read_b128 v[188:191], v244 offset:38912
	ds_read_b128 v[192:195], v244 offset:39936
	global_load_lds_dwordx4 v[224:225], off
	v_lshl_add_u64 v[224:225], s[42:43], 0, v[210:211]
	s_mov_b32 m0, s55
	s_nop 0
	global_load_lds_dwordx4 v[224:225], off
	s_waitcnt vmcnt(8)
	s_waitcnt lgkmcnt(0)
	s_barrier
	s_setprio 1
	v_mfma_f32_16x16x32_bf16 v[124:127], v[132:135], v[164:167], v[124:127]
	v_mfma_f32_16x16x32_bf16 v[120:123], v[140:143], v[164:167], v[120:123]
	v_mfma_f32_16x16x32_bf16 v[112:115], v[132:135], v[172:175], v[112:115]
	v_mfma_f32_16x16x32_bf16 v[104:107], v[140:143], v[172:175], v[104:107]
	v_mfma_f32_16x16x32_bf16 v[96:99], v[132:135], v[180:183], v[96:99]
	v_mfma_f32_16x16x32_bf16 v[88:91], v[140:143], v[180:183], v[88:91]
	v_mfma_f32_16x16x32_bf16 v[80:83], v[132:135], v[188:191], v[80:83]
	v_mfma_f32_16x16x32_bf16 v[72:75], v[140:143], v[188:191], v[72:75]
	v_mfma_f32_16x16x32_bf16 v[124:127], v[136:139], v[168:171], v[124:127]
	v_mfma_f32_16x16x32_bf16 v[120:123], v[144:147], v[168:171], v[120:123]
	v_mfma_f32_16x16x32_bf16 v[112:115], v[136:139], v[176:179], v[112:115]
	v_mfma_f32_16x16x32_bf16 v[104:107], v[144:147], v[176:179], v[104:107]
	v_mfma_f32_16x16x32_bf16 v[96:99], v[136:139], v[184:187], v[96:99]
	v_mfma_f32_16x16x32_bf16 v[88:91], v[144:147], v[184:187], v[88:91]
	v_mfma_f32_16x16x32_bf16 v[80:83], v[136:139], v[192:195], v[80:83]
	v_mfma_f32_16x16x32_bf16 v[72:75], v[144:147], v[192:195], v[72:75]
	v_mfma_f32_16x16x32_bf16 v[128:131], v[148:151], v[164:167], v[128:131]
	v_mfma_f32_16x16x32_bf16 v[116:119], v[156:159], v[164:167], v[116:119]
	v_mfma_f32_16x16x32_bf16 v[108:111], v[148:151], v[172:175], v[108:111]
	v_mfma_f32_16x16x32_bf16 v[100:103], v[156:159], v[172:175], v[100:103]
	v_mfma_f32_16x16x32_bf16 v[92:95], v[148:151], v[180:183], v[92:95]
	v_mfma_f32_16x16x32_bf16 v[84:87], v[156:159], v[180:183], v[84:87]
	v_mfma_f32_16x16x32_bf16 v[76:79], v[148:151], v[188:191], v[76:79]
	v_mfma_f32_16x16x32_bf16 v[68:71], v[156:159], v[188:191], v[68:71]
	v_mfma_f32_16x16x32_bf16 v[128:131], v[152:155], v[168:171], v[128:131]
	v_mfma_f32_16x16x32_bf16 v[116:119], v[160:163], v[168:171], v[116:119]
	v_mfma_f32_16x16x32_bf16 v[108:111], v[152:155], v[176:179], v[108:111]
	v_mfma_f32_16x16x32_bf16 v[100:103], v[160:163], v[176:179], v[100:103]
	v_mfma_f32_16x16x32_bf16 v[92:95], v[152:155], v[184:187], v[92:95]
	v_mfma_f32_16x16x32_bf16 v[84:87], v[160:163], v[184:187], v[84:87]
	v_mfma_f32_16x16x32_bf16 v[76:79], v[152:155], v[192:195], v[76:79]
	v_mfma_f32_16x16x32_bf16 v[68:71], v[160:163], v[192:195], v[68:71]
	s_setprio 0
	s_barrier
; #define PG8_STAGE(bufoff, gbase, voff) do { _Pragma("unroll") for (int _i = 0; _i < 2; ++_i) \
;         __builtin_amdgcn_global_load_lds((const unsigned*)((const char*)(gbase) + (voff)[_i]), (LAS unsigned*)(lds + (bufoff) + ldsw + _i * 8192), 16, 0, 0); } while (0)
; #define PG8_LDA(dst, b, h) do { _Pragma("unroll") for (int m = 0; m < 4; ++m) _Pragma("unroll") for (int k = 0; k < 2; ++k) dst[m][k] = *(const LAS bf16x8*)(lds + PG8_SA(b, h) + aoff + m * 2048 + k * 1024); } while (0)
; #define PG8_MMA(ai, bj, At, Bt) do { __builtin_amdgcn_s_setprio(1); _Pragma("unroll") for (int m = 0; m < 4; ++m) _Pragma("unroll") for (int n = 0; n < 2; ++n) _Pragma("unroll") for (int k = 0; k < 2; ++k) \
;         acc[ai][bj][m][n] = __builtin_amdgcn_mfma_f32_16x16x32_bf16(Bt[n][k], At[m][k], acc[ai][bj][m][n], 0, 0, 0); __builtin_amdgcn_s_setprio(0); } while (0)
; #define PG8_WAIT_V(n) asm volatile("s_waitcnt vmcnt(" #n ")" ::: "memory")
; #define PG8_WAIT_L(n) asm volatile("s_waitcnt lgkmcnt(" #n ")" ::: "memory")
; #define PG8_BAR __builtin_amdgcn_s_barrier()
; #define PG8_SCHED __builtin_amdgcn_sched_barrier(0)
; template <class Epi, class Sched>
; __device__ __forceinline__ void gemm_phase(const int tid, LAS unsigned char* lds, const bf16* Aop, const bf16* Bop, const int K_, const Sched& S, const Epi& E, const bf16* Aop1 = nullptr, const bf16* Bop1 = nullptr) {
;     ...
;             PG8_LDA(At, 1, 1); PG8_STAGE(PG8_SB(1, 0), b3, voffB); PG8_STAGE(PG8_SB(1, 1), b3 + hstep, voffB); PG8_STAGE(PG8_SA(1, 0), a3, voffA[0]);
;             PG8_WAIT_V(8); PG8_WAIT_L(0); PG8_BAR; PG8_MMA(1, 0, At, B0); PG8_MMA(1, 1, At, B1); PG8_BAR; PG8_SCHED;
;         }
	s_add_i32 s42, s70, s51
	v_lshl_add_u64 v[216:217], v[216:217], 0, s[20:21]
	s_mov_b32 m0, s42
	ds_read_b128 v[164:167], v244 offset:49152
	ds_read_b128 v[168:171], v244 offset:50176
	ds_read_b128 v[172:175], v244 offset:51200
	ds_read_b128 v[176:179], v244 offset:52224
	ds_read_b128 v[180:183], v244 offset:53248
	ds_read_b128 v[184:187], v244 offset:54272
	ds_read_b128 v[188:191], v244 offset:55296
	ds_read_b128 v[192:195], v244 offset:56320
	global_load_lds_dwordx4 v[216:217], off
	v_lshl_add_u64 v[216:217], v[218:219], 0, s[20:21]
	s_add_i32 m0, s42, 0x2000
	s_add_i32 s42, s71, s51
	global_load_lds_dwordx4 v[216:217], off
	v_lshl_add_u64 v[216:217], v[220:221], 0, s[20:21]
	s_mov_b32 m0, s42
	v_lshl_add_u64 v[196:197], v[196:197], 0, s[20:21]
	global_load_lds_dwordx4 v[216:217], off
	v_lshl_add_u64 v[216:217], v[222:223], 0, s[20:21]
	s_add_i32 m0, s42, 0x2000
	s_nop 0
	global_load_lds_dwordx4 v[216:217], off
	s_mov_b32 m0, s56
	s_nop 0
	global_load_lds_dwordx4 v[196:197], off
	v_lshl_add_u64 v[196:197], v[198:199], 0, s[20:21]
	s_mov_b32 m0, s57
	s_nop 0
	global_load_lds_dwordx4 v[196:197], off
	s_waitcnt vmcnt(8)
	s_waitcnt lgkmcnt(0)
	s_barrier
	s_setprio 1
	v_mfma_f32_16x16x32_bf16 v[64:67], v[132:135], v[164:167], v[64:67]
	v_mfma_f32_16x16x32_bf16 v[56:59], v[140:143], v[164:167], v[56:59]
	v_mfma_f32_16x16x32_bf16 v[48:51], v[132:135], v[172:175], v[48:51]
	v_mfma_f32_16x16x32_bf16 v[40:43], v[140:143], v[172:175], v[40:43]
	v_mfma_f32_16x16x32_bf16 v[32:35], v[132:135], v[180:183], v[32:35]
	v_mfma_f32_16x16x32_bf16 v[24:27], v[140:143], v[180:183], v[24:27]
	v_mfma_f32_16x16x32_bf16 v[16:19], v[132:135], v[188:191], v[16:19]
	v_mfma_f32_16x16x32_bf16 v[8:11], v[140:143], v[188:191], v[8:11]
	v_mfma_f32_16x16x32_bf16 v[64:67], v[136:139], v[168:171], v[64:67]
	v_mfma_f32_16x16x32_bf16 v[56:59], v[144:147], v[168:171], v[56:59]
	v_mfma_f32_16x16x32_bf16 v[48:51], v[136:139], v[176:179], v[48:51]
	v_mfma_f32_16x16x32_bf16 v[40:43], v[144:147], v[176:179], v[40:43]
	v_mfma_f32_16x16x32_bf16 v[32:35], v[136:139], v[184:187], v[32:35]
	v_mfma_f32_16x16x32_bf16 v[24:27], v[144:147], v[184:187], v[24:27]
	v_mfma_f32_16x16x32_bf16 v[16:19], v[136:139], v[192:195], v[16:19]
	v_mfma_f32_16x16x32_bf16 v[8:11], v[144:147], v[192:195], v[8:11]
	v_mfma_f32_16x16x32_bf16 v[60:63], v[148:151], v[164:167], v[60:63]
	v_mfma_f32_16x16x32_bf16 v[52:55], v[156:159], v[164:167], v[52:55]
	v_mfma_f32_16x16x32_bf16 v[44:47], v[148:151], v[172:175], v[44:47]
	v_mfma_f32_16x16x32_bf16 v[36:39], v[156:159], v[172:175], v[36:39]
	v_mfma_f32_16x16x32_bf16 v[28:31], v[148:151], v[180:183], v[28:31]
	v_mfma_f32_16x16x32_bf16 v[20:23], v[156:159], v[180:183], v[20:23]
	v_mfma_f32_16x16x32_bf16 v[12:15], v[148:151], v[188:191], v[12:15]
	v_mfma_f32_16x16x32_bf16 v[4:7], v[156:159], v[188:191], v[4:7]
	v_mfma_f32_16x16x32_bf16 v[60:63], v[152:155], v[168:171], v[60:63]
	v_mfma_f32_16x16x32_bf16 v[52:55], v[160:163], v[168:171], v[52:55]
	v_mfma_f32_16x16x32_bf16 v[44:47], v[152:155], v[176:179], v[44:47]
	v_mfma_f32_16x16x32_bf16 v[36:39], v[160:163], v[176:179], v[36:39]
	v_mfma_f32_16x16x32_bf16 v[28:31], v[152:155], v[184:187], v[28:31]
	v_mfma_f32_16x16x32_bf16 v[20:23], v[160:163], v[184:187], v[20:23]
	v_mfma_f32_16x16x32_bf16 v[12:15], v[152:155], v[192:195], v[12:15]
	v_mfma_f32_16x16x32_bf16 v[4:7], v[160:163], v[192:195], v[4:7]
	s_setprio 0
	s_barrier
	s_cmp_ge_i32 s69, s3
	s_cbranch_scc1 .LBB0_1318
; #define PG8_GOFFS(slot_) do { _Pragma("unroll") for (int _i = 0; _i < 2; ++_i) { int R, C; stage_rc(tid * 16 + _i * 8192, R, C); _Pragma("unroll") for (int _h = 0; _h < 2; ++_h) { \
;         unsigned t_ = gtab[(slot_) * 256 + R + 128 * _h]; t_ = t_ < (unsigned)(T - 1) ? t_ : (unsigned)(T - 1); voffA[_h][_i] = (t_ * (unsigned)K + (unsigned)C) * 2u; } } } while (0)
; #define PG8_STAGE(bufoff, gbase, voff) do { _Pragma("unroll") for (int _i = 0; _i < 2; ++_i) \
;         __builtin_amdgcn_global_load_lds((const unsigned*)((const char*)(gbase) + (voff)[_i]), (LAS unsigned*)(lds + (bufoff) + ldsw + _i * 8192), 16, 0, 0); } while (0)
; #define PG8_STAGE_A1(bufoff, gbase) do { if (Epi::GATHER) PG8_STAGE(bufoff, gbase, voffA[1]); else PG8_STAGE(bufoff, (gbase) + hstep, voffA[0]); } while (0)
; #define PG8_LDA(dst, b, h) do { _Pragma("unroll") for (int m = 0; m < 4; ++m) _Pragma("unroll") for (int k = 0; k < 2; ++k) dst[m][k] = *(const LAS bf16x8*)(lds + PG8_SA(b, h) + aoff + m * 2048 + k * 1024); } while (0)
; #define PG8_LDB(dst, b, h) do { _Pragma("unroll") for (int n = 0; n < 2; ++n) _Pragma("unroll") for (int k = 0; k < 2; ++k) dst[n][k] = *(const LAS bf16x8*)(lds + PG8_SB(b, h) + boff + n * 2048 + k * 1024); } while (0)
; #define PG8_MMA(ai, bj, At, Bt) do { __builtin_amdgcn_s_setprio(1); _Pragma("unroll") for (int m = 0; m < 4; ++m) _Pragma("unroll") for (int n = 0; n < 2; ++n) _Pragma("unroll") for (int k = 0; k < 2; ++k) \
;         acc[ai][bj][m][n] = __builtin_amdgcn_mfma_f32_16x16x32_bf16(Bt[n][k], At[m][k], acc[ai][bj][m][n], 0, 0, 0); __builtin_amdgcn_s_setprio(0); } while (0)
; #define PG8_WAIT_V(n) asm volatile("s_waitcnt vmcnt(" #n ")" ::: "memory")
; template <class Epi, class Sched>
; __device__ __forceinline__ void gemm_phase(const int tid, LAS unsigned char* lds, const bf16* Aop, const bf16* Bop, const int K_, const Sched& S, const Epi& E, const bf16* Aop1 = nullptr, const bf16* Bop1 = nullptr) {
;     ...
;             PG8_LDB(B0, 0, 0); PG8_LDB(B1, 0, 1); PG8_SCHED; PG8_LDA(At, 0, 0); PG8_STAGE_A1(PG8_SA(1, 1), a1);
;             PG8_WAIT_V(8); PG8_WAIT_L(0); PG8_BAR; PG8_MMA(0, 0, At, B0); PG8_MMA(0, 1, At, B1); PG8_BAR; PG8_SCHED;
;             PG8_LDA(At, 0, 1); PG8_STAGE(PG8_SB(0, 0), b2, voffB); PG8_STAGE(PG8_SB(0, 1), b2 + hstep, voffB); if (Epi::GATHER && last && has_next) PG8_GOFFS((ui + 1) & 1); PG8_STAGE(PG8_SA(0, 0), a2, voffA[0]);
.LBB0_1315:
	s_cmp_eq_u32 s60, s69
	s_cselect_b64 s[42:43], -1, 0
	s_add_u32 s72, s67, s40
	s_addc_u32 s73, s68, s41
	s_add_i32 s74, 0, 0x10000
	s_and_b64 s[70:71], s[42:43], exec
	s_cselect_b32 s71, s29, s73
	s_cselect_b32 s70, s28, s72
	s_add_i32 s75, 0, 0x14000
	v_add_u32_e32 v132, s74, v242
	v_add_u32_e32 v144, s75, v242
	ds_read_b128 v[148:151], v132
	ds_read_b128 v[152:155], v132 offset:1024
	ds_read_b128 v[156:159], v132 offset:2048
	ds_read_b128 v[160:163], v132 offset:3072
	ds_read_b128 v[132:135], v144
	ds_read_b128 v[136:139], v144 offset:1024
	ds_read_b128 v[140:143], v144 offset:2048
	ds_read_b128 v[144:147], v144 offset:3072
	s_add_i32 m0, s52, 0xc000
	s_add_u32 s72, s14, s40
	s_addc_u32 s73, s15, s41
	ds_read_b128 v[164:167], v244
	ds_read_b128 v[168:171], v244 offset:1024
	ds_read_b128 v[172:175], v244 offset:2048
	ds_read_b128 v[176:179], v244 offset:3072
	ds_read_b128 v[180:183], v244 offset:4096
	ds_read_b128 v[184:187], v244 offset:5120
	ds_read_b128 v[188:191], v244 offset:6144
	ds_read_b128 v[192:195], v244 offset:7168
	global_load_lds_dwordx4 v206, s[72:73]
	s_add_i32 m0, s52, 0xe000
	s_nop 0
	global_load_lds_dwordx4 v210, s[72:73]
	s_waitcnt vmcnt(8)
	s_waitcnt lgkmcnt(0)
	s_barrier
	s_setprio 1
	v_mfma_f32_16x16x32_bf16 v[124:127], v[148:151], v[164:167], v[124:127]
	v_mfma_f32_16x16x32_bf16 v[120:123], v[156:159], v[164:167], v[120:123]
	v_mfma_f32_16x16x32_bf16 v[112:115], v[148:151], v[172:175], v[112:115]
	v_mfma_f32_16x16x32_bf16 v[104:107], v[156:159], v[172:175], v[104:107]
	v_mfma_f32_16x16x32_bf16 v[96:99], v[148:151], v[180:183], v[96:99]
	v_mfma_f32_16x16x32_bf16 v[88:91], v[156:159], v[180:183], v[88:91]
	v_mfma_f32_16x16x32_bf16 v[80:83], v[148:151], v[188:191], v[80:83]
	v_mfma_f32_16x16x32_bf16 v[72:75], v[156:159], v[188:191], v[72:75]
	v_mfma_f32_16x16x32_bf16 v[124:127], v[152:155], v[168:171], v[124:127]
	v_mfma_f32_16x16x32_bf16 v[120:123], v[160:163], v[168:171], v[120:123]
	v_mfma_f32_16x16x32_bf16 v[112:115], v[152:155], v[176:179], v[112:115]
	v_mfma_f32_16x16x32_bf16 v[104:107], v[160:163], v[176:179], v[104:107]
	v_mfma_f32_16x16x32_bf16 v[96:99], v[152:155], v[184:187], v[96:99]
	v_mfma_f32_16x16x32_bf16 v[88:91], v[160:163], v[184:187], v[88:91]
	v_mfma_f32_16x16x32_bf16 v[80:83], v[152:155], v[192:195], v[80:83]
	v_mfma_f32_16x16x32_bf16 v[72:75], v[160:163], v[192:195], v[72:75]
	v_mfma_f32_16x16x32_bf16 v[128:131], v[132:135], v[164:167], v[128:131]
	v_mfma_f32_16x16x32_bf16 v[116:119], v[140:143], v[164:167], v[116:119]
	v_mfma_f32_16x16x32_bf16 v[108:111], v[132:135], v[172:175], v[108:111]
	v_mfma_f32_16x16x32_bf16 v[100:103], v[140:143], v[172:175], v[100:103]
	v_mfma_f32_16x16x32_bf16 v[92:95], v[132:135], v[180:183], v[92:95]
	v_mfma_f32_16x16x32_bf16 v[84:87], v[140:143], v[180:183], v[84:87]
	v_mfma_f32_16x16x32_bf16 v[76:79], v[132:135], v[188:191], v[76:79]
	v_mfma_f32_16x16x32_bf16 v[68:71], v[140:143], v[188:191], v[68:71]
	v_mfma_f32_16x16x32_bf16 v[128:131], v[136:139], v[168:171], v[128:131]
	v_mfma_f32_16x16x32_bf16 v[116:119], v[144:147], v[168:171], v[116:119]
	v_mfma_f32_16x16x32_bf16 v[108:111], v[136:139], v[176:179], v[108:111]
	v_mfma_f32_16x16x32_bf16 v[100:103], v[144:147], v[176:179], v[100:103]
	v_mfma_f32_16x16x32_bf16 v[92:95], v[136:139], v[184:187], v[92:95]
	v_mfma_f32_16x16x32_bf16 v[84:87], v[144:147], v[184:187], v[84:87]
	v_mfma_f32_16x16x32_bf16 v[76:79], v[136:139], v[192:195], v[76:79]
	v_mfma_f32_16x16x32_bf16 v[68:71], v[144:147], v[192:195], v[68:71]
	s_setprio 0
	s_barrier
	s_add_i32 s72, s74, s51
	v_lshl_add_u64 v[216:217], s[70:71], 0, v[0:1]
	s_mov_b32 m0, s72
	ds_read_b128 v[188:191], v244 offset:16384
	ds_read_b128 v[192:195], v244 offset:17408
	ds_read_b128 v[180:183], v244 offset:18432
	ds_read_b128 v[184:187], v244 offset:19456
	ds_read_b128 v[172:175], v244 offset:20480
	ds_read_b128 v[176:179], v244 offset:21504
	ds_read_b128 v[164:167], v244 offset:22528
	ds_read_b128 v[168:171], v244 offset:23552
	global_load_lds_dwordx4 v[216:217], off
	s_add_i32 m0, s72, 0x2000
	v_lshl_add_u64 v[218:219], s[70:71], 0, v[202:203]
	s_add_u32 s70, s70, s6
	s_addc_u32 s71, s71, s7
	s_add_i32 s72, s75, s51
	global_load_lds_dwordx4 v[218:219], off
	v_lshl_add_u64 v[220:221], s[70:71], 0, v[0:1]
	s_mov_b32 m0, s72
	v_lshl_add_u64 v[222:223], s[70:71], 0, v[202:203]
	global_load_lds_dwordx4 v[220:221], off
	s_add_i32 m0, s72, 0x2000
	s_and_b64 s[70:71], s[36:37], s[42:43]
	global_load_lds_dwordx4 v[222:223], off
	s_andn2_b64 vcc, exec, s[70:71]
	s_cbranch_vccnz .LBB0_1314
	ds_read_b32 v196, v245
	ds_read_b32 v197, v245 offset:512
	ds_read_b32 v198, v246
	s_waitcnt lgkmcnt(0)
	v_min_u32_e32 v196, 0x41ff, v196
	v_mul_lo_u32 v196, v196, s2
	v_add_lshl_u32 v204, v196, v3, 1
	ds_read_b32 v196, v246 offset:512
	v_min_u32_e32 v197, 0x41ff, v197
	v_mul_lo_u32 v197, v197, s2
	v_add_lshl_u32 v206, v197, v3, 1
	v_min_u32_e32 v197, 0x41ff, v198
	s_waitcnt lgkmcnt(0)
	v_min_u32_e32 v196, 0x41ff, v196
	v_mul_lo_u32 v197, v197, s2
	v_mul_lo_u32 v196, v196, s2
	v_add_lshl_u32 v208, v197, v200, 1
	v_add_lshl_u32 v210, v196, v200, 1
	s_branch .LBB0_1314

; #define PG8_GOFFS(slot_) do { _Pragma("unroll") for (int _i = 0; _i < 2; ++_i) { int R, C; stage_rc(tid * 16 + _i * 8192, R, C); _Pragma("unroll") for (int _h = 0; _h < 2; ++_h) { \
;         unsigned t_ = gtab[(slot_) * 256 + R + 128 * _h]; t_ = t_ < (unsigned)(T - 1) ? t_ : (unsigned)(T - 1); voffA[_h][_i] = (t_ * (unsigned)K + (unsigned)C) * 2u; } } } while (0)
; #define PG8_STAGE(bufoff, gbase, voff) do { _Pragma("unroll") for (int _i = 0; _i < 2; ++_i) \
;         __builtin_amdgcn_global_load_lds((const unsigned*)((const char*)(gbase) + (voff)[_i]), (LAS unsigned*)(lds + (bufoff) + ldsw + _i * 8192), 16, 0, 0); } while (0)
; #define PG8_STAGE_A1(bufoff, gbase) do { if (Epi::GATHER) PG8_STAGE(bufoff, gbase, voffA[1]); else PG8_STAGE(bufoff, (gbase) + hstep, voffA[0]); } while (0)
; #define PG8_LDA(dst, b, h) do { _Pragma("unroll") for (int m = 0; m < 4; ++m) _Pragma("unroll") for (int k = 0; k < 2; ++k) dst[m][k] = *(const LAS bf16x8*)(lds + PG8_SA(b, h) + aoff + m * 2048 + k * 1024); } while (0)
; template <class Epi, class Sched>
; __device__ __forceinline__ void gemm_phase(const int tid, LAS unsigned char* lds, const bf16* Aop, const bf16* Bop, const int K_, const Sched& S, const Epi& E, const bf16* Aop1 = nullptr, const bf16* Bop1 = nullptr) {
;     ...
;     f32x4 acc[2][2][4][2];
; #pragma unroll
;     for (int a = 0; a < 2; ++a)
; #pragma unroll
;         for (int b = 0; b < 2; ++b)
; #pragma unroll
;             for (int m = 0; m < 4; ++m)
; #pragma unroll
;                 for (int n = 0; n < 2; ++n) acc[a][b][m][n] = (f32x4){0.f, 0.f, 0.f, 0.f};
;     ...
;         for (int t = 0; t < nt; t += 2) {
;             const bool last = (t == nt - 2);
;             const char* a1 = cA + (size_t)(t + 1) * kstep;
;             const char* a2 = last ? nA : cA + (size_t)(t + 2) * kstep; const char* b2 = last ? nB : cB + (size_t)(t + 2) * kstep;
;             const char* a3 = a2 + kstep; const char* b3 = b2 + kstep;
;             PG8_LDB(B0, 0, 0); PG8_LDB(B1, 0, 1); PG8_SCHED; PG8_LDA(At, 0, 0); PG8_STAGE_A1(PG8_SA(1, 1), a1);
;             PG8_WAIT_V(8); PG8_WAIT_L(0); PG8_BAR; PG8_MMA(0, 0, At, B0); PG8_MMA(0, 1, At, B1); PG8_BAR; PG8_SCHED;
;             PG8_LDA(At, 0, 1); PG8_STAGE(PG8_SB(0, 0), b2, voffB); PG8_STAGE(PG8_SB(0, 1), b2 + hstep, voffB); if (Epi::GATHER && last && has_next) PG8_GOFFS((ui + 1) & 1); PG8_STAGE(PG8_SA(0, 0), a2, voffA[0]);
.LBB0_1398:
	v_mov_b32_e32 v127, 0
	s_andn2_b64 vcc, exec, s[16:17]
	s_cbranch_vccnz .LBB0_1401
	s_add_u32 s34, s34, 0x80
	s_addc_u32 s35, s35, 0
	s_add_u32 s65, s36, 0x100
	s_addc_u32 s66, s37, 0
	s_mov_b32 s36, 0
	s_add_i32 s67, s36, 2
	s_add_u32 s68, s34, 0x80
	s_addc_u32 s37, s35, 0
	s_add_i32 s70, 0, 0x10000
	s_cmp_eq_u32 s58, s36
	s_cselect_b32 s37, s27, s37
	s_cselect_b32 s36, s26, s68
	v_add_u32_e32 v147, s70, v144
	s_cselect_b32 s69, s29, s66
	s_cselect_b32 s68, s28, s65
	s_add_i32 s71, 0, 0x14000
	ds_read_b128 v[148:151], v147
	ds_read_b128 v[152:155], v147 offset:1024
	ds_read_b128 v[156:159], v147 offset:2048
	ds_read_b128 v[160:163], v147 offset:3072
	v_add_u32_e32 v147, s71, v144
	ds_read_b128 v[164:167], v147
	ds_read_b128 v[168:171], v147 offset:1024
	ds_read_b128 v[172:175], v147 offset:2048
	ds_read_b128 v[176:179], v147 offset:3072
	v_lshl_add_u64 v[196:197], s[34:35], 0, v[140:141]
	s_add_i32 m0, s51, 0xc000
	ds_read_b128 v[180:183], v146
	ds_read_b128 v[184:187], v146 offset:1024
	ds_read_b128 v[188:191], v146 offset:2048
	ds_read_b128 v[192:195], v146 offset:3072
	ds_read_b128 v[202:205], v146 offset:4096
	ds_read_b128 v[206:209], v146 offset:5120
	ds_read_b128 v[210:213], v146 offset:6144
	ds_read_b128 v[214:217], v146 offset:7168
	global_load_lds_dwordx4 v[196:197], off
	v_lshl_add_u64 v[196:197], s[34:35], 0, v[142:143]
	s_add_i32 m0, s51, 0xe000
	s_nop 0
	global_load_lds_dwordx4 v[196:197], off
	s_waitcnt vmcnt(8)
	s_waitcnt lgkmcnt(0)
	s_barrier
	s_setprio 1
	v_mfma_f32_16x16x32_bf16 v[124:127], v[148:151], v[180:183], 0
	v_mfma_f32_16x16x32_bf16 v[128:131], v[156:159], v[180:183], 0
	v_mfma_f32_16x16x32_bf16 v[112:115], v[148:151], v[188:191], 0
	v_mfma_f32_16x16x32_bf16 v[108:111], v[156:159], v[188:191], 0
	v_mfma_f32_16x16x32_bf16 v[96:99], v[148:151], v[202:205], 0
	v_mfma_f32_16x16x32_bf16 v[92:95], v[156:159], v[202:205], 0
	v_mfma_f32_16x16x32_bf16 v[80:83], v[148:151], v[210:213], 0
	v_mfma_f32_16x16x32_bf16 v[76:79], v[156:159], v[210:213], 0
	v_mfma_f32_16x16x32_bf16 v[124:127], v[152:155], v[184:187], v[124:127]
	v_mfma_f32_16x16x32_bf16 v[128:131], v[160:163], v[184:187], v[128:131]
	v_mfma_f32_16x16x32_bf16 v[112:115], v[152:155], v[192:195], v[112:115]
	v_mfma_f32_16x16x32_bf16 v[108:111], v[160:163], v[192:195], v[108:111]
	v_mfma_f32_16x16x32_bf16 v[96:99], v[152:155], v[206:209], v[96:99]
	v_mfma_f32_16x16x32_bf16 v[92:95], v[160:163], v[206:209], v[92:95]
	v_mfma_f32_16x16x32_bf16 v[80:83], v[152:155], v[214:217], v[80:83]
	v_mfma_f32_16x16x32_bf16 v[76:79], v[160:163], v[214:217], v[76:79]
	v_mfma_f32_16x16x32_bf16 v[120:123], v[164:167], v[180:183], 0
	v_mfma_f32_16x16x32_bf16 v[116:119], v[172:175], v[180:183], 0
	v_mfma_f32_16x16x32_bf16 v[104:107], v[164:167], v[188:191], 0
	v_mfma_f32_16x16x32_bf16 v[100:103], v[172:175], v[188:191], 0
	v_mfma_f32_16x16x32_bf16 v[88:91], v[164:167], v[202:205], 0
	v_mfma_f32_16x16x32_bf16 v[84:87], v[172:175], v[202:205], 0
	v_mfma_f32_16x16x32_bf16 v[72:75], v[164:167], v[210:213], 0
	v_mfma_f32_16x16x32_bf16 v[68:71], v[172:175], v[210:213], 0
	v_mfma_f32_16x16x32_bf16 v[120:123], v[168:171], v[184:187], v[120:123]
	v_mfma_f32_16x16x32_bf16 v[116:119], v[176:179], v[184:187], v[116:119]
	v_mfma_f32_16x16x32_bf16 v[104:107], v[168:171], v[192:195], v[104:107]
	v_mfma_f32_16x16x32_bf16 v[100:103], v[176:179], v[192:195], v[100:103]
	v_mfma_f32_16x16x32_bf16 v[88:91], v[168:171], v[206:209], v[88:91]
	v_mfma_f32_16x16x32_bf16 v[84:87], v[176:179], v[206:209], v[84:87]
	v_mfma_f32_16x16x32_bf16 v[72:75], v[168:171], v[214:217], v[72:75]
	v_mfma_f32_16x16x32_bf16 v[68:71], v[176:179], v[214:217], v[68:71]
	s_setprio 0
	s_barrier
	s_add_i32 s70, s70, s50
	v_lshl_add_u64 v[196:197], s[68:69], 0, v[134:135]
	s_mov_b32 m0, s70
	ds_read_b128 v[180:183], v146 offset:16384
	ds_read_b128 v[184:187], v146 offset:17408
	ds_read_b128 v[188:191], v146 offset:18432
	ds_read_b128 v[192:195], v146 offset:19456
	ds_read_b128 v[202:205], v146 offset:20480
	ds_read_b128 v[206:209], v146 offset:21504
	ds_read_b128 v[210:213], v146 offset:22528
	ds_read_b128 v[214:217], v146 offset:23552
	global_load_lds_dwordx4 v[196:197], off
	s_add_i32 m0, s70, 0x2000
	v_lshl_add_u64 v[198:199], s[68:69], 0, v[0:1]
	s_add_u32 s68, s68, s6
	s_addc_u32 s69, s69, s7
	s_add_i32 s70, s71, s50
	global_load_lds_dwordx4 v[198:199], off
	v_lshl_add_u64 v[218:219], s[68:69], 0, v[134:135]
	s_mov_b32 m0, s70
	v_lshl_add_u64 v[220:221], s[68:69], 0, v[0:1]
	global_load_lds_dwordx4 v[218:219], off
	s_add_i32 m0, s70, 0x2000
	v_lshl_add_u64 v[222:223], s[36:37], 0, v[136:137]
	global_load_lds_dwordx4 v[220:221], off
	s_mov_b32 m0, s51
	v_lshl_add_u64 v[224:225], s[36:37], 0, v[132:133]
	global_load_lds_dwordx4 v[222:223], off
	s_mov_b32 m0, s52
	s_nop 0
	global_load_lds_dwordx4 v[224:225], off
	s_waitcnt vmcnt(8)
	s_waitcnt lgkmcnt(0)
	s_barrier
; #define PG8_STAGE_A1(bufoff, gbase) do { if (Epi::GATHER) PG8_STAGE(bufoff, gbase, voffA[1]); else PG8_STAGE(bufoff, (gbase) + hstep, voffA[0]); } while (0)
; #define PG8_LDA(dst, b, h) do { _Pragma("unroll") for (int m = 0; m < 4; ++m) _Pragma("unroll") for (int k = 0; k < 2; ++k) dst[m][k] = *(const LAS bf16x8*)(lds + PG8_SA(b, h) + aoff + m * 2048 + k * 1024); } while (0)
; #define PG8_LDB(dst, b, h) do { _Pragma("unroll") for (int n = 0; n < 2; ++n) _Pragma("unroll") for (int k = 0; k < 2; ++k) dst[n][k] = *(const LAS bf16x8*)(lds + PG8_SB(b, h) + boff + n * 2048 + k * 1024); } while (0)
; #define PG8_MMA(ai, bj, At, Bt) do { __builtin_amdgcn_s_setprio(1); _Pragma("unroll") for (int m = 0; m < 4; ++m) _Pragma("unroll") for (int n = 0; n < 2; ++n) _Pragma("unroll") for (int k = 0; k < 2; ++k) \
;         acc[ai][bj][m][n] = __builtin_amdgcn_mfma_f32_16x16x32_bf16(Bt[n][k], At[m][k], acc[ai][bj][m][n], 0, 0, 0); __builtin_amdgcn_s_setprio(0); } while (0)
; #define PG8_WAIT_V(n) asm volatile("s_waitcnt vmcnt(" #n ")" ::: "memory")
; #define PG8_WAIT_L(n) asm volatile("s_waitcnt lgkmcnt(" #n ")" ::: "memory")
; #define PG8_BAR __builtin_amdgcn_s_barrier()
; #define PG8_SCHED __builtin_amdgcn_sched_barrier(0)
; template <class Epi, class Sched>
; __device__ __forceinline__ void gemm_phase(const int tid, LAS unsigned char* lds, const bf16* Aop, const bf16* Bop, const int K_, const Sched& S, const Epi& E, const bf16* Aop1 = nullptr, const bf16* Bop1 = nullptr) {
;     ...
;             PG8_WAIT_V(8); PG8_WAIT_L(0); PG8_BAR; PG8_MMA(1, 0, At, B0); PG8_MMA(1, 1, At, B1); PG8_BAR; PG8_SCHED;
;             PG8_LDB(B0, 1, 0); PG8_LDB(B1, 1, 1); PG8_SCHED; PG8_LDA(At, 1, 0); PG8_STAGE_A1(PG8_SA(0, 1), a2);
;             PG8_WAIT_V(8); PG8_WAIT_L(0); PG8_BAR; PG8_MMA(0, 0, At, B0); PG8_MMA(0, 1, At, B1); PG8_BAR; PG8_SCHED;
	s_setprio 1
	v_mfma_f32_16x16x32_bf16 v[64:67], v[148:151], v[180:183], 0
	v_mfma_f32_16x16x32_bf16 v[60:63], v[156:159], v[180:183], 0
	v_mfma_f32_16x16x32_bf16 v[48:51], v[148:151], v[188:191], 0
	v_mfma_f32_16x16x32_bf16 v[44:47], v[156:159], v[188:191], 0
	v_mfma_f32_16x16x32_bf16 v[32:35], v[148:151], v[202:205], 0
	v_mfma_f32_16x16x32_bf16 v[28:31], v[156:159], v[202:205], 0
	v_mfma_f32_16x16x32_bf16 v[16:19], v[148:151], v[210:213], 0
	v_mfma_f32_16x16x32_bf16 v[12:15], v[156:159], v[210:213], 0
	v_mfma_f32_16x16x32_bf16 v[64:67], v[152:155], v[184:187], v[64:67]
	v_mfma_f32_16x16x32_bf16 v[60:63], v[160:163], v[184:187], v[60:63]
	v_mfma_f32_16x16x32_bf16 v[48:51], v[152:155], v[192:195], v[48:51]
	v_mfma_f32_16x16x32_bf16 v[44:47], v[160:163], v[192:195], v[44:47]
	v_mfma_f32_16x16x32_bf16 v[32:35], v[152:155], v[206:209], v[32:35]
	v_mfma_f32_16x16x32_bf16 v[28:31], v[160:163], v[206:209], v[28:31]
	v_mfma_f32_16x16x32_bf16 v[16:19], v[152:155], v[214:217], v[16:19]
	v_mfma_f32_16x16x32_bf16 v[12:15], v[160:163], v[214:217], v[12:15]
	v_mfma_f32_16x16x32_bf16 v[56:59], v[164:167], v[180:183], 0
	v_mfma_f32_16x16x32_bf16 v[52:55], v[172:175], v[180:183], 0
	v_mfma_f32_16x16x32_bf16 v[40:43], v[164:167], v[188:191], 0
	v_mfma_f32_16x16x32_bf16 v[36:39], v[172:175], v[188:191], 0
	v_mfma_f32_16x16x32_bf16 v[24:27], v[164:167], v[202:205], 0
	v_mfma_f32_16x16x32_bf16 v[20:23], v[172:175], v[202:205], 0
	v_mfma_f32_16x16x32_bf16 v[8:11], v[164:167], v[210:213], 0
	v_mfma_f32_16x16x32_bf16 v[4:7], v[172:175], v[210:213], 0
	v_mfma_f32_16x16x32_bf16 v[56:59], v[168:171], v[184:187], v[56:59]
	v_mfma_f32_16x16x32_bf16 v[52:55], v[176:179], v[184:187], v[52:55]
	v_mfma_f32_16x16x32_bf16 v[40:43], v[168:171], v[192:195], v[40:43]
	v_mfma_f32_16x16x32_bf16 v[36:39], v[176:179], v[192:195], v[36:39]
	v_mfma_f32_16x16x32_bf16 v[24:27], v[168:171], v[206:209], v[24:27]
	v_mfma_f32_16x16x32_bf16 v[20:23], v[176:179], v[206:209], v[20:23]
	v_mfma_f32_16x16x32_bf16 v[8:11], v[168:171], v[214:217], v[8:11]
	v_mfma_f32_16x16x32_bf16 v[4:7], v[176:179], v[214:217], v[4:7]
	s_setprio 0
	s_barrier
	s_add_i32 s68, 0, 0x18000
	v_add_u32_e32 v147, s68, v144
	s_add_i32 s69, 0, 0x1c000
	ds_read_b128 v[148:151], v147
	ds_read_b128 v[152:155], v147 offset:1024
	ds_read_b128 v[156:159], v147 offset:2048
	ds_read_b128 v[160:163], v147 offset:3072
	v_add_u32_e32 v147, s69, v144
	ds_read_b128 v[164:167], v147
	ds_read_b128 v[168:171], v147 offset:1024
	ds_read_b128 v[172:175], v147 offset:2048
	ds_read_b128 v[176:179], v147 offset:3072
	s_add_u32 s36, s36, s6
	s_addc_u32 s37, s37, s7
	s_mov_b32 m0, s53
	v_lshl_add_u64 v[230:231], s[36:37], 0, v[136:137]
	ds_read_b128 v[180:183], v146 offset:32768
	ds_read_b128 v[184:187], v146 offset:33792
	ds_read_b128 v[188:191], v146 offset:34816
	ds_read_b128 v[192:195], v146 offset:35840
	ds_read_b128 v[202:205], v146 offset:36864
	ds_read_b128 v[206:209], v146 offset:37888
	ds_read_b128 v[210:213], v146 offset:38912
	ds_read_b128 v[214:217], v146 offset:39936
	global_load_lds_dwordx4 v[230:231], off
	v_lshl_add_u64 v[230:231], s[36:37], 0, v[132:133]
	s_mov_b32 m0, s54
	s_nop 0
	global_load_lds_dwordx4 v[230:231], off
	s_waitcnt vmcnt(8)
	s_waitcnt lgkmcnt(0)
	s_barrier
	s_setprio 1
	v_mfma_f32_16x16x32_bf16 v[124:127], v[148:151], v[180:183], v[124:127]
	v_mfma_f32_16x16x32_bf16 v[128:131], v[156:159], v[180:183], v[128:131]
	v_mfma_f32_16x16x32_bf16 v[112:115], v[148:151], v[188:191], v[112:115]
	v_mfma_f32_16x16x32_bf16 v[108:111], v[156:159], v[188:191], v[108:111]
	v_mfma_f32_16x16x32_bf16 v[96:99], v[148:151], v[202:205], v[96:99]
	v_mfma_f32_16x16x32_bf16 v[92:95], v[156:159], v[202:205], v[92:95]
	v_mfma_f32_16x16x32_bf16 v[80:83], v[148:151], v[210:213], v[80:83]
	v_mfma_f32_16x16x32_bf16 v[76:79], v[156:159], v[210:213], v[76:79]
	v_mfma_f32_16x16x32_bf16 v[124:127], v[152:155], v[184:187], v[124:127]
	v_mfma_f32_16x16x32_bf16 v[128:131], v[160:163], v[184:187], v[128:131]
	v_mfma_f32_16x16x32_bf16 v[112:115], v[152:155], v[192:195], v[112:115]
	v_mfma_f32_16x16x32_bf16 v[108:111], v[160:163], v[192:195], v[108:111]
	v_mfma_f32_16x16x32_bf16 v[96:99], v[152:155], v[206:209], v[96:99]
	v_mfma_f32_16x16x32_bf16 v[92:95], v[160:163], v[206:209], v[92:95]
	v_mfma_f32_16x16x32_bf16 v[80:83], v[152:155], v[214:217], v[80:83]
	v_mfma_f32_16x16x32_bf16 v[76:79], v[160:163], v[214:217], v[76:79]
	v_mfma_f32_16x16x32_bf16 v[120:123], v[164:167], v[180:183], v[120:123]
	v_mfma_f32_16x16x32_bf16 v[116:119], v[172:175], v[180:183], v[116:119]
	v_mfma_f32_16x16x32_bf16 v[104:107], v[164:167], v[188:191], v[104:107]
	v_mfma_f32_16x16x32_bf16 v[100:103], v[172:175], v[188:191], v[100:103]
	v_mfma_f32_16x16x32_bf16 v[88:91], v[164:167], v[202:205], v[88:91]
	v_mfma_f32_16x16x32_bf16 v[84:87], v[172:175], v[202:205], v[84:87]
	v_mfma_f32_16x16x32_bf16 v[72:75], v[164:167], v[210:213], v[72:75]
	v_mfma_f32_16x16x32_bf16 v[68:71], v[172:175], v[210:213], v[68:71]
	v_mfma_f32_16x16x32_bf16 v[120:123], v[168:171], v[184:187], v[120:123]
	v_mfma_f32_16x16x32_bf16 v[116:119], v[176:179], v[184:187], v[116:119]
	v_mfma_f32_16x16x32_bf16 v[104:107], v[168:171], v[192:195], v[104:107]
	v_mfma_f32_16x16x32_bf16 v[100:103], v[176:179], v[192:195], v[100:103]
	v_mfma_f32_16x16x32_bf16 v[88:91], v[168:171], v[206:209], v[88:91]
	v_mfma_f32_16x16x32_bf16 v[84:87], v[176:179], v[206:209], v[84:87]
	v_mfma_f32_16x16x32_bf16 v[72:75], v[168:171], v[214:217], v[72:75]
	v_mfma_f32_16x16x32_bf16 v[68:71], v[176:179], v[214:217], v[68:71]
	s_setprio 0
	s_barrier
; #define PG8_GOFFS(slot_) do { _Pragma("unroll") for (int _i = 0; _i < 2; ++_i) { int R, C; stage_rc(tid * 16 + _i * 8192, R, C); _Pragma("unroll") for (int _h = 0; _h < 2; ++_h) { \
;         unsigned t_ = gtab[(slot_) * 256 + R + 128 * _h]; t_ = t_ < (unsigned)(T - 1) ? t_ : (unsigned)(T - 1); voffA[_h][_i] = (t_ * (unsigned)K + (unsigned)C) * 2u; } } } while (0)
; #define PG8_STAGE(bufoff, gbase, voff) do { _Pragma("unroll") for (int _i = 0; _i < 2; ++_i) \
;         __builtin_amdgcn_global_load_lds((const unsigned*)((const char*)(gbase) + (voff)[_i]), (LAS unsigned*)(lds + (bufoff) + ldsw + _i * 8192), 16, 0, 0); } while (0)
; #define PG8_BAR __builtin_amdgcn_s_barrier()
; template <class Epi, class Sched>
; __device__ __forceinline__ void gemm_phase(const int tid, LAS unsigned char* lds, const bf16* Aop, const bf16* Bop, const int K_, const Sched& S, const Epi& E, const bf16* Aop1 = nullptr, const bf16* Bop1 = nullptr) {
;     ...
;         for (int t = 0; t < nt; t += 2) {
;             const bool last = (t == nt - 2);
;             const char* a1 = cA + (size_t)(t + 1) * kstep;
;             const char* a2 = last ? nA : cA + (size_t)(t + 2) * kstep; const char* b2 = last ? nB : cB + (size_t)(t + 2) * kstep;
;             const char* a3 = a2 + kstep; const char* b3 = b2 + kstep;
;             PG8_LDB(B0, 0, 0); PG8_LDB(B1, 0, 1); PG8_SCHED; PG8_LDA(At, 0, 0); PG8_STAGE_A1(PG8_SA(1, 1), a1);
;             PG8_WAIT_V(8); PG8_WAIT_L(0); PG8_BAR; PG8_MMA(0, 0, At, B0); PG8_MMA(0, 1, At, B1); PG8_BAR; PG8_SCHED;
;             PG8_LDA(At, 0, 1); PG8_STAGE(PG8_SB(0, 0), b2, voffB); PG8_STAGE(PG8_SB(0, 1), b2 + hstep, voffB); if (Epi::GATHER && last && has_next) PG8_GOFFS((ui + 1) & 1); PG8_STAGE(PG8_SA(0, 0), a2, voffA[0]);
;             PG8_WAIT_V(8); PG8_WAIT_L(0); PG8_BAR; PG8_MMA(1, 0, At, B0); PG8_MMA(1, 1, At, B1); PG8_BAR; PG8_SCHED;
;             PG8_LDB(B0, 1, 0); PG8_LDB(B1, 1, 1); PG8_SCHED; PG8_LDA(At, 1, 0); PG8_STAGE_A1(PG8_SA(0, 1), a2);
;             PG8_WAIT_V(8); PG8_WAIT_L(0); PG8_BAR; PG8_MMA(0, 0, At, B0); PG8_MMA(0, 1, At, B1); PG8_BAR; PG8_SCHED;
;             PG8_LDA(At, 1, 1); PG8_STAGE(PG8_SB(1, 0), b3, voffB); PG8_STAGE(PG8_SB(1, 1), b3 + hstep, voffB); PG8_STAGE(PG8_SA(1, 0), a3, voffA[0]);
;             PG8_WAIT_V(8); PG8_WAIT_L(0); PG8_BAR; PG8_MMA(1, 0, At, B0); PG8_MMA(1, 1, At, B1); PG8_BAR; PG8_SCHED;
;         }
	s_add_i32 s36, s68, s50
	v_lshl_add_u64 v[196:197], v[196:197], 0, s[20:21]
	s_mov_b32 m0, s36
	ds_read_b128 v[180:183], v146 offset:49152
	ds_read_b128 v[184:187], v146 offset:50176
	ds_read_b128 v[188:191], v146 offset:51200
	ds_read_b128 v[192:195], v146 offset:52224
	ds_read_b128 v[202:205], v146 offset:53248
	ds_read_b128 v[206:209], v146 offset:54272
	ds_read_b128 v[210:213], v146 offset:55296
	ds_read_b128 v[214:217], v146 offset:56320
	global_load_lds_dwordx4 v[196:197], off
	v_lshl_add_u64 v[196:197], v[198:199], 0, s[20:21]
	s_add_i32 m0, s36, 0x2000
	s_add_i32 s36, s69, s50
	global_load_lds_dwordx4 v[196:197], off
	v_lshl_add_u64 v[196:197], v[218:219], 0, s[20:21]
	s_mov_b32 m0, s36
	s_nop 0
	global_load_lds_dwordx4 v[196:197], off
	v_lshl_add_u64 v[196:197], v[220:221], 0, s[20:21]
	s_add_i32 m0, s36, 0x2000
	s_nop 0
	global_load_lds_dwordx4 v[196:197], off
	v_lshl_add_u64 v[196:197], v[222:223], 0, s[20:21]
	s_mov_b32 m0, s56
	s_nop 0
	global_load_lds_dwordx4 v[196:197], off
	v_lshl_add_u64 v[196:197], v[224:225], 0, s[20:21]
	s_mov_b32 m0, s57
	s_nop 0
	global_load_lds_dwordx4 v[196:197], off
	s_waitcnt vmcnt(8)
	s_waitcnt lgkmcnt(0)
	s_barrier
	s_setprio 1
	v_mfma_f32_16x16x32_bf16 v[64:67], v[148:151], v[180:183], v[64:67]
	v_mfma_f32_16x16x32_bf16 v[60:63], v[156:159], v[180:183], v[60:63]
	v_mfma_f32_16x16x32_bf16 v[48:51], v[148:151], v[188:191], v[48:51]
	v_mfma_f32_16x16x32_bf16 v[44:47], v[156:159], v[188:191], v[44:47]
	v_mfma_f32_16x16x32_bf16 v[32:35], v[148:151], v[202:205], v[32:35]
	v_mfma_f32_16x16x32_bf16 v[28:31], v[156:159], v[202:205], v[28:31]
	v_mfma_f32_16x16x32_bf16 v[16:19], v[148:151], v[210:213], v[16:19]
	v_mfma_f32_16x16x32_bf16 v[12:15], v[156:159], v[210:213], v[12:15]
	v_mfma_f32_16x16x32_bf16 v[64:67], v[152:155], v[184:187], v[64:67]
	v_mfma_f32_16x16x32_bf16 v[60:63], v[160:163], v[184:187], v[60:63]
	v_mfma_f32_16x16x32_bf16 v[48:51], v[152:155], v[192:195], v[48:51]
	v_mfma_f32_16x16x32_bf16 v[44:47], v[160:163], v[192:195], v[44:47]
	v_mfma_f32_16x16x32_bf16 v[32:35], v[152:155], v[206:209], v[32:35]
	v_mfma_f32_16x16x32_bf16 v[28:31], v[160:163], v[206:209], v[28:31]
	v_mfma_f32_16x16x32_bf16 v[16:19], v[152:155], v[214:217], v[16:19]
	v_mfma_f32_16x16x32_bf16 v[12:15], v[160:163], v[214:217], v[12:15]
	v_mfma_f32_16x16x32_bf16 v[56:59], v[164:167], v[180:183], v[56:59]
	v_mfma_f32_16x16x32_bf16 v[52:55], v[172:175], v[180:183], v[52:55]
	v_mfma_f32_16x16x32_bf16 v[40:43], v[164:167], v[188:191], v[40:43]
	v_mfma_f32_16x16x32_bf16 v[36:39], v[172:175], v[188:191], v[36:39]
	v_mfma_f32_16x16x32_bf16 v[24:27], v[164:167], v[202:205], v[24:27]
	v_mfma_f32_16x16x32_bf16 v[20:23], v[172:175], v[202:205], v[20:23]
	v_mfma_f32_16x16x32_bf16 v[8:11], v[164:167], v[210:213], v[8:11]
	v_mfma_f32_16x16x32_bf16 v[4:7], v[172:175], v[210:213], v[4:7]
	v_mfma_f32_16x16x32_bf16 v[56:59], v[168:171], v[184:187], v[56:59]
	v_mfma_f32_16x16x32_bf16 v[52:55], v[176:179], v[184:187], v[52:55]
	v_mfma_f32_16x16x32_bf16 v[40:43], v[168:171], v[192:195], v[40:43]
	v_mfma_f32_16x16x32_bf16 v[36:39], v[176:179], v[192:195], v[36:39]
	v_mfma_f32_16x16x32_bf16 v[24:27], v[168:171], v[206:209], v[24:27]
	v_mfma_f32_16x16x32_bf16 v[20:23], v[176:179], v[206:209], v[20:23]
	v_mfma_f32_16x16x32_bf16 v[8:11], v[168:171], v[214:217], v[8:11]
	v_mfma_f32_16x16x32_bf16 v[4:7], v[176:179], v[214:217], v[4:7]
	s_setprio 0
	s_barrier
	s_add_u32 s34, s34, 0x100
	s_addc_u32 s35, s35, 0
	s_add_u32 s65, s65, 0x100
	s_addc_u32 s66, s66, 0
	s_cmp_ge_i32 s67, s55
	s_mov_b32 s36, s67
	s_cbranch_scc0 .LBB0_1400
	s_branch .LBB0_1401
.LBB0_1400:
	s_add_i32 s67, s36, 2
	s_add_u32 s68, s34, 0x80
	s_addc_u32 s37, s35, 0
	s_add_i32 s70, 0, 0x10000
	s_cmp_eq_u32 s58, s36
	s_cselect_b32 s37, s27, s37
	s_cselect_b32 s36, s26, s68
	v_add_u32_e32 v147, s70, v144
	s_cselect_b32 s69, s29, s66
	s_cselect_b32 s68, s28, s65
	s_add_i32 s71, 0, 0x14000
	ds_read_b128 v[148:151], v147
	ds_read_b128 v[152:155], v147 offset:1024
	ds_read_b128 v[156:159], v147 offset:2048
	ds_read_b128 v[160:163], v147 offset:3072
	v_add_u32_e32 v147, s71, v144
	ds_read_b128 v[164:167], v147
	ds_read_b128 v[168:171], v147 offset:1024
	ds_read_b128 v[172:175], v147 offset:2048
	ds_read_b128 v[176:179], v147 offset:3072
	v_lshl_add_u64 v[196:197], s[34:35], 0, v[140:141]
	s_add_i32 m0, s51, 0xc000
	ds_read_b128 v[180:183], v146
	ds_read_b128 v[184:187], v146 offset:1024
	ds_read_b128 v[188:191], v146 offset:2048
	ds_read_b128 v[192:195], v146 offset:3072
	ds_read_b128 v[202:205], v146 offset:4096
	ds_read_b128 v[206:209], v146 offset:5120
	ds_read_b128 v[210:213], v146 offset:6144
	ds_read_b128 v[214:217], v146 offset:7168
	global_load_lds_dwordx4 v[196:197], off
	v_lshl_add_u64 v[196:197], s[34:35], 0, v[142:143]
	s_add_i32 m0, s51, 0xe000
	s_nop 0
	global_load_lds_dwordx4 v[196:197], off
	s_waitcnt vmcnt(8)
	s_waitcnt lgkmcnt(0)
	s_barrier
; #define PG8_GOFFS(slot_) do { _Pragma("unroll") for (int _i = 0; _i < 2; ++_i) { int R, C; stage_rc(tid * 16 + _i * 8192, R, C); _Pragma("unroll") for (int _h = 0; _h < 2; ++_h) { \
;         unsigned t_ = gtab[(slot_) * 256 + R + 128 * _h]; t_ = t_ < (unsigned)(T - 1) ? t_ : (unsigned)(T - 1); voffA[_h][_i] = (t_ * (unsigned)K + (unsigned)C) * 2u; } } } while (0)
; #define PG8_STAGE(bufoff, gbase, voff) do { _Pragma("unroll") for (int _i = 0; _i < 2; ++_i) \
;         __builtin_amdgcn_global_load_lds((const unsigned*)((const char*)(gbase) + (voff)[_i]), (LAS unsigned*)(lds + (bufoff) + ldsw + _i * 8192), 16, 0, 0); } while (0)
; #define PG8_LDA(dst, b, h) do { _Pragma("unroll") for (int m = 0; m < 4; ++m) _Pragma("unroll") for (int k = 0; k < 2; ++k) dst[m][k] = *(const LAS bf16x8*)(lds + PG8_SA(b, h) + aoff + m * 2048 + k * 1024); } while (0)
; #define PG8_MMA(ai, bj, At, Bt) do { __builtin_amdgcn_s_setprio(1); _Pragma("unroll") for (int m = 0; m < 4; ++m) _Pragma("unroll") for (int n = 0; n < 2; ++n) _Pragma("unroll") for (int k = 0; k < 2; ++k) \
;         acc[ai][bj][m][n] = __builtin_amdgcn_mfma_f32_16x16x32_bf16(Bt[n][k], At[m][k], acc[ai][bj][m][n], 0, 0, 0); __builtin_amdgcn_s_setprio(0); } while (0)
; #define PG8_WAIT_V(n) asm volatile("s_waitcnt vmcnt(" #n ")" ::: "memory")
; #define PG8_WAIT_L(n) asm volatile("s_waitcnt lgkmcnt(" #n ")" ::: "memory")
; #define PG8_BAR __builtin_amdgcn_s_barrier()
; #define PG8_SCHED __builtin_amdgcn_sched_barrier(0)
; template <class Epi, class Sched>
; __device__ __forceinline__ void gemm_phase(const int tid, LAS unsigned char* lds, const bf16* Aop, const bf16* Bop, const int K_, const Sched& S, const Epi& E, const bf16* Aop1 = nullptr, const bf16* Bop1 = nullptr) {
;     ...
;             PG8_WAIT_V(8); PG8_WAIT_L(0); PG8_BAR; PG8_MMA(0, 0, At, B0); PG8_MMA(0, 1, At, B1); PG8_BAR; PG8_SCHED;
;             PG8_LDA(At, 0, 1); PG8_STAGE(PG8_SB(0, 0), b2, voffB); PG8_STAGE(PG8_SB(0, 1), b2 + hstep, voffB); if (Epi::GATHER && last && has_next) PG8_GOFFS((ui + 1) & 1); PG8_STAGE(PG8_SA(0, 0), a2, voffA[0]);
;             PG8_WAIT_V(8); PG8_WAIT_L(0); PG8_BAR; PG8_MMA(1, 0, At, B0); PG8_MMA(1, 1, At, B1); PG8_BAR; PG8_SCHED;
	s_setprio 1
	v_mfma_f32_16x16x32_bf16 v[124:127], v[148:151], v[180:183], v[124:127]
	v_mfma_f32_16x16x32_bf16 v[128:131], v[156:159], v[180:183], v[128:131]
	v_mfma_f32_16x16x32_bf16 v[112:115], v[148:151], v[188:191], v[112:115]
	v_mfma_f32_16x16x32_bf16 v[108:111], v[156:159], v[188:191], v[108:111]
	v_mfma_f32_16x16x32_bf16 v[96:99], v[148:151], v[202:205], v[96:99]
	v_mfma_f32_16x16x32_bf16 v[92:95], v[156:159], v[202:205], v[92:95]
	v_mfma_f32_16x16x32_bf16 v[80:83], v[148:151], v[210:213], v[80:83]
	v_mfma_f32_16x16x32_bf16 v[76:79], v[156:159], v[210:213], v[76:79]
	v_mfma_f32_16x16x32_bf16 v[124:127], v[152:155], v[184:187], v[124:127]
	v_mfma_f32_16x16x32_bf16 v[128:131], v[160:163], v[184:187], v[128:131]
	v_mfma_f32_16x16x32_bf16 v[112:115], v[152:155], v[192:195], v[112:115]
	v_mfma_f32_16x16x32_bf16 v[108:111], v[160:163], v[192:195], v[108:111]
	v_mfma_f32_16x16x32_bf16 v[96:99], v[152:155], v[206:209], v[96:99]
	v_mfma_f32_16x16x32_bf16 v[92:95], v[160:163], v[206:209], v[92:95]
	v_mfma_f32_16x16x32_bf16 v[80:83], v[152:155], v[214:217], v[80:83]
	v_mfma_f32_16x16x32_bf16 v[76:79], v[160:163], v[214:217], v[76:79]
	v_mfma_f32_16x16x32_bf16 v[120:123], v[164:167], v[180:183], v[120:123]
	v_mfma_f32_16x16x32_bf16 v[116:119], v[172:175], v[180:183], v[116:119]
	v_mfma_f32_16x16x32_bf16 v[104:107], v[164:167], v[188:191], v[104:107]
	v_mfma_f32_16x16x32_bf16 v[100:103], v[172:175], v[188:191], v[100:103]
	v_mfma_f32_16x16x32_bf16 v[88:91], v[164:167], v[202:205], v[88:91]
	v_mfma_f32_16x16x32_bf16 v[84:87], v[172:175], v[202:205], v[84:87]
	v_mfma_f32_16x16x32_bf16 v[72:75], v[164:167], v[210:213], v[72:75]
	v_mfma_f32_16x16x32_bf16 v[68:71], v[172:175], v[210:213], v[68:71]
	v_mfma_f32_16x16x32_bf16 v[120:123], v[168:171], v[184:187], v[120:123]
	v_mfma_f32_16x16x32_bf16 v[116:119], v[176:179], v[184:187], v[116:119]
	v_mfma_f32_16x16x32_bf16 v[104:107], v[168:171], v[192:195], v[104:107]
	v_mfma_f32_16x16x32_bf16 v[100:103], v[176:179], v[192:195], v[100:103]
	v_mfma_f32_16x16x32_bf16 v[88:91], v[168:171], v[206:209], v[88:91]
	v_mfma_f32_16x16x32_bf16 v[84:87], v[176:179], v[206:209], v[84:87]
	v_mfma_f32_16x16x32_bf16 v[72:75], v[168:171], v[214:217], v[72:75]
	v_mfma_f32_16x16x32_bf16 v[68:71], v[176:179], v[214:217], v[68:71]
	s_setprio 0
	s_barrier
	s_add_i32 s70, s70, s50
	v_lshl_add_u64 v[196:197], s[68:69], 0, v[134:135]
	s_mov_b32 m0, s70
	ds_read_b128 v[180:183], v146 offset:16384
	ds_read_b128 v[184:187], v146 offset:17408
	ds_read_b128 v[188:191], v146 offset:18432
	ds_read_b128 v[192:195], v146 offset:19456
	ds_read_b128 v[202:205], v146 offset:20480
	ds_read_b128 v[206:209], v146 offset:21504
	ds_read_b128 v[210:213], v146 offset:22528
	ds_read_b128 v[214:217], v146 offset:23552
	global_load_lds_dwordx4 v[196:197], off
	s_add_i32 m0, s70, 0x2000
	v_lshl_add_u64 v[198:199], s[68:69], 0, v[0:1]
	s_add_u32 s68, s68, s6
	s_addc_u32 s69, s69, s7
	s_add_i32 s70, s71, s50
	global_load_lds_dwordx4 v[198:199], off
	v_lshl_add_u64 v[218:219], s[68:69], 0, v[134:135]
	s_mov_b32 m0, s70
	v_lshl_add_u64 v[220:221], s[68:69], 0, v[0:1]
	global_load_lds_dwordx4 v[218:219], off
	s_add_i32 m0, s70, 0x2000
	v_lshl_add_u64 v[222:223], s[36:37], 0, v[136:137]
	global_load_lds_dwordx4 v[220:221], off
	s_mov_b32 m0, s51
	v_lshl_add_u64 v[224:225], s[36:37], 0, v[132:133]
	global_load_lds_dwordx4 v[222:223], off
	s_mov_b32 m0, s52
	s_nop 0
	global_load_lds_dwordx4 v[224:225], off
	s_waitcnt vmcnt(8)
	s_waitcnt lgkmcnt(0)
	s_barrier
	s_setprio 1
	v_mfma_f32_16x16x32_bf16 v[64:67], v[148:151], v[180:183], v[64:67]
	v_mfma_f32_16x16x32_bf16 v[60:63], v[156:159], v[180:183], v[60:63]
	v_mfma_f32_16x16x32_bf16 v[48:51], v[148:151], v[188:191], v[48:51]
	v_mfma_f32_16x16x32_bf16 v[44:47], v[156:159], v[188:191], v[44:47]
	v_mfma_f32_16x16x32_bf16 v[32:35], v[148:151], v[202:205], v[32:35]
	v_mfma_f32_16x16x32_bf16 v[28:31], v[156:159], v[202:205], v[28:31]
	v_mfma_f32_16x16x32_bf16 v[16:19], v[148:151], v[210:213], v[16:19]
	v_mfma_f32_16x16x32_bf16 v[12:15], v[156:159], v[210:213], v[12:15]
	v_mfma_f32_16x16x32_bf16 v[64:67], v[152:155], v[184:187], v[64:67]
	v_mfma_f32_16x16x32_bf16 v[60:63], v[160:163], v[184:187], v[60:63]
	v_mfma_f32_16x16x32_bf16 v[48:51], v[152:155], v[192:195], v[48:51]
	v_mfma_f32_16x16x32_bf16 v[44:47], v[160:163], v[192:195], v[44:47]
	v_mfma_f32_16x16x32_bf16 v[32:35], v[152:155], v[206:209], v[32:35]
	v_mfma_f32_16x16x32_bf16 v[28:31], v[160:163], v[206:209], v[28:31]
	v_mfma_f32_16x16x32_bf16 v[16:19], v[152:155], v[214:217], v[16:19]
	v_mfma_f32_16x16x32_bf16 v[12:15], v[160:163], v[214:217], v[12:15]
	v_mfma_f32_16x16x32_bf16 v[56:59], v[164:167], v[180:183], v[56:59]
	v_mfma_f32_16x16x32_bf16 v[52:55], v[172:175], v[180:183], v[52:55]
	v_mfma_f32_16x16x32_bf16 v[40:43], v[164:167], v[188:191], v[40:43]
	v_mfma_f32_16x16x32_bf16 v[36:39], v[172:175], v[188:191], v[36:39]
	v_mfma_f32_16x16x32_bf16 v[24:27], v[164:167], v[202:205], v[24:27]
	v_mfma_f32_16x16x32_bf16 v[20:23], v[172:175], v[202:205], v[20:23]
	v_mfma_f32_16x16x32_bf16 v[8:11], v[164:167], v[210:213], v[8:11]
	v_mfma_f32_16x16x32_bf16 v[4:7], v[172:175], v[210:213], v[4:7]
	v_mfma_f32_16x16x32_bf16 v[56:59], v[168:171], v[184:187], v[56:59]
	v_mfma_f32_16x16x32_bf16 v[52:55], v[176:179], v[184:187], v[52:55]
	v_mfma_f32_16x16x32_bf16 v[40:43], v[168:171], v[192:195], v[40:43]
	v_mfma_f32_16x16x32_bf16 v[36:39], v[176:179], v[192:195], v[36:39]
	v_mfma_f32_16x16x32_bf16 v[24:27], v[168:171], v[206:209], v[24:27]
	v_mfma_f32_16x16x32_bf16 v[20:23], v[176:179], v[206:209], v[20:23]
	v_mfma_f32_16x16x32_bf16 v[8:11], v[168:171], v[214:217], v[8:11]
	v_mfma_f32_16x16x32_bf16 v[4:7], v[176:179], v[214:217], v[4:7]
	s_setprio 0
	s_barrier
; #define PG8_STAGE(bufoff, gbase, voff) do { _Pragma("unroll") for (int _i = 0; _i < 2; ++_i) \
;         __builtin_amdgcn_global_load_lds((const unsigned*)((const char*)(gbase) + (voff)[_i]), (LAS unsigned*)(lds + (bufoff) + ldsw + _i * 8192), 16, 0, 0); } while (0)
; #define PG8_STAGE_A1(bufoff, gbase) do { if (Epi::GATHER) PG8_STAGE(bufoff, gbase, voffA[1]); else PG8_STAGE(bufoff, (gbase) + hstep, voffA[0]); } while (0)
; #define PG8_LDA(dst, b, h) do { _Pragma("unroll") for (int m = 0; m < 4; ++m) _Pragma("unroll") for (int k = 0; k < 2; ++k) dst[m][k] = *(const LAS bf16x8*)(lds + PG8_SA(b, h) + aoff + m * 2048 + k * 1024); } while (0)
; #define PG8_LDB(dst, b, h) do { _Pragma("unroll") for (int n = 0; n < 2; ++n) _Pragma("unroll") for (int k = 0; k < 2; ++k) dst[n][k] = *(const LAS bf16x8*)(lds + PG8_SB(b, h) + boff + n * 2048 + k * 1024); } while (0)
; #define PG8_MMA(ai, bj, At, Bt) do { __builtin_amdgcn_s_setprio(1); _Pragma("unroll") for (int m = 0; m < 4; ++m) _Pragma("unroll") for (int n = 0; n < 2; ++n) _Pragma("unroll") for (int k = 0; k < 2; ++k) \
;         acc[ai][bj][m][n] = __builtin_amdgcn_mfma_f32_16x16x32_bf16(Bt[n][k], At[m][k], acc[ai][bj][m][n], 0, 0, 0); __builtin_amdgcn_s_setprio(0); } while (0)
; #define PG8_WAIT_V(n) asm volatile("s_waitcnt vmcnt(" #n ")" ::: "memory")
; #define PG8_WAIT_L(n) asm volatile("s_waitcnt lgkmcnt(" #n ")" ::: "memory")
; #define PG8_BAR __builtin_amdgcn_s_barrier()
; #define PG8_SCHED __builtin_amdgcn_sched_barrier(0)
; template <class Epi, class Sched>
; __device__ __forceinline__ void gemm_phase(const int tid, LAS unsigned char* lds, const bf16* Aop, const bf16* Bop, const int K_, const Sched& S, const Epi& E, const bf16* Aop1 = nullptr, const bf16* Bop1 = nullptr) {
;     ...
;             PG8_LDB(B0, 1, 0); PG8_LDB(B1, 1, 1); PG8_SCHED; PG8_LDA(At, 1, 0); PG8_STAGE_A1(PG8_SA(0, 1), a2);
;             PG8_WAIT_V(8); PG8_WAIT_L(0); PG8_BAR; PG8_MMA(0, 0, At, B0); PG8_MMA(0, 1, At, B1); PG8_BAR; PG8_SCHED;
;             PG8_LDA(At, 1, 1); PG8_STAGE(PG8_SB(1, 0), b3, voffB); PG8_STAGE(PG8_SB(1, 1), b3 + hstep, voffB); PG8_STAGE(PG8_SA(1, 0), a3, voffA[0]);
;             PG8_WAIT_V(8); PG8_WAIT_L(0); PG8_BAR; PG8_MMA(1, 0, At, B0); PG8_MMA(1, 1, At, B1); PG8_BAR; PG8_SCHED;
;         }
	s_add_i32 s68, 0, 0x18000
	v_add_u32_e32 v147, s68, v144
	s_add_i32 s69, 0, 0x1c000
	ds_read_b128 v[148:151], v147
	ds_read_b128 v[152:155], v147 offset:1024
	ds_read_b128 v[156:159], v147 offset:2048
	ds_read_b128 v[160:163], v147 offset:3072
	v_add_u32_e32 v147, s69, v144
	ds_read_b128 v[164:167], v147
	ds_read_b128 v[168:171], v147 offset:1024
	ds_read_b128 v[172:175], v147 offset:2048
	ds_read_b128 v[176:179], v147 offset:3072
	s_add_u32 s36, s36, s6
	s_addc_u32 s37, s37, s7
	s_mov_b32 m0, s53
	v_lshl_add_u64 v[230:231], s[36:37], 0, v[136:137]
	ds_read_b128 v[180:183], v146 offset:32768
	ds_read_b128 v[184:187], v146 offset:33792
	ds_read_b128 v[188:191], v146 offset:34816
	ds_read_b128 v[192:195], v146 offset:35840
	ds_read_b128 v[202:205], v146 offset:36864
	ds_read_b128 v[206:209], v146 offset:37888
	ds_read_b128 v[210:213], v146 offset:38912
	ds_read_b128 v[214:217], v146 offset:39936
	global_load_lds_dwordx4 v[230:231], off
	v_lshl_add_u64 v[230:231], s[36:37], 0, v[132:133]
	s_mov_b32 m0, s54
	s_nop 0
	global_load_lds_dwordx4 v[230:231], off
	s_waitcnt vmcnt(8)
	s_waitcnt lgkmcnt(0)
	s_barrier
	s_setprio 1
	v_mfma_f32_16x16x32_bf16 v[124:127], v[148:151], v[180:183], v[124:127]
	v_mfma_f32_16x16x32_bf16 v[128:131], v[156:159], v[180:183], v[128:131]
	v_mfma_f32_16x16x32_bf16 v[112:115], v[148:151], v[188:191], v[112:115]
	v_mfma_f32_16x16x32_bf16 v[108:111], v[156:159], v[188:191], v[108:111]
	v_mfma_f32_16x16x32_bf16 v[96:99], v[148:151], v[202:205], v[96:99]
	v_mfma_f32_16x16x32_bf16 v[92:95], v[156:159], v[202:205], v[92:95]
	v_mfma_f32_16x16x32_bf16 v[80:83], v[148:151], v[210:213], v[80:83]
	v_mfma_f32_16x16x32_bf16 v[76:79], v[156:159], v[210:213], v[76:79]
	v_mfma_f32_16x16x32_bf16 v[124:127], v[152:155], v[184:187], v[124:127]
	v_mfma_f32_16x16x32_bf16 v[128:131], v[160:163], v[184:187], v[128:131]
	v_mfma_f32_16x16x32_bf16 v[112:115], v[152:155], v[192:195], v[112:115]
	v_mfma_f32_16x16x32_bf16 v[108:111], v[160:163], v[192:195], v[108:111]
	v_mfma_f32_16x16x32_bf16 v[96:99], v[152:155], v[206:209], v[96:99]
	v_mfma_f32_16x16x32_bf16 v[92:95], v[160:163], v[206:209], v[92:95]
	v_mfma_f32_16x16x32_bf16 v[80:83], v[152:155], v[214:217], v[80:83]
	v_mfma_f32_16x16x32_bf16 v[76:79], v[160:163], v[214:217], v[76:79]
	v_mfma_f32_16x16x32_bf16 v[120:123], v[164:167], v[180:183], v[120:123]
	v_mfma_f32_16x16x32_bf16 v[116:119], v[172:175], v[180:183], v[116:119]
	v_mfma_f32_16x16x32_bf16 v[104:107], v[164:167], v[188:191], v[104:107]
	v_mfma_f32_16x16x32_bf16 v[100:103], v[172:175], v[188:191], v[100:103]
	v_mfma_f32_16x16x32_bf16 v[88:91], v[164:167], v[202:205], v[88:91]
	v_mfma_f32_16x16x32_bf16 v[84:87], v[172:175], v[202:205], v[84:87]
	v_mfma_f32_16x16x32_bf16 v[72:75], v[164:167], v[210:213], v[72:75]
	v_mfma_f32_16x16x32_bf16 v[68:71], v[172:175], v[210:213], v[68:71]
	v_mfma_f32_16x16x32_bf16 v[120:123], v[168:171], v[184:187], v[120:123]
	v_mfma_f32_16x16x32_bf16 v[116:119], v[176:179], v[184:187], v[116:119]
	v_mfma_f32_16x16x32_bf16 v[104:107], v[168:171], v[192:195], v[104:107]
	v_mfma_f32_16x16x32_bf16 v[100:103], v[176:179], v[192:195], v[100:103]
	v_mfma_f32_16x16x32_bf16 v[88:91], v[168:171], v[206:209], v[88:91]
	v_mfma_f32_16x16x32_bf16 v[84:87], v[176:179], v[206:209], v[84:87]
	v_mfma_f32_16x16x32_bf16 v[72:75], v[168:171], v[214:217], v[72:75]
	v_mfma_f32_16x16x32_bf16 v[68:71], v[176:179], v[214:217], v[68:71]
	s_setprio 0
	s_barrier
	s_add_i32 s36, s68, s50
	v_lshl_add_u64 v[196:197], v[196:197], 0, s[20:21]
	s_mov_b32 m0, s36
	ds_read_b128 v[180:183], v146 offset:49152
	ds_read_b128 v[184:187], v146 offset:50176
	ds_read_b128 v[188:191], v146 offset:51200
	ds_read_b128 v[192:195], v146 offset:52224
	ds_read_b128 v[202:205], v146 offset:53248
	ds_read_b128 v[206:209], v146 offset:54272
	ds_read_b128 v[210:213], v146 offset:55296
	ds_read_b128 v[214:217], v146 offset:56320
	global_load_lds_dwordx4 v[196:197], off
	v_lshl_add_u64 v[196:197], v[198:199], 0, s[20:21]
	s_add_i32 m0, s36, 0x2000
	s_add_i32 s36, s69, s50
	global_load_lds_dwordx4 v[196:197], off
	v_lshl_add_u64 v[196:197], v[218:219], 0, s[20:21]
	s_mov_b32 m0, s36
	s_nop 0
	global_load_lds_dwordx4 v[196:197], off
	v_lshl_add_u64 v[196:197], v[220:221], 0, s[20:21]
	s_add_i32 m0, s36, 0x2000
	s_nop 0
	global_load_lds_dwordx4 v[196:197], off
	v_lshl_add_u64 v[196:197], v[222:223], 0, s[20:21]
	s_mov_b32 m0, s56
	s_nop 0
	global_load_lds_dwordx4 v[196:197], off
	v_lshl_add_u64 v[196:197], v[224:225], 0, s[20:21]
	s_mov_b32 m0, s57
	s_nop 0
	global_load_lds_dwordx4 v[196:197], off
	s_waitcnt vmcnt(8)
	s_waitcnt lgkmcnt(0)
	s_barrier
	s_setprio 1
	v_mfma_f32_16x16x32_bf16 v[64:67], v[148:151], v[180:183], v[64:67]
	v_mfma_f32_16x16x32_bf16 v[60:63], v[156:159], v[180:183], v[60:63]
	v_mfma_f32_16x16x32_bf16 v[48:51], v[148:151], v[188:191], v[48:51]
	v_mfma_f32_16x16x32_bf16 v[44:47], v[156:159], v[188:191], v[44:47]
	v_mfma_f32_16x16x32_bf16 v[32:35], v[148:151], v[202:205], v[32:35]
	v_mfma_f32_16x16x32_bf16 v[28:31], v[156:159], v[202:205], v[28:31]
	v_mfma_f32_16x16x32_bf16 v[16:19], v[148:151], v[210:213], v[16:19]
	v_mfma_f32_16x16x32_bf16 v[12:15], v[156:159], v[210:213], v[12:15]
	v_mfma_f32_16x16x32_bf16 v[64:67], v[152:155], v[184:187], v[64:67]
	v_mfma_f32_16x16x32_bf16 v[60:63], v[160:163], v[184:187], v[60:63]
	v_mfma_f32_16x16x32_bf16 v[48:51], v[152:155], v[192:195], v[48:51]
	v_mfma_f32_16x16x32_bf16 v[44:47], v[160:163], v[192:195], v[44:47]
	v_mfma_f32_16x16x32_bf16 v[32:35], v[152:155], v[206:209], v[32:35]
	v_mfma_f32_16x16x32_bf16 v[28:31], v[160:163], v[206:209], v[28:31]
	v_mfma_f32_16x16x32_bf16 v[16:19], v[152:155], v[214:217], v[16:19]
	v_mfma_f32_16x16x32_bf16 v[12:15], v[160:163], v[214:217], v[12:15]
	v_mfma_f32_16x16x32_bf16 v[56:59], v[164:167], v[180:183], v[56:59]
	v_mfma_f32_16x16x32_bf16 v[52:55], v[172:175], v[180:183], v[52:55]
	v_mfma_f32_16x16x32_bf16 v[40:43], v[164:167], v[188:191], v[40:43]
	v_mfma_f32_16x16x32_bf16 v[36:39], v[172:175], v[188:191], v[36:39]
	v_mfma_f32_16x16x32_bf16 v[24:27], v[164:167], v[202:205], v[24:27]
	v_mfma_f32_16x16x32_bf16 v[20:23], v[172:175], v[202:205], v[20:23]
	v_mfma_f32_16x16x32_bf16 v[8:11], v[164:167], v[210:213], v[8:11]
	v_mfma_f32_16x16x32_bf16 v[4:7], v[172:175], v[210:213], v[4:7]
	v_mfma_f32_16x16x32_bf16 v[56:59], v[168:171], v[184:187], v[56:59]
	v_mfma_f32_16x16x32_bf16 v[52:55], v[176:179], v[184:187], v[52:55]
	v_mfma_f32_16x16x32_bf16 v[40:43], v[168:171], v[192:195], v[40:43]
	v_mfma_f32_16x16x32_bf16 v[36:39], v[176:179], v[192:195], v[36:39]
	v_mfma_f32_16x16x32_bf16 v[24:27], v[168:171], v[206:209], v[24:27]
	v_mfma_f32_16x16x32_bf16 v[20:23], v[176:179], v[206:209], v[20:23]
	v_mfma_f32_16x16x32_bf16 v[8:11], v[168:171], v[214:217], v[8:11]
	v_mfma_f32_16x16x32_bf16 v[4:7], v[176:179], v[214:217], v[4:7]
	s_setprio 0
	s_barrier
	s_add_u32 s34, s34, 0x100
	s_addc_u32 s35, s35, 0
	s_add_u32 s65, s65, 0x100
	s_addc_u32 s66, s66, 0
	s_cmp_ge_i32 s67, s55
	s_mov_b32 s36, s67
	s_cbranch_scc0 .LBB0_1400

; #define PG8_GOFFS(slot_) do { _Pragma("unroll") for (int _i = 0; _i < 2; ++_i) { int R, C; stage_rc(tid * 16 + _i * 8192, R, C); _Pragma("unroll") for (int _h = 0; _h < 2; ++_h) { \
;         unsigned t_ = gtab[(slot_) * 256 + R + 128 * _h]; t_ = t_ < (unsigned)(T - 1) ? t_ : (unsigned)(T - 1); voffA[_h][_i] = (t_ * (unsigned)K + (unsigned)C) * 2u; } } } while (0)
; #define PG8_STAGE(bufoff, gbase, voff) do { _Pragma("unroll") for (int _i = 0; _i < 2; ++_i) \
;         __builtin_amdgcn_global_load_lds((const unsigned*)((const char*)(gbase) + (voff)[_i]), (LAS unsigned*)(lds + (bufoff) + ldsw + _i * 8192), 16, 0, 0); } while (0)
; #define PG8_STAGE_A1(bufoff, gbase) do { if (Epi::GATHER) PG8_STAGE(bufoff, gbase, voffA[1]); else PG8_STAGE(bufoff, (gbase) + hstep, voffA[0]); } while (0)
; #define PG8_LDA(dst, b, h) do { _Pragma("unroll") for (int m = 0; m < 4; ++m) _Pragma("unroll") for (int k = 0; k < 2; ++k) dst[m][k] = *(const LAS bf16x8*)(lds + PG8_SA(b, h) + aoff + m * 2048 + k * 1024); } while (0)
; template <class Epi, class Sched>
; __device__ __forceinline__ void gemm_phase(const int tid, LAS unsigned char* lds, const bf16* Aop, const bf16* Bop, const int K_, const Sched& S, const Epi& E, const bf16* Aop1 = nullptr, const bf16* Bop1 = nullptr) {
;     ...
;     f32x4 acc[2][2][4][2];
; #pragma unroll
;     for (int a = 0; a < 2; ++a)
; #pragma unroll
;         for (int b = 0; b < 2; ++b)
; #pragma unroll
;             for (int m = 0; m < 4; ++m)
; #pragma unroll
;                 for (int n = 0; n < 2; ++n) acc[a][b][m][n] = (f32x4){0.f, 0.f, 0.f, 0.f};
;     ...
;         for (int t = 0; t < nt; t += 2) {
;             const bool last = (t == nt - 2);
;             const char* a1 = cA + (size_t)(t + 1) * kstep;
;             const char* a2 = last ? nA : cA + (size_t)(t + 2) * kstep; const char* b2 = last ? nB : cB + (size_t)(t + 2) * kstep;
;             const char* a3 = a2 + kstep; const char* b3 = b2 + kstep;
;             PG8_LDB(B0, 0, 0); PG8_LDB(B1, 0, 1); PG8_SCHED; PG8_LDA(At, 0, 0); PG8_STAGE_A1(PG8_SA(1, 1), a1);
;             PG8_WAIT_V(8); PG8_WAIT_L(0); PG8_BAR; PG8_MMA(0, 0, At, B0); PG8_MMA(0, 1, At, B1); PG8_BAR; PG8_SCHED;
;             PG8_LDA(At, 0, 1); PG8_STAGE(PG8_SB(0, 0), b2, voffB); PG8_STAGE(PG8_SB(0, 1), b2 + hstep, voffB); if (Epi::GATHER && last && has_next) PG8_GOFFS((ui + 1) & 1); PG8_STAGE(PG8_SA(0, 0), a2, voffA[0]);
.LBB0_1418:
	v_mov_b32_e32 v127, 0
	s_andn2_b64 vcc, exec, s[16:17]
	s_cbranch_vccnz .LBB0_1421
	s_add_u32 s34, s34, 0x80
	s_addc_u32 s35, s35, 0
	s_add_u32 s15, s36, 0x100
	s_addc_u32 s67, s37, 0
	s_mov_b32 s36, 0
	s_add_i32 s68, s36, 2
	s_add_u32 s69, s34, 0x80
	s_addc_u32 s37, s35, 0
	s_add_i32 s72, 0, 0x10000
	s_cmp_eq_u32 s61, s36
	s_cselect_b32 s37, s27, s37
	s_cselect_b32 s36, s26, s69
	s_cselect_b32 s71, s29, s67
	s_cselect_b32 s70, s28, s15
	s_add_i32 s69, 0, 0x14000
	v_add_u32_e32 v158, s72, v3
	v_add_u32_e32 v174, s69, v3
	ds_read_b128 v[146:149], v158
	ds_read_b128 v[150:153], v158 offset:1024
	ds_read_b128 v[154:157], v158 offset:2048
	ds_read_b128 v[158:161], v158 offset:3072
	ds_read_b128 v[162:165], v174
	ds_read_b128 v[166:169], v174 offset:1024
	ds_read_b128 v[170:173], v174 offset:2048
	ds_read_b128 v[174:177], v174 offset:3072
	v_lshl_add_u64 v[194:195], s[34:35], 0, v[140:141]
	s_add_i32 m0, s53, 0xc000
	ds_read_b128 v[178:181], v144
	ds_read_b128 v[182:185], v144 offset:1024
	ds_read_b128 v[186:189], v144 offset:2048
	ds_read_b128 v[190:193], v144 offset:3072
	ds_read_b128 v[202:205], v144 offset:4096
	ds_read_b128 v[206:209], v144 offset:5120
	ds_read_b128 v[210:213], v144 offset:6144
	ds_read_b128 v[214:217], v144 offset:7168
	global_load_lds_dwordx4 v[194:195], off
	v_lshl_add_u64 v[194:195], s[34:35], 0, v[142:143]
	s_add_i32 m0, s53, 0xe000
	s_nop 0
	global_load_lds_dwordx4 v[194:195], off
	s_waitcnt vmcnt(8)
	s_waitcnt lgkmcnt(0)
	s_barrier
	s_setprio 1
	v_mfma_f32_16x16x32_bf16 v[124:127], v[146:149], v[178:181], 0
	v_mfma_f32_16x16x32_bf16 v[128:131], v[154:157], v[178:181], 0
	v_mfma_f32_16x16x32_bf16 v[112:115], v[146:149], v[186:189], 0
	v_mfma_f32_16x16x32_bf16 v[108:111], v[154:157], v[186:189], 0
	v_mfma_f32_16x16x32_bf16 v[96:99], v[146:149], v[202:205], 0
	v_mfma_f32_16x16x32_bf16 v[92:95], v[154:157], v[202:205], 0
	v_mfma_f32_16x16x32_bf16 v[80:83], v[146:149], v[210:213], 0
	v_mfma_f32_16x16x32_bf16 v[76:79], v[154:157], v[210:213], 0
	v_mfma_f32_16x16x32_bf16 v[124:127], v[150:153], v[182:185], v[124:127]
	v_mfma_f32_16x16x32_bf16 v[128:131], v[158:161], v[182:185], v[128:131]
	v_mfma_f32_16x16x32_bf16 v[112:115], v[150:153], v[190:193], v[112:115]
	v_mfma_f32_16x16x32_bf16 v[108:111], v[158:161], v[190:193], v[108:111]
	v_mfma_f32_16x16x32_bf16 v[96:99], v[150:153], v[206:209], v[96:99]
	v_mfma_f32_16x16x32_bf16 v[92:95], v[158:161], v[206:209], v[92:95]
	v_mfma_f32_16x16x32_bf16 v[80:83], v[150:153], v[214:217], v[80:83]
	v_mfma_f32_16x16x32_bf16 v[76:79], v[158:161], v[214:217], v[76:79]
	v_mfma_f32_16x16x32_bf16 v[120:123], v[162:165], v[178:181], 0
	v_mfma_f32_16x16x32_bf16 v[116:119], v[170:173], v[178:181], 0
	v_mfma_f32_16x16x32_bf16 v[104:107], v[162:165], v[186:189], 0
	v_mfma_f32_16x16x32_bf16 v[100:103], v[170:173], v[186:189], 0
	v_mfma_f32_16x16x32_bf16 v[88:91], v[162:165], v[202:205], 0
	v_mfma_f32_16x16x32_bf16 v[84:87], v[170:173], v[202:205], 0
	v_mfma_f32_16x16x32_bf16 v[72:75], v[162:165], v[210:213], 0
	v_mfma_f32_16x16x32_bf16 v[68:71], v[170:173], v[210:213], 0
	v_mfma_f32_16x16x32_bf16 v[120:123], v[166:169], v[182:185], v[120:123]
	v_mfma_f32_16x16x32_bf16 v[116:119], v[174:177], v[182:185], v[116:119]
	v_mfma_f32_16x16x32_bf16 v[104:107], v[166:169], v[190:193], v[104:107]
	v_mfma_f32_16x16x32_bf16 v[100:103], v[174:177], v[190:193], v[100:103]
	v_mfma_f32_16x16x32_bf16 v[88:91], v[166:169], v[206:209], v[88:91]
	v_mfma_f32_16x16x32_bf16 v[84:87], v[174:177], v[206:209], v[84:87]
	v_mfma_f32_16x16x32_bf16 v[72:75], v[166:169], v[214:217], v[72:75]
	v_mfma_f32_16x16x32_bf16 v[68:71], v[174:177], v[214:217], v[68:71]
	s_setprio 0
	s_barrier
	s_add_i32 s72, s72, s52
	v_lshl_add_u64 v[194:195], s[70:71], 0, v[134:135]
	s_mov_b32 m0, s72
	ds_read_b128 v[178:181], v144 offset:16384
	ds_read_b128 v[182:185], v144 offset:17408
	ds_read_b128 v[186:189], v144 offset:18432
	ds_read_b128 v[190:193], v144 offset:19456
	ds_read_b128 v[202:205], v144 offset:20480
	ds_read_b128 v[206:209], v144 offset:21504
	ds_read_b128 v[210:213], v144 offset:22528
	ds_read_b128 v[214:217], v144 offset:23552
	global_load_lds_dwordx4 v[194:195], off
	s_add_i32 m0, s72, 0x2000
	v_lshl_add_u64 v[196:197], s[70:71], 0, v[0:1]
	s_add_u32 s70, s70, s6
	s_addc_u32 s71, s71, s7
	s_add_i32 s69, s69, s52
	global_load_lds_dwordx4 v[196:197], off
	v_lshl_add_u64 v[198:199], s[70:71], 0, v[134:135]
	s_mov_b32 m0, s69
	v_lshl_add_u64 v[218:219], s[70:71], 0, v[0:1]
	global_load_lds_dwordx4 v[198:199], off
	s_add_i32 m0, s69, 0x2000
	v_lshl_add_u64 v[220:221], s[36:37], 0, v[136:137]
	global_load_lds_dwordx4 v[218:219], off
	s_mov_b32 m0, s53
	v_lshl_add_u64 v[222:223], s[36:37], 0, v[132:133]
	global_load_lds_dwordx4 v[220:221], off
	s_mov_b32 m0, s54
	s_nop 0
	global_load_lds_dwordx4 v[222:223], off
	s_waitcnt vmcnt(8)
	s_waitcnt lgkmcnt(0)
	s_barrier
; #define PG8_GOFFS(slot_) do { _Pragma("unroll") for (int _i = 0; _i < 2; ++_i) { int R, C; stage_rc(tid * 16 + _i * 8192, R, C); _Pragma("unroll") for (int _h = 0; _h < 2; ++_h) { \
;         unsigned t_ = gtab[(slot_) * 256 + R + 128 * _h]; t_ = t_ < (unsigned)(T - 1) ? t_ : (unsigned)(T - 1); voffA[_h][_i] = (t_ * (unsigned)K + (unsigned)C) * 2u; } } } while (0)
; #define PG8_STAGE(bufoff, gbase, voff) do { _Pragma("unroll") for (int _i = 0; _i < 2; ++_i) \
;         __builtin_amdgcn_global_load_lds((const unsigned*)((const char*)(gbase) + (voff)[_i]), (LAS unsigned*)(lds + (bufoff) + ldsw + _i * 8192), 16, 0, 0); } while (0)
; #define PG8_STAGE_A1(bufoff, gbase) do { if (Epi::GATHER) PG8_STAGE(bufoff, gbase, voffA[1]); else PG8_STAGE(bufoff, (gbase) + hstep, voffA[0]); } while (0)
; #define PG8_LDA(dst, b, h) do { _Pragma("unroll") for (int m = 0; m < 4; ++m) _Pragma("unroll") for (int k = 0; k < 2; ++k) dst[m][k] = *(const LAS bf16x8*)(lds + PG8_SA(b, h) + aoff + m * 2048 + k * 1024); } while (0)
; #define PG8_LDB(dst, b, h) do { _Pragma("unroll") for (int n = 0; n < 2; ++n) _Pragma("unroll") for (int k = 0; k < 2; ++k) dst[n][k] = *(const LAS bf16x8*)(lds + PG8_SB(b, h) + boff + n * 2048 + k * 1024); } while (0)
; #define PG8_WAIT_V(n) asm volatile("s_waitcnt vmcnt(" #n ")" ::: "memory")
; #define PG8_WAIT_L(n) asm volatile("s_waitcnt lgkmcnt(" #n ")" ::: "memory")
; #define PG8_BAR __builtin_amdgcn_s_barrier()
; #define PG8_SCHED __builtin_amdgcn_sched_barrier(0)
; template <class Epi, class Sched>
; __device__ __forceinline__ void gemm_phase(const int tid, LAS unsigned char* lds, const bf16* Aop, const bf16* Bop, const int K_, const Sched& S, const Epi& E, const bf16* Aop1 = nullptr, const bf16* Bop1 = nullptr) {
;     ...
;             PG8_LDA(At, 0, 1); PG8_STAGE(PG8_SB(0, 0), b2, voffB); PG8_STAGE(PG8_SB(0, 1), b2 + hstep, voffB); if (Epi::GATHER && last && has_next) PG8_GOFFS((ui + 1) & 1); PG8_STAGE(PG8_SA(0, 0), a2, voffA[0]);
;             PG8_WAIT_V(8); PG8_WAIT_L(0); PG8_BAR; PG8_MMA(1, 0, At, B0); PG8_MMA(1, 1, At, B1); PG8_BAR; PG8_SCHED;
;             PG8_LDB(B0, 1, 0); PG8_LDB(B1, 1, 1); PG8_SCHED; PG8_LDA(At, 1, 0); PG8_STAGE_A1(PG8_SA(0, 1), a2);
;             PG8_WAIT_V(8); PG8_WAIT_L(0); PG8_BAR; PG8_MMA(0, 0, At, B0); PG8_MMA(0, 1, At, B1); PG8_BAR; PG8_SCHED;
	s_setprio 1
	v_mfma_f32_16x16x32_bf16 v[64:67], v[146:149], v[178:181], 0
	v_mfma_f32_16x16x32_bf16 v[60:63], v[154:157], v[178:181], 0
	v_mfma_f32_16x16x32_bf16 v[48:51], v[146:149], v[186:189], 0
	v_mfma_f32_16x16x32_bf16 v[44:47], v[154:157], v[186:189], 0
	v_mfma_f32_16x16x32_bf16 v[32:35], v[146:149], v[202:205], 0
	v_mfma_f32_16x16x32_bf16 v[28:31], v[154:157], v[202:205], 0
	v_mfma_f32_16x16x32_bf16 v[16:19], v[146:149], v[210:213], 0
	v_mfma_f32_16x16x32_bf16 v[12:15], v[154:157], v[210:213], 0
	v_mfma_f32_16x16x32_bf16 v[64:67], v[150:153], v[182:185], v[64:67]
	v_mfma_f32_16x16x32_bf16 v[60:63], v[158:161], v[182:185], v[60:63]
	v_mfma_f32_16x16x32_bf16 v[48:51], v[150:153], v[190:193], v[48:51]
	v_mfma_f32_16x16x32_bf16 v[44:47], v[158:161], v[190:193], v[44:47]
	v_mfma_f32_16x16x32_bf16 v[32:35], v[150:153], v[206:209], v[32:35]
	v_mfma_f32_16x16x32_bf16 v[28:31], v[158:161], v[206:209], v[28:31]
	v_mfma_f32_16x16x32_bf16 v[16:19], v[150:153], v[214:217], v[16:19]
	v_mfma_f32_16x16x32_bf16 v[12:15], v[158:161], v[214:217], v[12:15]
	v_mfma_f32_16x16x32_bf16 v[56:59], v[162:165], v[178:181], 0
	v_mfma_f32_16x16x32_bf16 v[52:55], v[170:173], v[178:181], 0
	v_mfma_f32_16x16x32_bf16 v[40:43], v[162:165], v[186:189], 0
	v_mfma_f32_16x16x32_bf16 v[36:39], v[170:173], v[186:189], 0
	v_mfma_f32_16x16x32_bf16 v[24:27], v[162:165], v[202:205], 0
	v_mfma_f32_16x16x32_bf16 v[20:23], v[170:173], v[202:205], 0
	v_mfma_f32_16x16x32_bf16 v[8:11], v[162:165], v[210:213], 0
	v_mfma_f32_16x16x32_bf16 v[4:7], v[170:173], v[210:213], 0
	v_mfma_f32_16x16x32_bf16 v[56:59], v[166:169], v[182:185], v[56:59]
	v_mfma_f32_16x16x32_bf16 v[52:55], v[174:177], v[182:185], v[52:55]
	v_mfma_f32_16x16x32_bf16 v[40:43], v[166:169], v[190:193], v[40:43]
	v_mfma_f32_16x16x32_bf16 v[36:39], v[174:177], v[190:193], v[36:39]
	v_mfma_f32_16x16x32_bf16 v[24:27], v[166:169], v[206:209], v[24:27]
	v_mfma_f32_16x16x32_bf16 v[20:23], v[174:177], v[206:209], v[20:23]
	v_mfma_f32_16x16x32_bf16 v[8:11], v[166:169], v[214:217], v[8:11]
	v_mfma_f32_16x16x32_bf16 v[4:7], v[174:177], v[214:217], v[4:7]
	s_setprio 0
	s_barrier
	s_add_i32 s69, 0, 0x18000
	s_add_i32 s70, 0, 0x1c000
	v_add_u32_e32 v158, s69, v3
	v_add_u32_e32 v174, s70, v3
	ds_read_b128 v[146:149], v158
	ds_read_b128 v[150:153], v158 offset:1024
	ds_read_b128 v[154:157], v158 offset:2048
	ds_read_b128 v[158:161], v158 offset:3072
	ds_read_b128 v[162:165], v174
	ds_read_b128 v[166:169], v174 offset:1024
	ds_read_b128 v[170:173], v174 offset:2048
	ds_read_b128 v[174:177], v174 offset:3072
	s_add_u32 s36, s36, s6
	s_addc_u32 s37, s37, s7
	s_mov_b32 m0, s55
	v_lshl_add_u64 v[224:225], s[36:37], 0, v[136:137]
	ds_read_b128 v[178:181], v144 offset:32768
	ds_read_b128 v[182:185], v144 offset:33792
	ds_read_b128 v[186:189], v144 offset:34816
	ds_read_b128 v[190:193], v144 offset:35840
	ds_read_b128 v[202:205], v144 offset:36864
	ds_read_b128 v[206:209], v144 offset:37888
	ds_read_b128 v[210:213], v144 offset:38912
	ds_read_b128 v[214:217], v144 offset:39936
	global_load_lds_dwordx4 v[224:225], off
	v_lshl_add_u64 v[224:225], s[36:37], 0, v[132:133]
	s_mov_b32 m0, s56
	s_nop 0
	global_load_lds_dwordx4 v[224:225], off
	s_waitcnt vmcnt(8)
	s_waitcnt lgkmcnt(0)
	s_barrier
	s_setprio 1
	v_mfma_f32_16x16x32_bf16 v[124:127], v[146:149], v[178:181], v[124:127]
	v_mfma_f32_16x16x32_bf16 v[128:131], v[154:157], v[178:181], v[128:131]
	v_mfma_f32_16x16x32_bf16 v[112:115], v[146:149], v[186:189], v[112:115]
	v_mfma_f32_16x16x32_bf16 v[108:111], v[154:157], v[186:189], v[108:111]
	v_mfma_f32_16x16x32_bf16 v[96:99], v[146:149], v[202:205], v[96:99]
	v_mfma_f32_16x16x32_bf16 v[92:95], v[154:157], v[202:205], v[92:95]
	v_mfma_f32_16x16x32_bf16 v[80:83], v[146:149], v[210:213], v[80:83]
	v_mfma_f32_16x16x32_bf16 v[76:79], v[154:157], v[210:213], v[76:79]
	v_mfma_f32_16x16x32_bf16 v[124:127], v[150:153], v[182:185], v[124:127]
	v_mfma_f32_16x16x32_bf16 v[128:131], v[158:161], v[182:185], v[128:131]
	v_mfma_f32_16x16x32_bf16 v[112:115], v[150:153], v[190:193], v[112:115]
	v_mfma_f32_16x16x32_bf16 v[108:111], v[158:161], v[190:193], v[108:111]
	v_mfma_f32_16x16x32_bf16 v[96:99], v[150:153], v[206:209], v[96:99]
	v_mfma_f32_16x16x32_bf16 v[92:95], v[158:161], v[206:209], v[92:95]
	v_mfma_f32_16x16x32_bf16 v[80:83], v[150:153], v[214:217], v[80:83]
	v_mfma_f32_16x16x32_bf16 v[76:79], v[158:161], v[214:217], v[76:79]
	v_mfma_f32_16x16x32_bf16 v[120:123], v[162:165], v[178:181], v[120:123]
	v_mfma_f32_16x16x32_bf16 v[116:119], v[170:173], v[178:181], v[116:119]
	v_mfma_f32_16x16x32_bf16 v[104:107], v[162:165], v[186:189], v[104:107]
	v_mfma_f32_16x16x32_bf16 v[100:103], v[170:173], v[186:189], v[100:103]
	v_mfma_f32_16x16x32_bf16 v[88:91], v[162:165], v[202:205], v[88:91]
	v_mfma_f32_16x16x32_bf16 v[84:87], v[170:173], v[202:205], v[84:87]
	v_mfma_f32_16x16x32_bf16 v[72:75], v[162:165], v[210:213], v[72:75]
	v_mfma_f32_16x16x32_bf16 v[68:71], v[170:173], v[210:213], v[68:71]
	v_mfma_f32_16x16x32_bf16 v[120:123], v[166:169], v[182:185], v[120:123]
	v_mfma_f32_16x16x32_bf16 v[116:119], v[174:177], v[182:185], v[116:119]
	v_mfma_f32_16x16x32_bf16 v[104:107], v[166:169], v[190:193], v[104:107]
	v_mfma_f32_16x16x32_bf16 v[100:103], v[174:177], v[190:193], v[100:103]
	v_mfma_f32_16x16x32_bf16 v[88:91], v[166:169], v[206:209], v[88:91]
	v_mfma_f32_16x16x32_bf16 v[84:87], v[174:177], v[206:209], v[84:87]
	v_mfma_f32_16x16x32_bf16 v[72:75], v[166:169], v[214:217], v[72:75]
	v_mfma_f32_16x16x32_bf16 v[68:71], v[174:177], v[214:217], v[68:71]
	s_setprio 0
	s_barrier
; #define PG8_GOFFS(slot_) do { _Pragma("unroll") for (int _i = 0; _i < 2; ++_i) { int R, C; stage_rc(tid * 16 + _i * 8192, R, C); _Pragma("unroll") for (int _h = 0; _h < 2; ++_h) { \
;         unsigned t_ = gtab[(slot_) * 256 + R + 128 * _h]; t_ = t_ < (unsigned)(T - 1) ? t_ : (unsigned)(T - 1); voffA[_h][_i] = (t_ * (unsigned)K + (unsigned)C) * 2u; } } } while (0)
; #define PG8_STAGE(bufoff, gbase, voff) do { _Pragma("unroll") for (int _i = 0; _i < 2; ++_i) \
;         __builtin_amdgcn_global_load_lds((const unsigned*)((const char*)(gbase) + (voff)[_i]), (LAS unsigned*)(lds + (bufoff) + ldsw + _i * 8192), 16, 0, 0); } while (0)
; #define PG8_WAIT_V(n) asm volatile("s_waitcnt vmcnt(" #n ")" ::: "memory")
; template <class Epi, class Sched>
; __device__ __forceinline__ void gemm_phase(const int tid, LAS unsigned char* lds, const bf16* Aop, const bf16* Bop, const int K_, const Sched& S, const Epi& E, const bf16* Aop1 = nullptr, const bf16* Bop1 = nullptr) {
;     ...
;         for (int t = 0; t < nt; t += 2) {
;             const bool last = (t == nt - 2);
;             const char* a1 = cA + (size_t)(t + 1) * kstep;
;             const char* a2 = last ? nA : cA + (size_t)(t + 2) * kstep; const char* b2 = last ? nB : cB + (size_t)(t + 2) * kstep;
;             const char* a3 = a2 + kstep; const char* b3 = b2 + kstep;
;             PG8_LDB(B0, 0, 0); PG8_LDB(B1, 0, 1); PG8_SCHED; PG8_LDA(At, 0, 0); PG8_STAGE_A1(PG8_SA(1, 1), a1);
;             PG8_WAIT_V(8); PG8_WAIT_L(0); PG8_BAR; PG8_MMA(0, 0, At, B0); PG8_MMA(0, 1, At, B1); PG8_BAR; PG8_SCHED;
;             PG8_LDA(At, 0, 1); PG8_STAGE(PG8_SB(0, 0), b2, voffB); PG8_STAGE(PG8_SB(0, 1), b2 + hstep, voffB); if (Epi::GATHER && last && has_next) PG8_GOFFS((ui + 1) & 1); PG8_STAGE(PG8_SA(0, 0), a2, voffA[0]);
;             PG8_WAIT_V(8); PG8_WAIT_L(0); PG8_BAR; PG8_MMA(1, 0, At, B0); PG8_MMA(1, 1, At, B1); PG8_BAR; PG8_SCHED;
;             PG8_LDB(B0, 1, 0); PG8_LDB(B1, 1, 1); PG8_SCHED; PG8_LDA(At, 1, 0); PG8_STAGE_A1(PG8_SA(0, 1), a2);
;             PG8_WAIT_V(8); PG8_WAIT_L(0); PG8_BAR; PG8_MMA(0, 0, At, B0); PG8_MMA(0, 1, At, B1); PG8_BAR; PG8_SCHED;
;             PG8_LDA(At, 1, 1); PG8_STAGE(PG8_SB(1, 0), b3, voffB); PG8_STAGE(PG8_SB(1, 1), b3 + hstep, voffB); PG8_STAGE(PG8_SA(1, 0), a3, voffA[0]);
;             PG8_WAIT_V(8); PG8_WAIT_L(0); PG8_BAR; PG8_MMA(1, 0, At, B0); PG8_MMA(1, 1, At, B1); PG8_BAR; PG8_SCHED;
	s_add_i32 s36, s69, s52
	v_lshl_add_u64 v[194:195], v[194:195], 0, s[20:21]
	s_mov_b32 m0, s36
	ds_read_b128 v[178:181], v144 offset:49152
	ds_read_b128 v[182:185], v144 offset:50176
	ds_read_b128 v[186:189], v144 offset:51200
	ds_read_b128 v[190:193], v144 offset:52224
	ds_read_b128 v[202:205], v144 offset:53248
	ds_read_b128 v[206:209], v144 offset:54272
	ds_read_b128 v[210:213], v144 offset:55296
	ds_read_b128 v[214:217], v144 offset:56320
	global_load_lds_dwordx4 v[194:195], off
	v_lshl_add_u64 v[194:195], v[196:197], 0, s[20:21]
	s_add_i32 m0, s36, 0x2000
	s_add_i32 s36, s70, s52
	global_load_lds_dwordx4 v[194:195], off
	v_lshl_add_u64 v[194:195], v[198:199], 0, s[20:21]
	s_mov_b32 m0, s36
	s_nop 0
	global_load_lds_dwordx4 v[194:195], off
	v_lshl_add_u64 v[194:195], v[218:219], 0, s[20:21]
	s_add_i32 m0, s36, 0x2000
	s_nop 0
	global_load_lds_dwordx4 v[194:195], off
	v_lshl_add_u64 v[194:195], v[220:221], 0, s[20:21]
	s_mov_b32 m0, s59
	s_nop 0
	global_load_lds_dwordx4 v[194:195], off
	v_lshl_add_u64 v[194:195], v[222:223], 0, s[20:21]
	s_mov_b32 m0, s60
	s_nop 0
	global_load_lds_dwordx4 v[194:195], off
	s_waitcnt vmcnt(8)
	s_waitcnt lgkmcnt(0)
	s_barrier
	s_setprio 1
	v_mfma_f32_16x16x32_bf16 v[64:67], v[146:149], v[178:181], v[64:67]
	v_mfma_f32_16x16x32_bf16 v[60:63], v[154:157], v[178:181], v[60:63]
	v_mfma_f32_16x16x32_bf16 v[48:51], v[146:149], v[186:189], v[48:51]
	v_mfma_f32_16x16x32_bf16 v[44:47], v[154:157], v[186:189], v[44:47]
	v_mfma_f32_16x16x32_bf16 v[32:35], v[146:149], v[202:205], v[32:35]
	v_mfma_f32_16x16x32_bf16 v[28:31], v[154:157], v[202:205], v[28:31]
	v_mfma_f32_16x16x32_bf16 v[16:19], v[146:149], v[210:213], v[16:19]
	v_mfma_f32_16x16x32_bf16 v[12:15], v[154:157], v[210:213], v[12:15]
	v_mfma_f32_16x16x32_bf16 v[64:67], v[150:153], v[182:185], v[64:67]
	v_mfma_f32_16x16x32_bf16 v[60:63], v[158:161], v[182:185], v[60:63]
	v_mfma_f32_16x16x32_bf16 v[48:51], v[150:153], v[190:193], v[48:51]
	v_mfma_f32_16x16x32_bf16 v[44:47], v[158:161], v[190:193], v[44:47]
	v_mfma_f32_16x16x32_bf16 v[32:35], v[150:153], v[206:209], v[32:35]
	v_mfma_f32_16x16x32_bf16 v[28:31], v[158:161], v[206:209], v[28:31]
	v_mfma_f32_16x16x32_bf16 v[16:19], v[150:153], v[214:217], v[16:19]
	v_mfma_f32_16x16x32_bf16 v[12:15], v[158:161], v[214:217], v[12:15]
	v_mfma_f32_16x16x32_bf16 v[56:59], v[162:165], v[178:181], v[56:59]
	v_mfma_f32_16x16x32_bf16 v[52:55], v[170:173], v[178:181], v[52:55]
	v_mfma_f32_16x16x32_bf16 v[40:43], v[162:165], v[186:189], v[40:43]
	v_mfma_f32_16x16x32_bf16 v[36:39], v[170:173], v[186:189], v[36:39]
	v_mfma_f32_16x16x32_bf16 v[24:27], v[162:165], v[202:205], v[24:27]
	v_mfma_f32_16x16x32_bf16 v[20:23], v[170:173], v[202:205], v[20:23]
	v_mfma_f32_16x16x32_bf16 v[8:11], v[162:165], v[210:213], v[8:11]
	v_mfma_f32_16x16x32_bf16 v[4:7], v[170:173], v[210:213], v[4:7]
	v_mfma_f32_16x16x32_bf16 v[56:59], v[166:169], v[182:185], v[56:59]
	v_mfma_f32_16x16x32_bf16 v[52:55], v[174:177], v[182:185], v[52:55]
	v_mfma_f32_16x16x32_bf16 v[40:43], v[166:169], v[190:193], v[40:43]
	v_mfma_f32_16x16x32_bf16 v[36:39], v[174:177], v[190:193], v[36:39]
	v_mfma_f32_16x16x32_bf16 v[24:27], v[166:169], v[206:209], v[24:27]
	v_mfma_f32_16x16x32_bf16 v[20:23], v[174:177], v[206:209], v[20:23]
	v_mfma_f32_16x16x32_bf16 v[8:11], v[166:169], v[214:217], v[8:11]
	v_mfma_f32_16x16x32_bf16 v[4:7], v[174:177], v[214:217], v[4:7]
	s_setprio 0
	s_barrier
	s_add_u32 s34, s34, 0x100
	s_addc_u32 s35, s35, 0
	s_add_u32 s15, s15, 0x100
	s_addc_u32 s67, s67, 0
	s_cmp_ge_i32 s68, s58
	s_mov_b32 s36, s68
	s_cbranch_scc0 .LBB0_1420
	s_branch .LBB0_1421
.LBB0_1420:
	s_add_i32 s68, s36, 2
	s_add_u32 s69, s34, 0x80
	s_addc_u32 s37, s35, 0
	s_add_i32 s72, 0, 0x10000
	s_cmp_eq_u32 s61, s36
	s_cselect_b32 s37, s27, s37
	s_cselect_b32 s36, s26, s69
	s_cselect_b32 s71, s29, s67
	s_cselect_b32 s70, s28, s15
	s_add_i32 s69, 0, 0x14000
	v_add_u32_e32 v158, s72, v3
	v_add_u32_e32 v174, s69, v3
	ds_read_b128 v[146:149], v158
	ds_read_b128 v[150:153], v158 offset:1024
	ds_read_b128 v[154:157], v158 offset:2048
	ds_read_b128 v[158:161], v158 offset:3072
	ds_read_b128 v[162:165], v174
	ds_read_b128 v[166:169], v174 offset:1024
	ds_read_b128 v[170:173], v174 offset:2048
	ds_read_b128 v[174:177], v174 offset:3072
	v_lshl_add_u64 v[194:195], s[34:35], 0, v[140:141]
	s_add_i32 m0, s53, 0xc000
	ds_read_b128 v[178:181], v144
	ds_read_b128 v[182:185], v144 offset:1024
	ds_read_b128 v[186:189], v144 offset:2048
	ds_read_b128 v[190:193], v144 offset:3072
	ds_read_b128 v[202:205], v144 offset:4096
	ds_read_b128 v[206:209], v144 offset:5120
	ds_read_b128 v[210:213], v144 offset:6144
	ds_read_b128 v[214:217], v144 offset:7168
	global_load_lds_dwordx4 v[194:195], off
	v_lshl_add_u64 v[194:195], s[34:35], 0, v[142:143]
	s_add_i32 m0, s53, 0xe000
	s_nop 0
	global_load_lds_dwordx4 v[194:195], off
	s_waitcnt vmcnt(8)
	s_waitcnt lgkmcnt(0)
	s_barrier
; #define PG8_GOFFS(slot_) do { _Pragma("unroll") for (int _i = 0; _i < 2; ++_i) { int R, C; stage_rc(tid * 16 + _i * 8192, R, C); _Pragma("unroll") for (int _h = 0; _h < 2; ++_h) { \
;         unsigned t_ = gtab[(slot_) * 256 + R + 128 * _h]; t_ = t_ < (unsigned)(T - 1) ? t_ : (unsigned)(T - 1); voffA[_h][_i] = (t_ * (unsigned)K + (unsigned)C) * 2u; } } } while (0)
; #define PG8_STAGE(bufoff, gbase, voff) do { _Pragma("unroll") for (int _i = 0; _i < 2; ++_i) \
;         __builtin_amdgcn_global_load_lds((const unsigned*)((const char*)(gbase) + (voff)[_i]), (LAS unsigned*)(lds + (bufoff) + ldsw + _i * 8192), 16, 0, 0); } while (0)
; #define PG8_STAGE_A1(bufoff, gbase) do { if (Epi::GATHER) PG8_STAGE(bufoff, gbase, voffA[1]); else PG8_STAGE(bufoff, (gbase) + hstep, voffA[0]); } while (0)
; #define PG8_LDA(dst, b, h) do { _Pragma("unroll") for (int m = 0; m < 4; ++m) _Pragma("unroll") for (int k = 0; k < 2; ++k) dst[m][k] = *(const LAS bf16x8*)(lds + PG8_SA(b, h) + aoff + m * 2048 + k * 1024); } while (0)
; #define PG8_LDB(dst, b, h) do { _Pragma("unroll") for (int n = 0; n < 2; ++n) _Pragma("unroll") for (int k = 0; k < 2; ++k) dst[n][k] = *(const LAS bf16x8*)(lds + PG8_SB(b, h) + boff + n * 2048 + k * 1024); } while (0)
; #define PG8_WAIT_V(n) asm volatile("s_waitcnt vmcnt(" #n ")" ::: "memory")
; #define PG8_WAIT_L(n) asm volatile("s_waitcnt lgkmcnt(" #n ")" ::: "memory")
; #define PG8_BAR __builtin_amdgcn_s_barrier()
; #define PG8_SCHED __builtin_amdgcn_sched_barrier(0)
; template <class Epi, class Sched>
; __device__ __forceinline__ void gemm_phase(const int tid, LAS unsigned char* lds, const bf16* Aop, const bf16* Bop, const int K_, const Sched& S, const Epi& E, const bf16* Aop1 = nullptr, const bf16* Bop1 = nullptr) {
;     ...
;             PG8_LDB(B0, 0, 0); PG8_LDB(B1, 0, 1); PG8_SCHED; PG8_LDA(At, 0, 0); PG8_STAGE_A1(PG8_SA(1, 1), a1);
;             PG8_WAIT_V(8); PG8_WAIT_L(0); PG8_BAR; PG8_MMA(0, 0, At, B0); PG8_MMA(0, 1, At, B1); PG8_BAR; PG8_SCHED;
;             PG8_LDA(At, 0, 1); PG8_STAGE(PG8_SB(0, 0), b2, voffB); PG8_STAGE(PG8_SB(0, 1), b2 + hstep, voffB); if (Epi::GATHER && last && has_next) PG8_GOFFS((ui + 1) & 1); PG8_STAGE(PG8_SA(0, 0), a2, voffA[0]);
;             PG8_WAIT_V(8); PG8_WAIT_L(0); PG8_BAR; PG8_MMA(1, 0, At, B0); PG8_MMA(1, 1, At, B1); PG8_BAR; PG8_SCHED;
	s_setprio 1
	v_mfma_f32_16x16x32_bf16 v[124:127], v[146:149], v[178:181], v[124:127]
	v_mfma_f32_16x16x32_bf16 v[128:131], v[154:157], v[178:181], v[128:131]
	v_mfma_f32_16x16x32_bf16 v[112:115], v[146:149], v[186:189], v[112:115]
	v_mfma_f32_16x16x32_bf16 v[108:111], v[154:157], v[186:189], v[108:111]
	v_mfma_f32_16x16x32_bf16 v[96:99], v[146:149], v[202:205], v[96:99]
	v_mfma_f32_16x16x32_bf16 v[92:95], v[154:157], v[202:205], v[92:95]
	v_mfma_f32_16x16x32_bf16 v[80:83], v[146:149], v[210:213], v[80:83]
	v_mfma_f32_16x16x32_bf16 v[76:79], v[154:157], v[210:213], v[76:79]
	v_mfma_f32_16x16x32_bf16 v[124:127], v[150:153], v[182:185], v[124:127]
	v_mfma_f32_16x16x32_bf16 v[128:131], v[158:161], v[182:185], v[128:131]
	v_mfma_f32_16x16x32_bf16 v[112:115], v[150:153], v[190:193], v[112:115]
	v_mfma_f32_16x16x32_bf16 v[108:111], v[158:161], v[190:193], v[108:111]
	v_mfma_f32_16x16x32_bf16 v[96:99], v[150:153], v[206:209], v[96:99]
	v_mfma_f32_16x16x32_bf16 v[92:95], v[158:161], v[206:209], v[92:95]
	v_mfma_f32_16x16x32_bf16 v[80:83], v[150:153], v[214:217], v[80:83]
	v_mfma_f32_16x16x32_bf16 v[76:79], v[158:161], v[214:217], v[76:79]
	v_mfma_f32_16x16x32_bf16 v[120:123], v[162:165], v[178:181], v[120:123]
	v_mfma_f32_16x16x32_bf16 v[116:119], v[170:173], v[178:181], v[116:119]
	v_mfma_f32_16x16x32_bf16 v[104:107], v[162:165], v[186:189], v[104:107]
	v_mfma_f32_16x16x32_bf16 v[100:103], v[170:173], v[186:189], v[100:103]
	v_mfma_f32_16x16x32_bf16 v[88:91], v[162:165], v[202:205], v[88:91]
	v_mfma_f32_16x16x32_bf16 v[84:87], v[170:173], v[202:205], v[84:87]
	v_mfma_f32_16x16x32_bf16 v[72:75], v[162:165], v[210:213], v[72:75]
	v_mfma_f32_16x16x32_bf16 v[68:71], v[170:173], v[210:213], v[68:71]
	v_mfma_f32_16x16x32_bf16 v[120:123], v[166:169], v[182:185], v[120:123]
	v_mfma_f32_16x16x32_bf16 v[116:119], v[174:177], v[182:185], v[116:119]
	v_mfma_f32_16x16x32_bf16 v[104:107], v[166:169], v[190:193], v[104:107]
	v_mfma_f32_16x16x32_bf16 v[100:103], v[174:177], v[190:193], v[100:103]
	v_mfma_f32_16x16x32_bf16 v[88:91], v[166:169], v[206:209], v[88:91]
	v_mfma_f32_16x16x32_bf16 v[84:87], v[174:177], v[206:209], v[84:87]
	v_mfma_f32_16x16x32_bf16 v[72:75], v[166:169], v[214:217], v[72:75]
	v_mfma_f32_16x16x32_bf16 v[68:71], v[174:177], v[214:217], v[68:71]
	s_setprio 0
	s_barrier
	s_add_i32 s72, s72, s52
	v_lshl_add_u64 v[194:195], s[70:71], 0, v[134:135]
	s_mov_b32 m0, s72
	ds_read_b128 v[178:181], v144 offset:16384
	ds_read_b128 v[182:185], v144 offset:17408
	ds_read_b128 v[186:189], v144 offset:18432
	ds_read_b128 v[190:193], v144 offset:19456
	ds_read_b128 v[202:205], v144 offset:20480
	ds_read_b128 v[206:209], v144 offset:21504
	ds_read_b128 v[210:213], v144 offset:22528
	ds_read_b128 v[214:217], v144 offset:23552
	global_load_lds_dwordx4 v[194:195], off
	s_add_i32 m0, s72, 0x2000
	v_lshl_add_u64 v[196:197], s[70:71], 0, v[0:1]
	s_add_u32 s70, s70, s6
	s_addc_u32 s71, s71, s7
	s_add_i32 s69, s69, s52
	global_load_lds_dwordx4 v[196:197], off
	v_lshl_add_u64 v[198:199], s[70:71], 0, v[134:135]
	s_mov_b32 m0, s69
	v_lshl_add_u64 v[218:219], s[70:71], 0, v[0:1]
	global_load_lds_dwordx4 v[198:199], off
	s_add_i32 m0, s69, 0x2000
	v_lshl_add_u64 v[220:221], s[36:37], 0, v[136:137]
	global_load_lds_dwordx4 v[218:219], off
	s_mov_b32 m0, s53
	v_lshl_add_u64 v[222:223], s[36:37], 0, v[132:133]
	global_load_lds_dwordx4 v[220:221], off
	s_mov_b32 m0, s54
	s_nop 0
	global_load_lds_dwordx4 v[222:223], off
	s_waitcnt vmcnt(8)
	s_waitcnt lgkmcnt(0)
	s_barrier
	s_setprio 1
	v_mfma_f32_16x16x32_bf16 v[64:67], v[146:149], v[178:181], v[64:67]
	v_mfma_f32_16x16x32_bf16 v[60:63], v[154:157], v[178:181], v[60:63]
	v_mfma_f32_16x16x32_bf16 v[48:51], v[146:149], v[186:189], v[48:51]
	v_mfma_f32_16x16x32_bf16 v[44:47], v[154:157], v[186:189], v[44:47]
	v_mfma_f32_16x16x32_bf16 v[32:35], v[146:149], v[202:205], v[32:35]
	v_mfma_f32_16x16x32_bf16 v[28:31], v[154:157], v[202:205], v[28:31]
	v_mfma_f32_16x16x32_bf16 v[16:19], v[146:149], v[210:213], v[16:19]
	v_mfma_f32_16x16x32_bf16 v[12:15], v[154:157], v[210:213], v[12:15]
	v_mfma_f32_16x16x32_bf16 v[64:67], v[150:153], v[182:185], v[64:67]
	v_mfma_f32_16x16x32_bf16 v[60:63], v[158:161], v[182:185], v[60:63]
	v_mfma_f32_16x16x32_bf16 v[48:51], v[150:153], v[190:193], v[48:51]
	v_mfma_f32_16x16x32_bf16 v[44:47], v[158:161], v[190:193], v[44:47]
	v_mfma_f32_16x16x32_bf16 v[32:35], v[150:153], v[206:209], v[32:35]
	v_mfma_f32_16x16x32_bf16 v[28:31], v[158:161], v[206:209], v[28:31]
	v_mfma_f32_16x16x32_bf16 v[16:19], v[150:153], v[214:217], v[16:19]
	v_mfma_f32_16x16x32_bf16 v[12:15], v[158:161], v[214:217], v[12:15]
	v_mfma_f32_16x16x32_bf16 v[56:59], v[162:165], v[178:181], v[56:59]
	v_mfma_f32_16x16x32_bf16 v[52:55], v[170:173], v[178:181], v[52:55]
	v_mfma_f32_16x16x32_bf16 v[40:43], v[162:165], v[186:189], v[40:43]
	v_mfma_f32_16x16x32_bf16 v[36:39], v[170:173], v[186:189], v[36:39]
	v_mfma_f32_16x16x32_bf16 v[24:27], v[162:165], v[202:205], v[24:27]
	v_mfma_f32_16x16x32_bf16 v[20:23], v[170:173], v[202:205], v[20:23]
	v_mfma_f32_16x16x32_bf16 v[8:11], v[162:165], v[210:213], v[8:11]
	v_mfma_f32_16x16x32_bf16 v[4:7], v[170:173], v[210:213], v[4:7]
	v_mfma_f32_16x16x32_bf16 v[56:59], v[166:169], v[182:185], v[56:59]
	v_mfma_f32_16x16x32_bf16 v[52:55], v[174:177], v[182:185], v[52:55]
	v_mfma_f32_16x16x32_bf16 v[40:43], v[166:169], v[190:193], v[40:43]
	v_mfma_f32_16x16x32_bf16 v[36:39], v[174:177], v[190:193], v[36:39]
	v_mfma_f32_16x16x32_bf16 v[24:27], v[166:169], v[206:209], v[24:27]
	v_mfma_f32_16x16x32_bf16 v[20:23], v[174:177], v[206:209], v[20:23]
	v_mfma_f32_16x16x32_bf16 v[8:11], v[166:169], v[214:217], v[8:11]
	v_mfma_f32_16x16x32_bf16 v[4:7], v[174:177], v[214:217], v[4:7]
	s_setprio 0
	s_barrier
; #define PG8_STAGE(bufoff, gbase, voff) do { _Pragma("unroll") for (int _i = 0; _i < 2; ++_i) \
;         __builtin_amdgcn_global_load_lds((const unsigned*)((const char*)(gbase) + (voff)[_i]), (LAS unsigned*)(lds + (bufoff) + ldsw + _i * 8192), 16, 0, 0); } while (0)
; #define PG8_STAGE_A1(bufoff, gbase) do { if (Epi::GATHER) PG8_STAGE(bufoff, gbase, voffA[1]); else PG8_STAGE(bufoff, (gbase) + hstep, voffA[0]); } while (0)
; #define PG8_LDA(dst, b, h) do { _Pragma("unroll") for (int m = 0; m < 4; ++m) _Pragma("unroll") for (int k = 0; k < 2; ++k) dst[m][k] = *(const LAS bf16x8*)(lds + PG8_SA(b, h) + aoff + m * 2048 + k * 1024); } while (0)
; #define PG8_LDB(dst, b, h) do { _Pragma("unroll") for (int n = 0; n < 2; ++n) _Pragma("unroll") for (int k = 0; k < 2; ++k) dst[n][k] = *(const LAS bf16x8*)(lds + PG8_SB(b, h) + boff + n * 2048 + k * 1024); } while (0)
; #define PG8_MMA(ai, bj, At, Bt) do { __builtin_amdgcn_s_setprio(1); _Pragma("unroll") for (int m = 0; m < 4; ++m) _Pragma("unroll") for (int n = 0; n < 2; ++n) _Pragma("unroll") for (int k = 0; k < 2; ++k) \
;         acc[ai][bj][m][n] = __builtin_amdgcn_mfma_f32_16x16x32_bf16(Bt[n][k], At[m][k], acc[ai][bj][m][n], 0, 0, 0); __builtin_amdgcn_s_setprio(0); } while (0)
; #define PG8_WAIT_V(n) asm volatile("s_waitcnt vmcnt(" #n ")" ::: "memory")
; #define PG8_WAIT_L(n) asm volatile("s_waitcnt lgkmcnt(" #n ")" ::: "memory")
; #define PG8_BAR __builtin_amdgcn_s_barrier()
; #define PG8_SCHED __builtin_amdgcn_sched_barrier(0)
; template <class Epi, class Sched>
; __device__ __forceinline__ void gemm_phase(const int tid, LAS unsigned char* lds, const bf16* Aop, const bf16* Bop, const int K_, const Sched& S, const Epi& E, const bf16* Aop1 = nullptr, const bf16* Bop1 = nullptr) {
;     ...
;             PG8_LDB(B0, 1, 0); PG8_LDB(B1, 1, 1); PG8_SCHED; PG8_LDA(At, 1, 0); PG8_STAGE_A1(PG8_SA(0, 1), a2);
;             PG8_WAIT_V(8); PG8_WAIT_L(0); PG8_BAR; PG8_MMA(0, 0, At, B0); PG8_MMA(0, 1, At, B1); PG8_BAR; PG8_SCHED;
;             PG8_LDA(At, 1, 1); PG8_STAGE(PG8_SB(1, 0), b3, voffB); PG8_STAGE(PG8_SB(1, 1), b3 + hstep, voffB); PG8_STAGE(PG8_SA(1, 0), a3, voffA[0]);
;             PG8_WAIT_V(8); PG8_WAIT_L(0); PG8_BAR; PG8_MMA(1, 0, At, B0); PG8_MMA(1, 1, At, B1); PG8_BAR; PG8_SCHED;
;         }
	s_add_i32 s69, 0, 0x18000
	s_add_i32 s70, 0, 0x1c000
	v_add_u32_e32 v158, s69, v3
	v_add_u32_e32 v174, s70, v3
	ds_read_b128 v[146:149], v158
	ds_read_b128 v[150:153], v158 offset:1024
	ds_read_b128 v[154:157], v158 offset:2048
	ds_read_b128 v[158:161], v158 offset:3072
	ds_read_b128 v[162:165], v174
	ds_read_b128 v[166:169], v174 offset:1024
	ds_read_b128 v[170:173], v174 offset:2048
	ds_read_b128 v[174:177], v174 offset:3072
	s_add_u32 s36, s36, s6
	s_addc_u32 s37, s37, s7
	s_mov_b32 m0, s55
	v_lshl_add_u64 v[224:225], s[36:37], 0, v[136:137]
	ds_read_b128 v[178:181], v144 offset:32768
	ds_read_b128 v[182:185], v144 offset:33792
	ds_read_b128 v[186:189], v144 offset:34816
	ds_read_b128 v[190:193], v144 offset:35840
	ds_read_b128 v[202:205], v144 offset:36864
	ds_read_b128 v[206:209], v144 offset:37888
	ds_read_b128 v[210:213], v144 offset:38912
	ds_read_b128 v[214:217], v144 offset:39936
	global_load_lds_dwordx4 v[224:225], off
	v_lshl_add_u64 v[224:225], s[36:37], 0, v[132:133]
	s_mov_b32 m0, s56
	s_nop 0
	global_load_lds_dwordx4 v[224:225], off
	s_waitcnt vmcnt(8)
	s_waitcnt lgkmcnt(0)
	s_barrier
	s_setprio 1
	v_mfma_f32_16x16x32_bf16 v[124:127], v[146:149], v[178:181], v[124:127]
	v_mfma_f32_16x16x32_bf16 v[128:131], v[154:157], v[178:181], v[128:131]
	v_mfma_f32_16x16x32_bf16 v[112:115], v[146:149], v[186:189], v[112:115]
	v_mfma_f32_16x16x32_bf16 v[108:111], v[154:157], v[186:189], v[108:111]
	v_mfma_f32_16x16x32_bf16 v[96:99], v[146:149], v[202:205], v[96:99]
	v_mfma_f32_16x16x32_bf16 v[92:95], v[154:157], v[202:205], v[92:95]
	v_mfma_f32_16x16x32_bf16 v[80:83], v[146:149], v[210:213], v[80:83]
	v_mfma_f32_16x16x32_bf16 v[76:79], v[154:157], v[210:213], v[76:79]
	v_mfma_f32_16x16x32_bf16 v[124:127], v[150:153], v[182:185], v[124:127]
	v_mfma_f32_16x16x32_bf16 v[128:131], v[158:161], v[182:185], v[128:131]
	v_mfma_f32_16x16x32_bf16 v[112:115], v[150:153], v[190:193], v[112:115]
	v_mfma_f32_16x16x32_bf16 v[108:111], v[158:161], v[190:193], v[108:111]
	v_mfma_f32_16x16x32_bf16 v[96:99], v[150:153], v[206:209], v[96:99]
	v_mfma_f32_16x16x32_bf16 v[92:95], v[158:161], v[206:209], v[92:95]
	v_mfma_f32_16x16x32_bf16 v[80:83], v[150:153], v[214:217], v[80:83]
	v_mfma_f32_16x16x32_bf16 v[76:79], v[158:161], v[214:217], v[76:79]
	v_mfma_f32_16x16x32_bf16 v[120:123], v[162:165], v[178:181], v[120:123]
	v_mfma_f32_16x16x32_bf16 v[116:119], v[170:173], v[178:181], v[116:119]
	v_mfma_f32_16x16x32_bf16 v[104:107], v[162:165], v[186:189], v[104:107]
	v_mfma_f32_16x16x32_bf16 v[100:103], v[170:173], v[186:189], v[100:103]
	v_mfma_f32_16x16x32_bf16 v[88:91], v[162:165], v[202:205], v[88:91]
	v_mfma_f32_16x16x32_bf16 v[84:87], v[170:173], v[202:205], v[84:87]
	v_mfma_f32_16x16x32_bf16 v[72:75], v[162:165], v[210:213], v[72:75]
	v_mfma_f32_16x16x32_bf16 v[68:71], v[170:173], v[210:213], v[68:71]
	v_mfma_f32_16x16x32_bf16 v[120:123], v[166:169], v[182:185], v[120:123]
	v_mfma_f32_16x16x32_bf16 v[116:119], v[174:177], v[182:185], v[116:119]
	v_mfma_f32_16x16x32_bf16 v[104:107], v[166:169], v[190:193], v[104:107]
	v_mfma_f32_16x16x32_bf16 v[100:103], v[174:177], v[190:193], v[100:103]
	v_mfma_f32_16x16x32_bf16 v[88:91], v[166:169], v[206:209], v[88:91]
	v_mfma_f32_16x16x32_bf16 v[84:87], v[174:177], v[206:209], v[84:87]
	v_mfma_f32_16x16x32_bf16 v[72:75], v[166:169], v[214:217], v[72:75]
	v_mfma_f32_16x16x32_bf16 v[68:71], v[174:177], v[214:217], v[68:71]
	s_setprio 0
	s_barrier
	s_add_i32 s36, s69, s52
	v_lshl_add_u64 v[194:195], v[194:195], 0, s[20:21]
	s_mov_b32 m0, s36
	ds_read_b128 v[178:181], v144 offset:49152
	ds_read_b128 v[182:185], v144 offset:50176
	ds_read_b128 v[186:189], v144 offset:51200
	ds_read_b128 v[190:193], v144 offset:52224
	ds_read_b128 v[202:205], v144 offset:53248
	ds_read_b128 v[206:209], v144 offset:54272
	ds_read_b128 v[210:213], v144 offset:55296
	ds_read_b128 v[214:217], v144 offset:56320
	global_load_lds_dwordx4 v[194:195], off
	v_lshl_add_u64 v[194:195], v[196:197], 0, s[20:21]
	s_add_i32 m0, s36, 0x2000
	s_add_i32 s36, s70, s52
	global_load_lds_dwordx4 v[194:195], off
	v_lshl_add_u64 v[194:195], v[198:199], 0, s[20:21]
	s_mov_b32 m0, s36
	s_nop 0
	global_load_lds_dwordx4 v[194:195], off
	v_lshl_add_u64 v[194:195], v[218:219], 0, s[20:21]
	s_add_i32 m0, s36, 0x2000
	s_nop 0
	global_load_lds_dwordx4 v[194:195], off
	v_lshl_add_u64 v[194:195], v[220:221], 0, s[20:21]
	s_mov_b32 m0, s59
	s_nop 0
	global_load_lds_dwordx4 v[194:195], off
	v_lshl_add_u64 v[194:195], v[222:223], 0, s[20:21]
	s_mov_b32 m0, s60
	s_nop 0
	global_load_lds_dwordx4 v[194:195], off
	s_waitcnt vmcnt(8)
	s_waitcnt lgkmcnt(0)
	s_barrier
	s_setprio 1
	v_mfma_f32_16x16x32_bf16 v[64:67], v[146:149], v[178:181], v[64:67]
	v_mfma_f32_16x16x32_bf16 v[60:63], v[154:157], v[178:181], v[60:63]
	v_mfma_f32_16x16x32_bf16 v[48:51], v[146:149], v[186:189], v[48:51]
	v_mfma_f32_16x16x32_bf16 v[44:47], v[154:157], v[186:189], v[44:47]
	v_mfma_f32_16x16x32_bf16 v[32:35], v[146:149], v[202:205], v[32:35]
	v_mfma_f32_16x16x32_bf16 v[28:31], v[154:157], v[202:205], v[28:31]
	v_mfma_f32_16x16x32_bf16 v[16:19], v[146:149], v[210:213], v[16:19]
	v_mfma_f32_16x16x32_bf16 v[12:15], v[154:157], v[210:213], v[12:15]
	v_mfma_f32_16x16x32_bf16 v[64:67], v[150:153], v[182:185], v[64:67]
	v_mfma_f32_16x16x32_bf16 v[60:63], v[158:161], v[182:185], v[60:63]
	v_mfma_f32_16x16x32_bf16 v[48:51], v[150:153], v[190:193], v[48:51]
	v_mfma_f32_16x16x32_bf16 v[44:47], v[158:161], v[190:193], v[44:47]
	v_mfma_f32_16x16x32_bf16 v[32:35], v[150:153], v[206:209], v[32:35]
	v_mfma_f32_16x16x32_bf16 v[28:31], v[158:161], v[206:209], v[28:31]
	v_mfma_f32_16x16x32_bf16 v[16:19], v[150:153], v[214:217], v[16:19]
	v_mfma_f32_16x16x32_bf16 v[12:15], v[158:161], v[214:217], v[12:15]
	v_mfma_f32_16x16x32_bf16 v[56:59], v[162:165], v[178:181], v[56:59]
	v_mfma_f32_16x16x32_bf16 v[52:55], v[170:173], v[178:181], v[52:55]
	v_mfma_f32_16x16x32_bf16 v[40:43], v[162:165], v[186:189], v[40:43]
	v_mfma_f32_16x16x32_bf16 v[36:39], v[170:173], v[186:189], v[36:39]
	v_mfma_f32_16x16x32_bf16 v[24:27], v[162:165], v[202:205], v[24:27]
	v_mfma_f32_16x16x32_bf16 v[20:23], v[170:173], v[202:205], v[20:23]
	v_mfma_f32_16x16x32_bf16 v[8:11], v[162:165], v[210:213], v[8:11]
	v_mfma_f32_16x16x32_bf16 v[4:7], v[170:173], v[210:213], v[4:7]
	v_mfma_f32_16x16x32_bf16 v[56:59], v[166:169], v[182:185], v[56:59]
	v_mfma_f32_16x16x32_bf16 v[52:55], v[174:177], v[182:185], v[52:55]
	v_mfma_f32_16x16x32_bf16 v[40:43], v[166:169], v[190:193], v[40:43]
	v_mfma_f32_16x16x32_bf16 v[36:39], v[174:177], v[190:193], v[36:39]
	v_mfma_f32_16x16x32_bf16 v[24:27], v[166:169], v[206:209], v[24:27]
	v_mfma_f32_16x16x32_bf16 v[20:23], v[174:177], v[206:209], v[20:23]
	v_mfma_f32_16x16x32_bf16 v[8:11], v[166:169], v[214:217], v[8:11]
	v_mfma_f32_16x16x32_bf16 v[4:7], v[174:177], v[214:217], v[4:7]
	s_setprio 0
	s_barrier
	s_add_u32 s34, s34, 0x100
	s_addc_u32 s35, s35, 0
	s_add_u32 s15, s15, 0x100
	s_addc_u32 s67, s67, 0
	s_cmp_ge_i32 s68, s58
	s_mov_b32 s36, s68
	s_cbranch_scc0 .LBB0_1420

; #define PG8_GOFFS(slot_) do { _Pragma("unroll") for (int _i = 0; _i < 2; ++_i) { int R, C; stage_rc(tid * 16 + _i * 8192, R, C); _Pragma("unroll") for (int _h = 0; _h < 2; ++_h) { \
;         unsigned t_ = gtab[(slot_) * 256 + R + 128 * _h]; t_ = t_ < (unsigned)(T - 1) ? t_ : (unsigned)(T - 1); voffA[_h][_i] = (t_ * (unsigned)K + (unsigned)C) * 2u; } } } while (0)
; #define PG8_STAGE(bufoff, gbase, voff) do { _Pragma("unroll") for (int _i = 0; _i < 2; ++_i) \
;         __builtin_amdgcn_global_load_lds((const unsigned*)((const char*)(gbase) + (voff)[_i]), (LAS unsigned*)(lds + (bufoff) + ldsw + _i * 8192), 16, 0, 0); } while (0)
; #define PG8_STAGE_A1(bufoff, gbase) do { if (Epi::GATHER) PG8_STAGE(bufoff, gbase, voffA[1]); else PG8_STAGE(bufoff, (gbase) + hstep, voffA[0]); } while (0)
; #define PG8_LDA(dst, b, h) do { _Pragma("unroll") for (int m = 0; m < 4; ++m) _Pragma("unroll") for (int k = 0; k < 2; ++k) dst[m][k] = *(const LAS bf16x8*)(lds + PG8_SA(b, h) + aoff + m * 2048 + k * 1024); } while (0)
; #define PG8_LDB(dst, b, h) do { _Pragma("unroll") for (int n = 0; n < 2; ++n) _Pragma("unroll") for (int k = 0; k < 2; ++k) dst[n][k] = *(const LAS bf16x8*)(lds + PG8_SB(b, h) + boff + n * 2048 + k * 1024); } while (0)
; #define PG8_WAIT_V(n) asm volatile("s_waitcnt vmcnt(" #n ")" ::: "memory")
; template <class Epi, class Sched>
; __device__ __forceinline__ void gemm_phase(const int tid, LAS unsigned char* lds, const bf16* Aop, const bf16* Bop, const int K_, const Sched& S, const Epi& E, const bf16* Aop1 = nullptr, const bf16* Bop1 = nullptr) {
;     ...
;         for (int t = 0; t < nt; t += 2) {
;             const bool last = (t == nt - 2);
;             const char* a1 = cA + (size_t)(t + 1) * kstep;
;             const char* a2 = last ? nA : cA + (size_t)(t + 2) * kstep; const char* b2 = last ? nB : cB + (size_t)(t + 2) * kstep;
;             const char* a3 = a2 + kstep; const char* b3 = b2 + kstep;
;             PG8_LDB(B0, 0, 0); PG8_LDB(B1, 0, 1); PG8_SCHED; PG8_LDA(At, 0, 0); PG8_STAGE_A1(PG8_SA(1, 1), a1);
;             PG8_WAIT_V(8); PG8_WAIT_L(0); PG8_BAR; PG8_MMA(0, 0, At, B0); PG8_MMA(0, 1, At, B1); PG8_BAR; PG8_SCHED;
;             PG8_LDA(At, 0, 1); PG8_STAGE(PG8_SB(0, 0), b2, voffB); PG8_STAGE(PG8_SB(0, 1), b2 + hstep, voffB); if (Epi::GATHER && last && has_next) PG8_GOFFS((ui + 1) & 1); PG8_STAGE(PG8_SA(0, 0), a2, voffA[0]);
.LBB0_1595:
	v_mov_b32_e32 v131, 0
	s_andn2_b64 vcc, exec, s[64:65]
	s_cbranch_vccnz .LBB0_1598
	s_add_u32 s2, s2, 0x80
	s_addc_u32 s3, s3, 0
	s_add_u32 s6, s4, 0x100
	s_addc_u32 s7, s5, 0
	s_mov_b32 s4, 0
	s_add_i32 s72, s4, 2
	s_add_u32 s73, s2, 0x80
	s_addc_u32 s5, s3, 0
	s_add_i32 s76, 0, 0x10000
	s_cmp_eq_u32 s37, s4
	s_cselect_b32 s5, s41, s5
	s_cselect_b32 s4, s40, s73
	v_add_u32_e32 v158, s76, v160
	s_cselect_b32 s75, s69, s7
	s_cselect_b32 s74, s68, s6
	s_add_i32 s73, 0, 0x14000
	ds_read_b128 v[132:135], v158
	ds_read_b128 v[136:139], v158 offset:1024
	ds_read_b128 v[154:157], v158 offset:2048
	ds_read_b128 v[164:167], v158 offset:3072
	v_add_u32_e32 v158, s73, v160
	ds_read_b128 v[168:171], v158
	ds_read_b128 v[172:175], v158 offset:1024
	ds_read_b128 v[176:179], v158 offset:2048
	ds_read_b128 v[180:183], v158 offset:3072
	v_lshl_add_u64 v[158:159], s[2:3], 0, v[150:151]
	s_add_i32 m0, s17, 0xc000
	ds_read_b128 v[184:187], v162
	ds_read_b128 v[188:191], v162 offset:1024
	ds_read_b128 v[192:195], v162 offset:2048
	ds_read_b128 v[202:205], v162 offset:3072
	ds_read_b128 v[206:209], v162 offset:4096
	ds_read_b128 v[210:213], v162 offset:5120
	ds_read_b128 v[214:217], v162 offset:6144
	ds_read_b128 v[218:221], v162 offset:7168
	global_load_lds_dwordx4 v[158:159], off
	v_lshl_add_u64 v[158:159], s[2:3], 0, v[152:153]
	s_add_i32 m0, s17, 0xe000
	s_nop 0
	global_load_lds_dwordx4 v[158:159], off
	s_waitcnt vmcnt(8)
	s_waitcnt lgkmcnt(0)
	s_barrier
	s_setprio 1
	v_mfma_f32_16x16x32_bf16 v[128:131], v[132:135], v[184:187], 0
	v_mfma_f32_16x16x32_bf16 v[124:127], v[154:157], v[184:187], 0
	v_mfma_f32_16x16x32_bf16 v[112:115], v[132:135], v[192:195], 0
	v_mfma_f32_16x16x32_bf16 v[108:111], v[154:157], v[192:195], 0
	v_mfma_f32_16x16x32_bf16 v[96:99], v[132:135], v[206:209], 0
	v_mfma_f32_16x16x32_bf16 v[92:95], v[154:157], v[206:209], 0
	v_mfma_f32_16x16x32_bf16 v[80:83], v[132:135], v[214:217], 0
	v_mfma_f32_16x16x32_bf16 v[76:79], v[154:157], v[214:217], 0
	v_mfma_f32_16x16x32_bf16 v[128:131], v[136:139], v[188:191], v[128:131]
	v_mfma_f32_16x16x32_bf16 v[124:127], v[164:167], v[188:191], v[124:127]
	v_mfma_f32_16x16x32_bf16 v[112:115], v[136:139], v[202:205], v[112:115]
	v_mfma_f32_16x16x32_bf16 v[108:111], v[164:167], v[202:205], v[108:111]
	v_mfma_f32_16x16x32_bf16 v[96:99], v[136:139], v[210:213], v[96:99]
	v_mfma_f32_16x16x32_bf16 v[92:95], v[164:167], v[210:213], v[92:95]
	v_mfma_f32_16x16x32_bf16 v[80:83], v[136:139], v[218:221], v[80:83]
	v_mfma_f32_16x16x32_bf16 v[76:79], v[164:167], v[218:221], v[76:79]
	v_mfma_f32_16x16x32_bf16 v[120:123], v[168:171], v[184:187], 0
	v_mfma_f32_16x16x32_bf16 v[116:119], v[176:179], v[184:187], 0
	v_mfma_f32_16x16x32_bf16 v[104:107], v[168:171], v[192:195], 0
	v_mfma_f32_16x16x32_bf16 v[100:103], v[176:179], v[192:195], 0
	v_mfma_f32_16x16x32_bf16 v[88:91], v[168:171], v[206:209], 0
	v_mfma_f32_16x16x32_bf16 v[84:87], v[176:179], v[206:209], 0
	v_mfma_f32_16x16x32_bf16 v[72:75], v[168:171], v[214:217], 0
	v_mfma_f32_16x16x32_bf16 v[68:71], v[176:179], v[214:217], 0
	v_mfma_f32_16x16x32_bf16 v[120:123], v[172:175], v[188:191], v[120:123]
	v_mfma_f32_16x16x32_bf16 v[116:119], v[180:183], v[188:191], v[116:119]
	v_mfma_f32_16x16x32_bf16 v[104:107], v[172:175], v[202:205], v[104:107]
	v_mfma_f32_16x16x32_bf16 v[100:103], v[180:183], v[202:205], v[100:103]
	v_mfma_f32_16x16x32_bf16 v[88:91], v[172:175], v[210:213], v[88:91]
	v_mfma_f32_16x16x32_bf16 v[84:87], v[180:183], v[210:213], v[84:87]
	v_mfma_f32_16x16x32_bf16 v[72:75], v[172:175], v[218:221], v[72:75]
	v_mfma_f32_16x16x32_bf16 v[68:71], v[180:183], v[218:221], v[68:71]
	s_setprio 0
	s_barrier
	s_add_i32 s76, s76, s16
	v_lshl_add_u64 v[158:159], s[74:75], 0, v[142:143]
	s_mov_b32 m0, s76
	ds_read_b128 v[184:187], v162 offset:16384
	ds_read_b128 v[188:191], v162 offset:17408
	ds_read_b128 v[192:195], v162 offset:18432
	ds_read_b128 v[202:205], v162 offset:19456
	ds_read_b128 v[206:209], v162 offset:20480
	ds_read_b128 v[210:213], v162 offset:21504
	ds_read_b128 v[214:217], v162 offset:22528
	ds_read_b128 v[218:221], v162 offset:23552
	global_load_lds_dwordx4 v[158:159], off
	s_add_i32 m0, s76, 0x2000
	v_lshl_add_u64 v[196:197], s[74:75], 0, v[146:147]
	s_add_u32 s74, s74, s58
	s_addc_u32 s75, s75, s59
	s_add_i32 s73, s73, s16
	global_load_lds_dwordx4 v[196:197], off
	v_lshl_add_u64 v[198:199], s[74:75], 0, v[142:143]
	s_mov_b32 m0, s73
	v_lshl_add_u64 v[222:223], s[74:75], 0, v[146:147]
	global_load_lds_dwordx4 v[198:199], off
	s_add_i32 m0, s73, 0x2000
	v_lshl_add_u64 v[224:225], s[4:5], 0, v[140:141]
	global_load_lds_dwordx4 v[222:223], off
	s_mov_b32 m0, s17
	v_lshl_add_u64 v[230:231], s[4:5], 0, v[144:145]
	global_load_lds_dwordx4 v[224:225], off
	s_mov_b32 m0, s28
	s_nop 0
	global_load_lds_dwordx4 v[230:231], off
	s_waitcnt vmcnt(8)
	s_waitcnt lgkmcnt(0)
	s_barrier
; #define PG8_STAGE_A1(bufoff, gbase) do { if (Epi::GATHER) PG8_STAGE(bufoff, gbase, voffA[1]); else PG8_STAGE(bufoff, (gbase) + hstep, voffA[0]); } while (0)
; #define PG8_LDA(dst, b, h) do { _Pragma("unroll") for (int m = 0; m < 4; ++m) _Pragma("unroll") for (int k = 0; k < 2; ++k) dst[m][k] = *(const LAS bf16x8*)(lds + PG8_SA(b, h) + aoff + m * 2048 + k * 1024); } while (0)
; #define PG8_LDB(dst, b, h) do { _Pragma("unroll") for (int n = 0; n < 2; ++n) _Pragma("unroll") for (int k = 0; k < 2; ++k) dst[n][k] = *(const LAS bf16x8*)(lds + PG8_SB(b, h) + boff + n * 2048 + k * 1024); } while (0)
; #define PG8_MMA(ai, bj, At, Bt) do { __builtin_amdgcn_s_setprio(1); _Pragma("unroll") for (int m = 0; m < 4; ++m) _Pragma("unroll") for (int n = 0; n < 2; ++n) _Pragma("unroll") for (int k = 0; k < 2; ++k) \
;         acc[ai][bj][m][n] = __builtin_amdgcn_mfma_f32_16x16x32_bf16(Bt[n][k], At[m][k], acc[ai][bj][m][n], 0, 0, 0); __builtin_amdgcn_s_setprio(0); } while (0)
; #define PG8_WAIT_V(n) asm volatile("s_waitcnt vmcnt(" #n ")" ::: "memory")
; #define PG8_WAIT_L(n) asm volatile("s_waitcnt lgkmcnt(" #n ")" ::: "memory")
; #define PG8_BAR __builtin_amdgcn_s_barrier()
; #define PG8_SCHED __builtin_amdgcn_sched_barrier(0)
; template <class Epi, class Sched>
; __device__ __forceinline__ void gemm_phase(const int tid, LAS unsigned char* lds, const bf16* Aop, const bf16* Bop, const int K_, const Sched& S, const Epi& E, const bf16* Aop1 = nullptr, const bf16* Bop1 = nullptr) {
;     ...
;             PG8_WAIT_V(8); PG8_WAIT_L(0); PG8_BAR; PG8_MMA(1, 0, At, B0); PG8_MMA(1, 1, At, B1); PG8_BAR; PG8_SCHED;
;             PG8_LDB(B0, 1, 0); PG8_LDB(B1, 1, 1); PG8_SCHED; PG8_LDA(At, 1, 0); PG8_STAGE_A1(PG8_SA(0, 1), a2);
;             PG8_WAIT_V(8); PG8_WAIT_L(0); PG8_BAR; PG8_MMA(0, 0, At, B0); PG8_MMA(0, 1, At, B1); PG8_BAR; PG8_SCHED;
	s_setprio 1
	v_mfma_f32_16x16x32_bf16 v[64:67], v[132:135], v[184:187], 0
	v_mfma_f32_16x16x32_bf16 v[60:63], v[154:157], v[184:187], 0
	v_mfma_f32_16x16x32_bf16 v[48:51], v[132:135], v[192:195], 0
	v_mfma_f32_16x16x32_bf16 v[44:47], v[154:157], v[192:195], 0
	v_mfma_f32_16x16x32_bf16 v[32:35], v[132:135], v[206:209], 0
	v_mfma_f32_16x16x32_bf16 v[28:31], v[154:157], v[206:209], 0
	v_mfma_f32_16x16x32_bf16 v[16:19], v[132:135], v[214:217], 0
	v_mfma_f32_16x16x32_bf16 v[12:15], v[154:157], v[214:217], 0
	v_mfma_f32_16x16x32_bf16 v[64:67], v[136:139], v[188:191], v[64:67]
	v_mfma_f32_16x16x32_bf16 v[60:63], v[164:167], v[188:191], v[60:63]
	v_mfma_f32_16x16x32_bf16 v[48:51], v[136:139], v[202:205], v[48:51]
	v_mfma_f32_16x16x32_bf16 v[44:47], v[164:167], v[202:205], v[44:47]
	v_mfma_f32_16x16x32_bf16 v[32:35], v[136:139], v[210:213], v[32:35]
	v_mfma_f32_16x16x32_bf16 v[28:31], v[164:167], v[210:213], v[28:31]
	v_mfma_f32_16x16x32_bf16 v[16:19], v[136:139], v[218:221], v[16:19]
	v_mfma_f32_16x16x32_bf16 v[12:15], v[164:167], v[218:221], v[12:15]
	v_mfma_f32_16x16x32_bf16 v[56:59], v[168:171], v[184:187], 0
	v_mfma_f32_16x16x32_bf16 v[52:55], v[176:179], v[184:187], 0
	v_mfma_f32_16x16x32_bf16 v[40:43], v[168:171], v[192:195], 0
	v_mfma_f32_16x16x32_bf16 v[36:39], v[176:179], v[192:195], 0
	v_mfma_f32_16x16x32_bf16 v[24:27], v[168:171], v[206:209], 0
	v_mfma_f32_16x16x32_bf16 v[20:23], v[176:179], v[206:209], 0
	v_mfma_f32_16x16x32_bf16 v[8:11], v[168:171], v[214:217], 0
	v_mfma_f32_16x16x32_bf16 v[4:7], v[176:179], v[214:217], 0
	v_mfma_f32_16x16x32_bf16 v[56:59], v[172:175], v[188:191], v[56:59]
	v_mfma_f32_16x16x32_bf16 v[52:55], v[180:183], v[188:191], v[52:55]
	v_mfma_f32_16x16x32_bf16 v[40:43], v[172:175], v[202:205], v[40:43]
	v_mfma_f32_16x16x32_bf16 v[36:39], v[180:183], v[202:205], v[36:39]
	v_mfma_f32_16x16x32_bf16 v[24:27], v[172:175], v[210:213], v[24:27]
	v_mfma_f32_16x16x32_bf16 v[20:23], v[180:183], v[210:213], v[20:23]
	v_mfma_f32_16x16x32_bf16 v[8:11], v[172:175], v[218:221], v[8:11]
	v_mfma_f32_16x16x32_bf16 v[4:7], v[180:183], v[218:221], v[4:7]
	s_setprio 0
	s_barrier
	s_add_i32 s73, 0, 0x18000
	v_add_u32_e32 v163, s73, v160
	s_add_i32 s74, 0, 0x1c000
	ds_read_b128 v[132:135], v163
	ds_read_b128 v[136:139], v163 offset:1024
	ds_read_b128 v[154:157], v163 offset:2048
	ds_read_b128 v[164:167], v163 offset:3072
	v_add_u32_e32 v163, s74, v160
	ds_read_b128 v[168:171], v163
	ds_read_b128 v[172:175], v163 offset:1024
	ds_read_b128 v[176:179], v163 offset:2048
	ds_read_b128 v[180:183], v163 offset:3072
	s_add_u32 s4, s4, s58
	s_addc_u32 s5, s5, s59
	s_mov_b32 m0, s29
	v_lshl_add_u64 v[232:233], s[4:5], 0, v[140:141]
	ds_read_b128 v[184:187], v162 offset:32768
	ds_read_b128 v[188:191], v162 offset:33792
	ds_read_b128 v[192:195], v162 offset:34816
	ds_read_b128 v[202:205], v162 offset:35840
	ds_read_b128 v[206:209], v162 offset:36864
	ds_read_b128 v[210:213], v162 offset:37888
	ds_read_b128 v[214:217], v162 offset:38912
	ds_read_b128 v[218:221], v162 offset:39936
	global_load_lds_dwordx4 v[232:233], off
	v_lshl_add_u64 v[232:233], s[4:5], 0, v[144:145]
	s_mov_b32 m0, s34
	s_nop 0
	global_load_lds_dwordx4 v[232:233], off
	s_waitcnt vmcnt(8)
	s_waitcnt lgkmcnt(0)
	s_barrier
	s_setprio 1
	v_mfma_f32_16x16x32_bf16 v[128:131], v[132:135], v[184:187], v[128:131]
	v_mfma_f32_16x16x32_bf16 v[124:127], v[154:157], v[184:187], v[124:127]
	v_mfma_f32_16x16x32_bf16 v[112:115], v[132:135], v[192:195], v[112:115]
	v_mfma_f32_16x16x32_bf16 v[108:111], v[154:157], v[192:195], v[108:111]
	v_mfma_f32_16x16x32_bf16 v[96:99], v[132:135], v[206:209], v[96:99]
	v_mfma_f32_16x16x32_bf16 v[92:95], v[154:157], v[206:209], v[92:95]
	v_mfma_f32_16x16x32_bf16 v[80:83], v[132:135], v[214:217], v[80:83]
	v_mfma_f32_16x16x32_bf16 v[76:79], v[154:157], v[214:217], v[76:79]
	v_mfma_f32_16x16x32_bf16 v[128:131], v[136:139], v[188:191], v[128:131]
	v_mfma_f32_16x16x32_bf16 v[124:127], v[164:167], v[188:191], v[124:127]
	v_mfma_f32_16x16x32_bf16 v[112:115], v[136:139], v[202:205], v[112:115]
	v_mfma_f32_16x16x32_bf16 v[108:111], v[164:167], v[202:205], v[108:111]
	v_mfma_f32_16x16x32_bf16 v[96:99], v[136:139], v[210:213], v[96:99]
	v_mfma_f32_16x16x32_bf16 v[92:95], v[164:167], v[210:213], v[92:95]
	v_mfma_f32_16x16x32_bf16 v[80:83], v[136:139], v[218:221], v[80:83]
	v_mfma_f32_16x16x32_bf16 v[76:79], v[164:167], v[218:221], v[76:79]
	v_mfma_f32_16x16x32_bf16 v[120:123], v[168:171], v[184:187], v[120:123]
	v_mfma_f32_16x16x32_bf16 v[116:119], v[176:179], v[184:187], v[116:119]
	v_mfma_f32_16x16x32_bf16 v[104:107], v[168:171], v[192:195], v[104:107]
	v_mfma_f32_16x16x32_bf16 v[100:103], v[176:179], v[192:195], v[100:103]
	v_mfma_f32_16x16x32_bf16 v[88:91], v[168:171], v[206:209], v[88:91]
	v_mfma_f32_16x16x32_bf16 v[84:87], v[176:179], v[206:209], v[84:87]
	v_mfma_f32_16x16x32_bf16 v[72:75], v[168:171], v[214:217], v[72:75]
	v_mfma_f32_16x16x32_bf16 v[68:71], v[176:179], v[214:217], v[68:71]
	v_mfma_f32_16x16x32_bf16 v[120:123], v[172:175], v[188:191], v[120:123]
	v_mfma_f32_16x16x32_bf16 v[116:119], v[180:183], v[188:191], v[116:119]
	v_mfma_f32_16x16x32_bf16 v[104:107], v[172:175], v[202:205], v[104:107]
	v_mfma_f32_16x16x32_bf16 v[100:103], v[180:183], v[202:205], v[100:103]
	v_mfma_f32_16x16x32_bf16 v[88:91], v[172:175], v[210:213], v[88:91]
	v_mfma_f32_16x16x32_bf16 v[84:87], v[180:183], v[210:213], v[84:87]
	v_mfma_f32_16x16x32_bf16 v[72:75], v[172:175], v[218:221], v[72:75]
	v_mfma_f32_16x16x32_bf16 v[68:71], v[180:183], v[218:221], v[68:71]
	s_setprio 0
	s_barrier
; #define PG8_GOFFS(slot_) do { _Pragma("unroll") for (int _i = 0; _i < 2; ++_i) { int R, C; stage_rc(tid * 16 + _i * 8192, R, C); _Pragma("unroll") for (int _h = 0; _h < 2; ++_h) { \
;         unsigned t_ = gtab[(slot_) * 256 + R + 128 * _h]; t_ = t_ < (unsigned)(T - 1) ? t_ : (unsigned)(T - 1); voffA[_h][_i] = (t_ * (unsigned)K + (unsigned)C) * 2u; } } } while (0)
; #define PG8_STAGE(bufoff, gbase, voff) do { _Pragma("unroll") for (int _i = 0; _i < 2; ++_i) \
;         __builtin_amdgcn_global_load_lds((const unsigned*)((const char*)(gbase) + (voff)[_i]), (LAS unsigned*)(lds + (bufoff) + ldsw + _i * 8192), 16, 0, 0); } while (0)
; #define PG8_WAIT_V(n) asm volatile("s_waitcnt vmcnt(" #n ")" ::: "memory")
; template <class Epi, class Sched>
; __device__ __forceinline__ void gemm_phase(const int tid, LAS unsigned char* lds, const bf16* Aop, const bf16* Bop, const int K_, const Sched& S, const Epi& E, const bf16* Aop1 = nullptr, const bf16* Bop1 = nullptr) {
;     ...
;         for (int t = 0; t < nt; t += 2) {
;             const bool last = (t == nt - 2);
;             const char* a1 = cA + (size_t)(t + 1) * kstep;
;             const char* a2 = last ? nA : cA + (size_t)(t + 2) * kstep; const char* b2 = last ? nB : cB + (size_t)(t + 2) * kstep;
;             const char* a3 = a2 + kstep; const char* b3 = b2 + kstep;
;             PG8_LDB(B0, 0, 0); PG8_LDB(B1, 0, 1); PG8_SCHED; PG8_LDA(At, 0, 0); PG8_STAGE_A1(PG8_SA(1, 1), a1);
;             PG8_WAIT_V(8); PG8_WAIT_L(0); PG8_BAR; PG8_MMA(0, 0, At, B0); PG8_MMA(0, 1, At, B1); PG8_BAR; PG8_SCHED;
;             PG8_LDA(At, 0, 1); PG8_STAGE(PG8_SB(0, 0), b2, voffB); PG8_STAGE(PG8_SB(0, 1), b2 + hstep, voffB); if (Epi::GATHER && last && has_next) PG8_GOFFS((ui + 1) & 1); PG8_STAGE(PG8_SA(0, 0), a2, voffA[0]);
;             PG8_WAIT_V(8); PG8_WAIT_L(0); PG8_BAR; PG8_MMA(1, 0, At, B0); PG8_MMA(1, 1, At, B1); PG8_BAR; PG8_SCHED;
;             PG8_LDB(B0, 1, 0); PG8_LDB(B1, 1, 1); PG8_SCHED; PG8_LDA(At, 1, 0); PG8_STAGE_A1(PG8_SA(0, 1), a2);
;             PG8_WAIT_V(8); PG8_WAIT_L(0); PG8_BAR; PG8_MMA(0, 0, At, B0); PG8_MMA(0, 1, At, B1); PG8_BAR; PG8_SCHED;
;             PG8_LDA(At, 1, 1); PG8_STAGE(PG8_SB(1, 0), b3, voffB); PG8_STAGE(PG8_SB(1, 1), b3 + hstep, voffB); PG8_STAGE(PG8_SA(1, 0), a3, voffA[0]);
;             PG8_WAIT_V(8); PG8_WAIT_L(0); PG8_BAR; PG8_MMA(1, 0, At, B0); PG8_MMA(1, 1, At, B1); PG8_BAR; PG8_SCHED;
	s_add_i32 s4, s73, s16
	v_lshl_add_u64 v[158:159], v[158:159], 0, s[20:21]
	s_mov_b32 m0, s4
	ds_read_b128 v[184:187], v162 offset:49152
	ds_read_b128 v[188:191], v162 offset:50176
	ds_read_b128 v[192:195], v162 offset:51200
	ds_read_b128 v[202:205], v162 offset:52224
	ds_read_b128 v[206:209], v162 offset:53248
	ds_read_b128 v[210:213], v162 offset:54272
	ds_read_b128 v[214:217], v162 offset:55296
	ds_read_b128 v[218:221], v162 offset:56320
	global_load_lds_dwordx4 v[158:159], off
	v_lshl_add_u64 v[158:159], v[196:197], 0, s[20:21]
	s_add_i32 m0, s4, 0x2000
	s_add_i32 s4, s74, s16
	global_load_lds_dwordx4 v[158:159], off
	v_lshl_add_u64 v[158:159], v[198:199], 0, s[20:21]
	s_mov_b32 m0, s4
	s_nop 0
	global_load_lds_dwordx4 v[158:159], off
	v_lshl_add_u64 v[158:159], v[222:223], 0, s[20:21]
	s_add_i32 m0, s4, 0x2000
	s_nop 0
	global_load_lds_dwordx4 v[158:159], off
	v_lshl_add_u64 v[158:159], v[224:225], 0, s[20:21]
	s_mov_b32 m0, s35
	s_nop 0
	global_load_lds_dwordx4 v[158:159], off
	v_lshl_add_u64 v[158:159], v[230:231], 0, s[20:21]
	s_mov_b32 m0, s36
	s_nop 0
	global_load_lds_dwordx4 v[158:159], off
	s_waitcnt vmcnt(8)
	s_waitcnt lgkmcnt(0)
	s_barrier
	s_setprio 1
	v_mfma_f32_16x16x32_bf16 v[64:67], v[132:135], v[184:187], v[64:67]
	v_mfma_f32_16x16x32_bf16 v[60:63], v[154:157], v[184:187], v[60:63]
	v_mfma_f32_16x16x32_bf16 v[48:51], v[132:135], v[192:195], v[48:51]
	v_mfma_f32_16x16x32_bf16 v[44:47], v[154:157], v[192:195], v[44:47]
	v_mfma_f32_16x16x32_bf16 v[32:35], v[132:135], v[206:209], v[32:35]
	v_mfma_f32_16x16x32_bf16 v[28:31], v[154:157], v[206:209], v[28:31]
	v_mfma_f32_16x16x32_bf16 v[16:19], v[132:135], v[214:217], v[16:19]
	v_mfma_f32_16x16x32_bf16 v[12:15], v[154:157], v[214:217], v[12:15]
	v_mfma_f32_16x16x32_bf16 v[64:67], v[136:139], v[188:191], v[64:67]
	v_mfma_f32_16x16x32_bf16 v[60:63], v[164:167], v[188:191], v[60:63]
	v_mfma_f32_16x16x32_bf16 v[48:51], v[136:139], v[202:205], v[48:51]
	v_mfma_f32_16x16x32_bf16 v[44:47], v[164:167], v[202:205], v[44:47]
	v_mfma_f32_16x16x32_bf16 v[32:35], v[136:139], v[210:213], v[32:35]
	v_mfma_f32_16x16x32_bf16 v[28:31], v[164:167], v[210:213], v[28:31]
	v_mfma_f32_16x16x32_bf16 v[16:19], v[136:139], v[218:221], v[16:19]
	v_mfma_f32_16x16x32_bf16 v[12:15], v[164:167], v[218:221], v[12:15]
	v_mfma_f32_16x16x32_bf16 v[56:59], v[168:171], v[184:187], v[56:59]
	v_mfma_f32_16x16x32_bf16 v[52:55], v[176:179], v[184:187], v[52:55]
	v_mfma_f32_16x16x32_bf16 v[40:43], v[168:171], v[192:195], v[40:43]
	v_mfma_f32_16x16x32_bf16 v[36:39], v[176:179], v[192:195], v[36:39]
	v_mfma_f32_16x16x32_bf16 v[24:27], v[168:171], v[206:209], v[24:27]
	v_mfma_f32_16x16x32_bf16 v[20:23], v[176:179], v[206:209], v[20:23]
	v_mfma_f32_16x16x32_bf16 v[8:11], v[168:171], v[214:217], v[8:11]
	v_mfma_f32_16x16x32_bf16 v[4:7], v[176:179], v[214:217], v[4:7]
	v_mfma_f32_16x16x32_bf16 v[56:59], v[172:175], v[188:191], v[56:59]
	v_mfma_f32_16x16x32_bf16 v[52:55], v[180:183], v[188:191], v[52:55]
	v_mfma_f32_16x16x32_bf16 v[40:43], v[172:175], v[202:205], v[40:43]
	v_mfma_f32_16x16x32_bf16 v[36:39], v[180:183], v[202:205], v[36:39]
	v_mfma_f32_16x16x32_bf16 v[24:27], v[172:175], v[210:213], v[24:27]
	v_mfma_f32_16x16x32_bf16 v[20:23], v[180:183], v[210:213], v[20:23]
	v_mfma_f32_16x16x32_bf16 v[8:11], v[172:175], v[218:221], v[8:11]
	v_mfma_f32_16x16x32_bf16 v[4:7], v[180:183], v[218:221], v[4:7]
	s_setprio 0
	s_barrier
	s_add_u32 s2, s2, 0x100
	s_addc_u32 s3, s3, 0
	s_add_u32 s6, s6, 0x100
	s_addc_u32 s7, s7, 0
	s_cmp_ge_i32 s72, s8
	s_mov_b32 s4, s72
	s_cbranch_scc0 .LBB0_1597
	s_branch .LBB0_1598
.LBB0_1597:
	s_add_i32 s72, s4, 2
	s_add_u32 s73, s2, 0x80
	s_addc_u32 s5, s3, 0
	s_add_i32 s76, 0, 0x10000
	s_cmp_eq_u32 s37, s4
	s_cselect_b32 s5, s41, s5
	s_cselect_b32 s4, s40, s73
	v_add_u32_e32 v158, s76, v160
	s_cselect_b32 s75, s69, s7
	s_cselect_b32 s74, s68, s6
	s_add_i32 s73, 0, 0x14000
	ds_read_b128 v[132:135], v158
	ds_read_b128 v[136:139], v158 offset:1024
	ds_read_b128 v[154:157], v158 offset:2048
	ds_read_b128 v[164:167], v158 offset:3072
	v_add_u32_e32 v158, s73, v160
	ds_read_b128 v[168:171], v158
	ds_read_b128 v[172:175], v158 offset:1024
	ds_read_b128 v[176:179], v158 offset:2048
	ds_read_b128 v[180:183], v158 offset:3072
	v_lshl_add_u64 v[158:159], s[2:3], 0, v[150:151]
	s_add_i32 m0, s17, 0xc000
	ds_read_b128 v[184:187], v162
	ds_read_b128 v[188:191], v162 offset:1024
	ds_read_b128 v[192:195], v162 offset:2048
	ds_read_b128 v[202:205], v162 offset:3072
	ds_read_b128 v[206:209], v162 offset:4096
	ds_read_b128 v[210:213], v162 offset:5120
	ds_read_b128 v[214:217], v162 offset:6144
	ds_read_b128 v[218:221], v162 offset:7168
	global_load_lds_dwordx4 v[158:159], off
	v_lshl_add_u64 v[158:159], s[2:3], 0, v[152:153]
	s_add_i32 m0, s17, 0xe000
	s_nop 0
	global_load_lds_dwordx4 v[158:159], off
	s_waitcnt vmcnt(8)
	s_waitcnt lgkmcnt(0)
	s_barrier
; #define PG8_GOFFS(slot_) do { _Pragma("unroll") for (int _i = 0; _i < 2; ++_i) { int R, C; stage_rc(tid * 16 + _i * 8192, R, C); _Pragma("unroll") for (int _h = 0; _h < 2; ++_h) { \
;         unsigned t_ = gtab[(slot_) * 256 + R + 128 * _h]; t_ = t_ < (unsigned)(T - 1) ? t_ : (unsigned)(T - 1); voffA[_h][_i] = (t_ * (unsigned)K + (unsigned)C) * 2u; } } } while (0)
; #define PG8_STAGE(bufoff, gbase, voff) do { _Pragma("unroll") for (int _i = 0; _i < 2; ++_i) \
;         __builtin_amdgcn_global_load_lds((const unsigned*)((const char*)(gbase) + (voff)[_i]), (LAS unsigned*)(lds + (bufoff) + ldsw + _i * 8192), 16, 0, 0); } while (0)
; #define PG8_STAGE_A1(bufoff, gbase) do { if (Epi::GATHER) PG8_STAGE(bufoff, gbase, voffA[1]); else PG8_STAGE(bufoff, (gbase) + hstep, voffA[0]); } while (0)
; #define PG8_LDA(dst, b, h) do { _Pragma("unroll") for (int m = 0; m < 4; ++m) _Pragma("unroll") for (int k = 0; k < 2; ++k) dst[m][k] = *(const LAS bf16x8*)(lds + PG8_SA(b, h) + aoff + m * 2048 + k * 1024); } while (0)
; #define PG8_LDB(dst, b, h) do { _Pragma("unroll") for (int n = 0; n < 2; ++n) _Pragma("unroll") for (int k = 0; k < 2; ++k) dst[n][k] = *(const LAS bf16x8*)(lds + PG8_SB(b, h) + boff + n * 2048 + k * 1024); } while (0)
; #define PG8_WAIT_V(n) asm volatile("s_waitcnt vmcnt(" #n ")" ::: "memory")
; #define PG8_WAIT_L(n) asm volatile("s_waitcnt lgkmcnt(" #n ")" ::: "memory")
; #define PG8_BAR __builtin_amdgcn_s_barrier()
; #define PG8_SCHED __builtin_amdgcn_sched_barrier(0)
; template <class Epi, class Sched>
; __device__ __forceinline__ void gemm_phase(const int tid, LAS unsigned char* lds, const bf16* Aop, const bf16* Bop, const int K_, const Sched& S, const Epi& E, const bf16* Aop1 = nullptr, const bf16* Bop1 = nullptr) {
;     ...
;             PG8_LDB(B0, 0, 0); PG8_LDB(B1, 0, 1); PG8_SCHED; PG8_LDA(At, 0, 0); PG8_STAGE_A1(PG8_SA(1, 1), a1);
;             PG8_WAIT_V(8); PG8_WAIT_L(0); PG8_BAR; PG8_MMA(0, 0, At, B0); PG8_MMA(0, 1, At, B1); PG8_BAR; PG8_SCHED;
;             PG8_LDA(At, 0, 1); PG8_STAGE(PG8_SB(0, 0), b2, voffB); PG8_STAGE(PG8_SB(0, 1), b2 + hstep, voffB); if (Epi::GATHER && last && has_next) PG8_GOFFS((ui + 1) & 1); PG8_STAGE(PG8_SA(0, 0), a2, voffA[0]);
;             PG8_WAIT_V(8); PG8_WAIT_L(0); PG8_BAR; PG8_MMA(1, 0, At, B0); PG8_MMA(1, 1, At, B1); PG8_BAR; PG8_SCHED;
	s_setprio 1
	v_mfma_f32_16x16x32_bf16 v[128:131], v[132:135], v[184:187], v[128:131]
	v_mfma_f32_16x16x32_bf16 v[124:127], v[154:157], v[184:187], v[124:127]
	v_mfma_f32_16x16x32_bf16 v[112:115], v[132:135], v[192:195], v[112:115]
	v_mfma_f32_16x16x32_bf16 v[108:111], v[154:157], v[192:195], v[108:111]
	v_mfma_f32_16x16x32_bf16 v[96:99], v[132:135], v[206:209], v[96:99]
	v_mfma_f32_16x16x32_bf16 v[92:95], v[154:157], v[206:209], v[92:95]
	v_mfma_f32_16x16x32_bf16 v[80:83], v[132:135], v[214:217], v[80:83]
	v_mfma_f32_16x16x32_bf16 v[76:79], v[154:157], v[214:217], v[76:79]
	v_mfma_f32_16x16x32_bf16 v[128:131], v[136:139], v[188:191], v[128:131]
	v_mfma_f32_16x16x32_bf16 v[124:127], v[164:167], v[188:191], v[124:127]
	v_mfma_f32_16x16x32_bf16 v[112:115], v[136:139], v[202:205], v[112:115]
	v_mfma_f32_16x16x32_bf16 v[108:111], v[164:167], v[202:205], v[108:111]
	v_mfma_f32_16x16x32_bf16 v[96:99], v[136:139], v[210:213], v[96:99]
	v_mfma_f32_16x16x32_bf16 v[92:95], v[164:167], v[210:213], v[92:95]
	v_mfma_f32_16x16x32_bf16 v[80:83], v[136:139], v[218:221], v[80:83]
	v_mfma_f32_16x16x32_bf16 v[76:79], v[164:167], v[218:221], v[76:79]
	v_mfma_f32_16x16x32_bf16 v[120:123], v[168:171], v[184:187], v[120:123]
	v_mfma_f32_16x16x32_bf16 v[116:119], v[176:179], v[184:187], v[116:119]
	v_mfma_f32_16x16x32_bf16 v[104:107], v[168:171], v[192:195], v[104:107]
	v_mfma_f32_16x16x32_bf16 v[100:103], v[176:179], v[192:195], v[100:103]
	v_mfma_f32_16x16x32_bf16 v[88:91], v[168:171], v[206:209], v[88:91]
	v_mfma_f32_16x16x32_bf16 v[84:87], v[176:179], v[206:209], v[84:87]
	v_mfma_f32_16x16x32_bf16 v[72:75], v[168:171], v[214:217], v[72:75]
	v_mfma_f32_16x16x32_bf16 v[68:71], v[176:179], v[214:217], v[68:71]
	v_mfma_f32_16x16x32_bf16 v[120:123], v[172:175], v[188:191], v[120:123]
	v_mfma_f32_16x16x32_bf16 v[116:119], v[180:183], v[188:191], v[116:119]
	v_mfma_f32_16x16x32_bf16 v[104:107], v[172:175], v[202:205], v[104:107]
	v_mfma_f32_16x16x32_bf16 v[100:103], v[180:183], v[202:205], v[100:103]
	v_mfma_f32_16x16x32_bf16 v[88:91], v[172:175], v[210:213], v[88:91]
	v_mfma_f32_16x16x32_bf16 v[84:87], v[180:183], v[210:213], v[84:87]
	v_mfma_f32_16x16x32_bf16 v[72:75], v[172:175], v[218:221], v[72:75]
	v_mfma_f32_16x16x32_bf16 v[68:71], v[180:183], v[218:221], v[68:71]
	s_setprio 0
	s_barrier
	s_add_i32 s76, s76, s16
	v_lshl_add_u64 v[158:159], s[74:75], 0, v[142:143]
	s_mov_b32 m0, s76
	ds_read_b128 v[184:187], v162 offset:16384
	ds_read_b128 v[188:191], v162 offset:17408
	ds_read_b128 v[192:195], v162 offset:18432
	ds_read_b128 v[202:205], v162 offset:19456
	ds_read_b128 v[206:209], v162 offset:20480
	ds_read_b128 v[210:213], v162 offset:21504
	ds_read_b128 v[214:217], v162 offset:22528
	ds_read_b128 v[218:221], v162 offset:23552
	global_load_lds_dwordx4 v[158:159], off
	s_add_i32 m0, s76, 0x2000
	v_lshl_add_u64 v[196:197], s[74:75], 0, v[146:147]
	s_add_u32 s74, s74, s58
	s_addc_u32 s75, s75, s59
	s_add_i32 s73, s73, s16
	global_load_lds_dwordx4 v[196:197], off
	v_lshl_add_u64 v[198:199], s[74:75], 0, v[142:143]
	s_mov_b32 m0, s73
	v_lshl_add_u64 v[222:223], s[74:75], 0, v[146:147]
	global_load_lds_dwordx4 v[198:199], off
	s_add_i32 m0, s73, 0x2000
	v_lshl_add_u64 v[224:225], s[4:5], 0, v[140:141]
	global_load_lds_dwordx4 v[222:223], off
	s_mov_b32 m0, s17
	v_lshl_add_u64 v[230:231], s[4:5], 0, v[144:145]
	global_load_lds_dwordx4 v[224:225], off
	s_mov_b32 m0, s28
	s_nop 0
	global_load_lds_dwordx4 v[230:231], off
	s_waitcnt vmcnt(8)
	s_waitcnt lgkmcnt(0)
	s_barrier
	s_setprio 1
	v_mfma_f32_16x16x32_bf16 v[64:67], v[132:135], v[184:187], v[64:67]
	v_mfma_f32_16x16x32_bf16 v[60:63], v[154:157], v[184:187], v[60:63]
	v_mfma_f32_16x16x32_bf16 v[48:51], v[132:135], v[192:195], v[48:51]
	v_mfma_f32_16x16x32_bf16 v[44:47], v[154:157], v[192:195], v[44:47]
	v_mfma_f32_16x16x32_bf16 v[32:35], v[132:135], v[206:209], v[32:35]
	v_mfma_f32_16x16x32_bf16 v[28:31], v[154:157], v[206:209], v[28:31]
	v_mfma_f32_16x16x32_bf16 v[16:19], v[132:135], v[214:217], v[16:19]
	v_mfma_f32_16x16x32_bf16 v[12:15], v[154:157], v[214:217], v[12:15]
	v_mfma_f32_16x16x32_bf16 v[64:67], v[136:139], v[188:191], v[64:67]
	v_mfma_f32_16x16x32_bf16 v[60:63], v[164:167], v[188:191], v[60:63]
	v_mfma_f32_16x16x32_bf16 v[48:51], v[136:139], v[202:205], v[48:51]
	v_mfma_f32_16x16x32_bf16 v[44:47], v[164:167], v[202:205], v[44:47]
	v_mfma_f32_16x16x32_bf16 v[32:35], v[136:139], v[210:213], v[32:35]
	v_mfma_f32_16x16x32_bf16 v[28:31], v[164:167], v[210:213], v[28:31]
	v_mfma_f32_16x16x32_bf16 v[16:19], v[136:139], v[218:221], v[16:19]
	v_mfma_f32_16x16x32_bf16 v[12:15], v[164:167], v[218:221], v[12:15]
	v_mfma_f32_16x16x32_bf16 v[56:59], v[168:171], v[184:187], v[56:59]
	v_mfma_f32_16x16x32_bf16 v[52:55], v[176:179], v[184:187], v[52:55]
	v_mfma_f32_16x16x32_bf16 v[40:43], v[168:171], v[192:195], v[40:43]
	v_mfma_f32_16x16x32_bf16 v[36:39], v[176:179], v[192:195], v[36:39]
	v_mfma_f32_16x16x32_bf16 v[24:27], v[168:171], v[206:209], v[24:27]
	v_mfma_f32_16x16x32_bf16 v[20:23], v[176:179], v[206:209], v[20:23]
	v_mfma_f32_16x16x32_bf16 v[8:11], v[168:171], v[214:217], v[8:11]
	v_mfma_f32_16x16x32_bf16 v[4:7], v[176:179], v[214:217], v[4:7]
	v_mfma_f32_16x16x32_bf16 v[56:59], v[172:175], v[188:191], v[56:59]
	v_mfma_f32_16x16x32_bf16 v[52:55], v[180:183], v[188:191], v[52:55]
	v_mfma_f32_16x16x32_bf16 v[40:43], v[172:175], v[202:205], v[40:43]
	v_mfma_f32_16x16x32_bf16 v[36:39], v[180:183], v[202:205], v[36:39]
	v_mfma_f32_16x16x32_bf16 v[24:27], v[172:175], v[210:213], v[24:27]
	v_mfma_f32_16x16x32_bf16 v[20:23], v[180:183], v[210:213], v[20:23]
	v_mfma_f32_16x16x32_bf16 v[8:11], v[172:175], v[218:221], v[8:11]
	v_mfma_f32_16x16x32_bf16 v[4:7], v[180:183], v[218:221], v[4:7]
	s_setprio 0
	s_barrier
; #define PG8_STAGE(bufoff, gbase, voff) do { _Pragma("unroll") for (int _i = 0; _i < 2; ++_i) \
;         __builtin_amdgcn_global_load_lds((const unsigned*)((const char*)(gbase) + (voff)[_i]), (LAS unsigned*)(lds + (bufoff) + ldsw + _i * 8192), 16, 0, 0); } while (0)
; #define PG8_STAGE_A1(bufoff, gbase) do { if (Epi::GATHER) PG8_STAGE(bufoff, gbase, voffA[1]); else PG8_STAGE(bufoff, (gbase) + hstep, voffA[0]); } while (0)
; #define PG8_LDA(dst, b, h) do { _Pragma("unroll") for (int m = 0; m < 4; ++m) _Pragma("unroll") for (int k = 0; k < 2; ++k) dst[m][k] = *(const LAS bf16x8*)(lds + PG8_SA(b, h) + aoff + m * 2048 + k * 1024); } while (0)
; #define PG8_LDB(dst, b, h) do { _Pragma("unroll") for (int n = 0; n < 2; ++n) _Pragma("unroll") for (int k = 0; k < 2; ++k) dst[n][k] = *(const LAS bf16x8*)(lds + PG8_SB(b, h) + boff + n * 2048 + k * 1024); } while (0)
; #define PG8_MMA(ai, bj, At, Bt) do { __builtin_amdgcn_s_setprio(1); _Pragma("unroll") for (int m = 0; m < 4; ++m) _Pragma("unroll") for (int n = 0; n < 2; ++n) _Pragma("unroll") for (int k = 0; k < 2; ++k) \
;         acc[ai][bj][m][n] = __builtin_amdgcn_mfma_f32_16x16x32_bf16(Bt[n][k], At[m][k], acc[ai][bj][m][n], 0, 0, 0); __builtin_amdgcn_s_setprio(0); } while (0)
; #define PG8_WAIT_V(n) asm volatile("s_waitcnt vmcnt(" #n ")" ::: "memory")
; #define PG8_WAIT_L(n) asm volatile("s_waitcnt lgkmcnt(" #n ")" ::: "memory")
; #define PG8_BAR __builtin_amdgcn_s_barrier()
; #define PG8_SCHED __builtin_amdgcn_sched_barrier(0)
; template <class Epi, class Sched>
; __device__ __forceinline__ void gemm_phase(const int tid, LAS unsigned char* lds, const bf16* Aop, const bf16* Bop, const int K_, const Sched& S, const Epi& E, const bf16* Aop1 = nullptr, const bf16* Bop1 = nullptr) {
;     ...
;             PG8_LDB(B0, 1, 0); PG8_LDB(B1, 1, 1); PG8_SCHED; PG8_LDA(At, 1, 0); PG8_STAGE_A1(PG8_SA(0, 1), a2);
;             PG8_WAIT_V(8); PG8_WAIT_L(0); PG8_BAR; PG8_MMA(0, 0, At, B0); PG8_MMA(0, 1, At, B1); PG8_BAR; PG8_SCHED;
;             PG8_LDA(At, 1, 1); PG8_STAGE(PG8_SB(1, 0), b3, voffB); PG8_STAGE(PG8_SB(1, 1), b3 + hstep, voffB); PG8_STAGE(PG8_SA(1, 0), a3, voffA[0]);
;             PG8_WAIT_V(8); PG8_WAIT_L(0); PG8_BAR; PG8_MMA(1, 0, At, B0); PG8_MMA(1, 1, At, B1); PG8_BAR; PG8_SCHED;
;         }
	s_add_i32 s73, 0, 0x18000
	v_add_u32_e32 v163, s73, v160
	s_add_i32 s74, 0, 0x1c000
	ds_read_b128 v[132:135], v163
	ds_read_b128 v[136:139], v163 offset:1024
	ds_read_b128 v[154:157], v163 offset:2048
	ds_read_b128 v[164:167], v163 offset:3072
	v_add_u32_e32 v163, s74, v160
	ds_read_b128 v[168:171], v163
	ds_read_b128 v[172:175], v163 offset:1024
	ds_read_b128 v[176:179], v163 offset:2048
	ds_read_b128 v[180:183], v163 offset:3072
	s_add_u32 s4, s4, s58
	s_addc_u32 s5, s5, s59
	s_mov_b32 m0, s29
	v_lshl_add_u64 v[232:233], s[4:5], 0, v[140:141]
	ds_read_b128 v[184:187], v162 offset:32768
	ds_read_b128 v[188:191], v162 offset:33792
	ds_read_b128 v[192:195], v162 offset:34816
	ds_read_b128 v[202:205], v162 offset:35840
	ds_read_b128 v[206:209], v162 offset:36864
	ds_read_b128 v[210:213], v162 offset:37888
	ds_read_b128 v[214:217], v162 offset:38912
	ds_read_b128 v[218:221], v162 offset:39936
	global_load_lds_dwordx4 v[232:233], off
	v_lshl_add_u64 v[232:233], s[4:5], 0, v[144:145]
	s_mov_b32 m0, s34
	s_nop 0
	global_load_lds_dwordx4 v[232:233], off
	s_waitcnt vmcnt(8)
	s_waitcnt lgkmcnt(0)
	s_barrier
	s_setprio 1
	v_mfma_f32_16x16x32_bf16 v[128:131], v[132:135], v[184:187], v[128:131]
	v_mfma_f32_16x16x32_bf16 v[124:127], v[154:157], v[184:187], v[124:127]
	v_mfma_f32_16x16x32_bf16 v[112:115], v[132:135], v[192:195], v[112:115]
	v_mfma_f32_16x16x32_bf16 v[108:111], v[154:157], v[192:195], v[108:111]
	v_mfma_f32_16x16x32_bf16 v[96:99], v[132:135], v[206:209], v[96:99]
	v_mfma_f32_16x16x32_bf16 v[92:95], v[154:157], v[206:209], v[92:95]
	v_mfma_f32_16x16x32_bf16 v[80:83], v[132:135], v[214:217], v[80:83]
	v_mfma_f32_16x16x32_bf16 v[76:79], v[154:157], v[214:217], v[76:79]
	v_mfma_f32_16x16x32_bf16 v[128:131], v[136:139], v[188:191], v[128:131]
	v_mfma_f32_16x16x32_bf16 v[124:127], v[164:167], v[188:191], v[124:127]
	v_mfma_f32_16x16x32_bf16 v[112:115], v[136:139], v[202:205], v[112:115]
	v_mfma_f32_16x16x32_bf16 v[108:111], v[164:167], v[202:205], v[108:111]
	v_mfma_f32_16x16x32_bf16 v[96:99], v[136:139], v[210:213], v[96:99]
	v_mfma_f32_16x16x32_bf16 v[92:95], v[164:167], v[210:213], v[92:95]
	v_mfma_f32_16x16x32_bf16 v[80:83], v[136:139], v[218:221], v[80:83]
	v_mfma_f32_16x16x32_bf16 v[76:79], v[164:167], v[218:221], v[76:79]
	v_mfma_f32_16x16x32_bf16 v[120:123], v[168:171], v[184:187], v[120:123]
	v_mfma_f32_16x16x32_bf16 v[116:119], v[176:179], v[184:187], v[116:119]
	v_mfma_f32_16x16x32_bf16 v[104:107], v[168:171], v[192:195], v[104:107]
	v_mfma_f32_16x16x32_bf16 v[100:103], v[176:179], v[192:195], v[100:103]
	v_mfma_f32_16x16x32_bf16 v[88:91], v[168:171], v[206:209], v[88:91]
	v_mfma_f32_16x16x32_bf16 v[84:87], v[176:179], v[206:209], v[84:87]
	v_mfma_f32_16x16x32_bf16 v[72:75], v[168:171], v[214:217], v[72:75]
	v_mfma_f32_16x16x32_bf16 v[68:71], v[176:179], v[214:217], v[68:71]
	v_mfma_f32_16x16x32_bf16 v[120:123], v[172:175], v[188:191], v[120:123]
	v_mfma_f32_16x16x32_bf16 v[116:119], v[180:183], v[188:191], v[116:119]
	v_mfma_f32_16x16x32_bf16 v[104:107], v[172:175], v[202:205], v[104:107]
	v_mfma_f32_16x16x32_bf16 v[100:103], v[180:183], v[202:205], v[100:103]
	v_mfma_f32_16x16x32_bf16 v[88:91], v[172:175], v[210:213], v[88:91]
	v_mfma_f32_16x16x32_bf16 v[84:87], v[180:183], v[210:213], v[84:87]
	v_mfma_f32_16x16x32_bf16 v[72:75], v[172:175], v[218:221], v[72:75]
	v_mfma_f32_16x16x32_bf16 v[68:71], v[180:183], v[218:221], v[68:71]
	s_setprio 0
	s_barrier
	s_add_i32 s4, s73, s16
	v_lshl_add_u64 v[158:159], v[158:159], 0, s[20:21]
	s_mov_b32 m0, s4
	ds_read_b128 v[184:187], v162 offset:49152
	ds_read_b128 v[188:191], v162 offset:50176
	ds_read_b128 v[192:195], v162 offset:51200
	ds_read_b128 v[202:205], v162 offset:52224
	ds_read_b128 v[206:209], v162 offset:53248
	ds_read_b128 v[210:213], v162 offset:54272
	ds_read_b128 v[214:217], v162 offset:55296
	ds_read_b128 v[218:221], v162 offset:56320
	global_load_lds_dwordx4 v[158:159], off
	v_lshl_add_u64 v[158:159], v[196:197], 0, s[20:21]
	s_add_i32 m0, s4, 0x2000
	s_add_i32 s4, s74, s16
	global_load_lds_dwordx4 v[158:159], off
	v_lshl_add_u64 v[158:159], v[198:199], 0, s[20:21]
	s_mov_b32 m0, s4
	s_nop 0
	global_load_lds_dwordx4 v[158:159], off
	v_lshl_add_u64 v[158:159], v[222:223], 0, s[20:21]
	s_add_i32 m0, s4, 0x2000
	s_nop 0
	global_load_lds_dwordx4 v[158:159], off
	v_lshl_add_u64 v[158:159], v[224:225], 0, s[20:21]
	s_mov_b32 m0, s35
	s_nop 0
	global_load_lds_dwordx4 v[158:159], off
	v_lshl_add_u64 v[158:159], v[230:231], 0, s[20:21]
	s_mov_b32 m0, s36
	s_nop 0
	global_load_lds_dwordx4 v[158:159], off
	s_waitcnt vmcnt(8)
	s_waitcnt lgkmcnt(0)
	s_barrier
	s_setprio 1
	v_mfma_f32_16x16x32_bf16 v[64:67], v[132:135], v[184:187], v[64:67]
	v_mfma_f32_16x16x32_bf16 v[60:63], v[154:157], v[184:187], v[60:63]
	v_mfma_f32_16x16x32_bf16 v[48:51], v[132:135], v[192:195], v[48:51]
	v_mfma_f32_16x16x32_bf16 v[44:47], v[154:157], v[192:195], v[44:47]
	v_mfma_f32_16x16x32_bf16 v[32:35], v[132:135], v[206:209], v[32:35]
	v_mfma_f32_16x16x32_bf16 v[28:31], v[154:157], v[206:209], v[28:31]
	v_mfma_f32_16x16x32_bf16 v[16:19], v[132:135], v[214:217], v[16:19]
	v_mfma_f32_16x16x32_bf16 v[12:15], v[154:157], v[214:217], v[12:15]
	v_mfma_f32_16x16x32_bf16 v[64:67], v[136:139], v[188:191], v[64:67]
	v_mfma_f32_16x16x32_bf16 v[60:63], v[164:167], v[188:191], v[60:63]
	v_mfma_f32_16x16x32_bf16 v[48:51], v[136:139], v[202:205], v[48:51]
	v_mfma_f32_16x16x32_bf16 v[44:47], v[164:167], v[202:205], v[44:47]
	v_mfma_f32_16x16x32_bf16 v[32:35], v[136:139], v[210:213], v[32:35]
	v_mfma_f32_16x16x32_bf16 v[28:31], v[164:167], v[210:213], v[28:31]
	v_mfma_f32_16x16x32_bf16 v[16:19], v[136:139], v[218:221], v[16:19]
	v_mfma_f32_16x16x32_bf16 v[12:15], v[164:167], v[218:221], v[12:15]
	v_mfma_f32_16x16x32_bf16 v[56:59], v[168:171], v[184:187], v[56:59]
	v_mfma_f32_16x16x32_bf16 v[52:55], v[176:179], v[184:187], v[52:55]
	v_mfma_f32_16x16x32_bf16 v[40:43], v[168:171], v[192:195], v[40:43]
	v_mfma_f32_16x16x32_bf16 v[36:39], v[176:179], v[192:195], v[36:39]
	v_mfma_f32_16x16x32_bf16 v[24:27], v[168:171], v[206:209], v[24:27]
	v_mfma_f32_16x16x32_bf16 v[20:23], v[176:179], v[206:209], v[20:23]
	v_mfma_f32_16x16x32_bf16 v[8:11], v[168:171], v[214:217], v[8:11]
	v_mfma_f32_16x16x32_bf16 v[4:7], v[176:179], v[214:217], v[4:7]
	v_mfma_f32_16x16x32_bf16 v[56:59], v[172:175], v[188:191], v[56:59]
	v_mfma_f32_16x16x32_bf16 v[52:55], v[180:183], v[188:191], v[52:55]
	v_mfma_f32_16x16x32_bf16 v[40:43], v[172:175], v[202:205], v[40:43]
	v_mfma_f32_16x16x32_bf16 v[36:39], v[180:183], v[202:205], v[36:39]
	v_mfma_f32_16x16x32_bf16 v[24:27], v[172:175], v[210:213], v[24:27]
	v_mfma_f32_16x16x32_bf16 v[20:23], v[180:183], v[210:213], v[20:23]
	v_mfma_f32_16x16x32_bf16 v[8:11], v[172:175], v[218:221], v[8:11]
	v_mfma_f32_16x16x32_bf16 v[4:7], v[180:183], v[218:221], v[4:7]
	s_setprio 0
	s_barrier
	s_add_u32 s2, s2, 0x100
	s_addc_u32 s3, s3, 0
	s_add_u32 s6, s6, 0x100
	s_addc_u32 s7, s7, 0
	s_cmp_ge_i32 s72, s8
	s_mov_b32 s4, s72
	s_cbranch_scc0 .LBB0_1597
